# lever 4: static s_setprio 1 for waves 4-7 across every GEMM K loop (reset to 0 at loop exit)
# baseline (speedup 1.0000x reference)
.LBB0_74:
	s_lshr_b32 s0, s5, 1
	s_and_b32 s0, s0, 0x1ffff80
	v_or_b32_e32 v0, s0, v154
	s_and_b32 s0, s5, 0xc0
	s_mov_b32 s5, s15
	s_lshl_b64 s[4:5], s[4:5], 16
	v_lshlrev_b32_e32 v128, 7, v0
	v_or_b32_e32 v0, s0, v154
	s_add_u32 s6, s4, s74
	v_lshlrev_b32_e32 v139, 7, v0
	v_lshl_add_u64 v[0:1], s[66:67], 0, v[130:131]
	s_addc_u32 s7, s5, s75
	s_waitcnt vmcnt(16)
	v_lshl_add_u64 v[142:143], v[0:1], 0, s[6:7]
	s_add_u32 s4, s4, s76
	v_lshl_add_u64 v[0:1], s[66:67], 0, v[134:135]
	s_addc_u32 s5, s5, s77
	v_lshl_add_u64 v[146:147], v[0:1], 0, s[6:7]
	v_mov_b32_e32 v0, 0
	v_lshl_add_u64 v[144:145], v[132:133], 0, s[4:5]
	v_lshl_add_u64 v[148:149], v[136:137], 0, s[4:5]
	s_mov_b64 s[4:5], 0
	s_mov_b32 s12, 0
	v_mov_b32_e32 v1, v0
	v_mov_b32_e32 v2, v0
	v_mov_b32_e32 v3, v0
	v_mov_b32_e32 v4, v0
	v_mov_b32_e32 v5, v0
	v_mov_b32_e32 v6, v0
	v_mov_b32_e32 v7, v0
	v_mov_b32_e32 v8, v0
	v_mov_b32_e32 v9, v0
	v_mov_b32_e32 v10, v0
	v_mov_b32_e32 v11, v0
	v_mov_b32_e32 v12, v0
	v_mov_b32_e32 v13, v0
	v_mov_b32_e32 v14, v0
	v_mov_b32_e32 v15, v0
	v_mov_b32_e32 v16, v0
	v_mov_b32_e32 v17, v0
	v_mov_b32_e32 v18, v0
	v_mov_b32_e32 v19, v0
	v_mov_b32_e32 v20, v0
	v_mov_b32_e32 v21, v0
	v_mov_b32_e32 v22, v0
	v_mov_b32_e32 v23, v0
	v_mov_b32_e32 v24, v0
	v_mov_b32_e32 v25, v0
	v_mov_b32_e32 v26, v0
	v_mov_b32_e32 v27, v0
	v_mov_b32_e32 v28, v0
	v_mov_b32_e32 v29, v0
	v_mov_b32_e32 v30, v0
	v_mov_b32_e32 v31, v0
	v_mov_b32_e32 v32, v0
	v_mov_b32_e32 v33, v0
	v_mov_b32_e32 v34, v0
	v_mov_b32_e32 v35, v0
	v_mov_b32_e32 v36, v0
	v_mov_b32_e32 v37, v0
	v_mov_b32_e32 v38, v0
	v_mov_b32_e32 v39, v0
	v_mov_b32_e32 v40, v0
	v_mov_b32_e32 v41, v0
	v_mov_b32_e32 v42, v0
	v_mov_b32_e32 v43, v0
	v_mov_b32_e32 v44, v0
	v_mov_b32_e32 v45, v0
	v_mov_b32_e32 v46, v0
	v_mov_b32_e32 v47, v0
	v_mov_b32_e32 v48, v0
	v_mov_b32_e32 v49, v0
	v_mov_b32_e32 v50, v0
	v_mov_b32_e32 v51, v0
	v_mov_b32_e32 v52, v0
	v_mov_b32_e32 v53, v0
	v_mov_b32_e32 v54, v0
	v_mov_b32_e32 v55, v0
	v_mov_b32_e32 v56, v0
	v_mov_b32_e32 v57, v0
	v_mov_b32_e32 v58, v0
	v_mov_b32_e32 v59, v0
	v_mov_b32_e32 v60, v0
	v_mov_b32_e32 v61, v0
	v_mov_b32_e32 v62, v0
	v_mov_b32_e32 v63, v0
	v_mov_b32_e32 v64, v0
	v_mov_b32_e32 v65, v0
	v_mov_b32_e32 v66, v0
	v_mov_b32_e32 v67, v0
	v_mov_b32_e32 v68, v0
	v_mov_b32_e32 v69, v0
	v_mov_b32_e32 v70, v0
	v_mov_b32_e32 v71, v0
	v_mov_b32_e32 v72, v0
	v_mov_b32_e32 v73, v0
	v_mov_b32_e32 v74, v0
	v_mov_b32_e32 v75, v0
	v_mov_b32_e32 v76, v0
	v_mov_b32_e32 v77, v0
	v_mov_b32_e32 v78, v0
	v_mov_b32_e32 v79, v0
	v_mov_b32_e32 v80, v0
	v_mov_b32_e32 v81, v0
	v_mov_b32_e32 v82, v0
	v_mov_b32_e32 v83, v0
	v_mov_b32_e32 v84, v0
	v_mov_b32_e32 v85, v0
	v_mov_b32_e32 v86, v0
	v_mov_b32_e32 v87, v0
	v_mov_b32_e32 v88, v0
	v_mov_b32_e32 v89, v0
	v_mov_b32_e32 v90, v0
	v_mov_b32_e32 v91, v0
	v_mov_b32_e32 v92, v0
	v_mov_b32_e32 v93, v0
	v_mov_b32_e32 v94, v0
	v_mov_b32_e32 v95, v0
	v_mov_b32_e32 v96, v0
	v_mov_b32_e32 v97, v0
	v_mov_b32_e32 v98, v0
	v_mov_b32_e32 v99, v0
	v_mov_b32_e32 v100, v0
	v_mov_b32_e32 v101, v0
	v_mov_b32_e32 v102, v0
	v_mov_b32_e32 v103, v0
	v_mov_b32_e32 v104, v0
	v_mov_b32_e32 v105, v0
	v_mov_b32_e32 v106, v0
	v_mov_b32_e32 v107, v0
	v_mov_b32_e32 v108, v0
	v_mov_b32_e32 v109, v0
	v_mov_b32_e32 v110, v0
	v_mov_b32_e32 v111, v0
	v_mov_b32_e32 v112, v0
	v_mov_b32_e32 v113, v0
	v_mov_b32_e32 v114, v0
	v_mov_b32_e32 v115, v0
	v_mov_b32_e32 v116, v0
	v_mov_b32_e32 v117, v0
	v_mov_b32_e32 v118, v0
	v_mov_b32_e32 v119, v0
	v_mov_b32_e32 v120, v0
	v_mov_b32_e32 v121, v0
	v_mov_b32_e32 v122, v0
	v_mov_b32_e32 v123, v0
	v_mov_b32_e32 v124, v0
	v_mov_b32_e32 v125, v0
	v_mov_b32_e32 v126, v0
	v_mov_b32_e32 v127, v0
	s_waitcnt vmcnt(16) lgkmcnt(0)
	s_barrier
	v_readfirstlane_b32 s98, v178
	s_nop 3
	s_lshr_b32 s98, s98, 6
	s_cmp_ge_u32 s98, 4
	s_cbranch_scc0 .Lprio_done_1
	s_setprio 1
.Lprio_done_1:
	v_bfe_u32 v250, v178, 3, 3
	v_and_b32_e32 v251, 7, v178
	v_lshrrev_b32_e32 v252, 1, v250
	v_xor_b32_e32 v251, v251, v252
	v_lshlrev_b32_e32 v251, 4, v251
	v_lshl_or_b32 v250, v250, 11, v251
	v_xor_b32_e32 v251, 64, v250
	v_add_u32_e32 v251, 0x4000, v251
	v_add_u32_e32 v252, 0x8000, v250
	v_add_u32_e32 v253, 0x8000, v251
	v_lshl_add_u64 v[242:243], v[142:143], 0, s[4:5]
	v_lshl_add_u64 v[242:243], v[242:243], 0, s[38:39]
	v_lshl_add_u64 v[244:245], v[144:145], 0, s[4:5]
	v_lshl_add_u64 v[244:245], v[244:245], 0, s[40:41]
	v_add_u32_e32 v254, v128, v155
	v_add_u32_e32 v255, v139, v155
	v_readfirstlane_b32 s98, v242
	v_readfirstlane_b32 s99, v243
	v_readfirstlane_b32 s100, v244
	v_readfirstlane_b32 s101, v245
	ds_read_b128 v[206:209], v254
	ds_read_b128 v[210:213], v254 offset:2048
	ds_read_b128 v[150:153], v255 offset:32768
	ds_read_b128 v[194:197], v255 offset:34816
	ds_read_b128 v[198:201], v255 offset:36864
	ds_read_b128 v[202:205], v255 offset:38912
	s_nop 4
	s_lshl_b32 m0, s4, 9
	s_and_b32 m0, m0, 0x10000
	s_xor_b32 m0, m0, 0x10000
	s_add_i32 m0, m0, s8
	s_nop 0
	global_load_lds_dwordx4 v250, s[98:99]
	s_add_i32 m0, m0, 0x8000
	s_nop 0
	global_load_lds_dwordx4 v250, s[100:101]
	s_add_i32 m0, m0, 0xffff8400
	s_nop 0
	global_load_lds_dwordx4 v251, s[98:99]
	s_add_i32 m0, m0, 0x8000
	s_nop 0
	global_load_lds_dwordx4 v251, s[100:101]

.Lgx_75:
	s_setprio 0
	v_mfma_f32_16x16x32_bf16 v[28:31], v[150:153], v[242:245], v[28:31]
	v_mfma_f32_16x16x32_bf16 v[12:15], v[150:153], v[246:249], v[12:15]
	v_mfma_f32_16x16x32_bf16 v[24:27], v[194:197], v[242:245], v[24:27]
	v_mfma_f32_16x16x32_bf16 v[8:11], v[194:197], v[246:249], v[8:11]
	v_mfma_f32_16x16x32_bf16 v[20:23], v[198:201], v[242:245], v[20:23]
	v_mfma_f32_16x16x32_bf16 v[4:7], v[198:201], v[246:249], v[4:7]
	v_mfma_f32_16x16x32_bf16 v[16:19], v[202:205], v[242:245], v[16:19]
	v_mfma_f32_16x16x32_bf16 v[0:3], v[202:205], v[246:249], v[0:3]
	v_add_u32_e32 v139, s6, v139
	v_add_u32_e32 v141, v139, v155
	ds_read_b128 v[142:145], v141 offset:32768
	ds_read_b128 v[150:153], v141 offset:34816
	ds_read_b128 v[194:197], v141 offset:36864
	ds_read_b128 v[198:201], v141 offset:38912
	v_add_u32_e32 v128, s6, v128
	v_add_u32_e32 v193, v128, v155
	ds_read_b128 v[146:149], v193
	v_add_u32_e32 v139, v139, v156
	v_add_u32_e32 v128, v128, v156
	s_waitcnt lgkmcnt(0)
	v_mfma_f32_16x16x32_bf16 v[124:127], v[142:145], v[146:149], v[124:127]
	s_and_b64 vcc, exec, s[60:61]
	v_mfma_f32_16x16x32_bf16 v[120:123], v[150:153], v[146:149], v[120:123]
	v_mfma_f32_16x16x32_bf16 v[116:119], v[194:197], v[146:149], v[116:119]
	v_mfma_f32_16x16x32_bf16 v[112:115], v[198:201], v[146:149], v[112:115]
	ds_read_b128 v[146:149], v193 offset:2048
	s_waitcnt lgkmcnt(0)
	v_mfma_f32_16x16x32_bf16 v[108:111], v[142:145], v[146:149], v[108:111]
	v_mfma_f32_16x16x32_bf16 v[104:107], v[150:153], v[146:149], v[104:107]
	v_mfma_f32_16x16x32_bf16 v[100:103], v[194:197], v[146:149], v[100:103]
	v_mfma_f32_16x16x32_bf16 v[96:99], v[198:201], v[146:149], v[96:99]
	ds_read_b128 v[146:149], v193 offset:4096
	s_waitcnt lgkmcnt(0)
	v_mfma_f32_16x16x32_bf16 v[92:95], v[142:145], v[146:149], v[92:95]
	v_mfma_f32_16x16x32_bf16 v[88:91], v[150:153], v[146:149], v[88:91]
	v_mfma_f32_16x16x32_bf16 v[84:87], v[194:197], v[146:149], v[84:87]
	v_mfma_f32_16x16x32_bf16 v[80:83], v[198:201], v[146:149], v[80:83]
	ds_read_b128 v[146:149], v193 offset:6144
	s_waitcnt lgkmcnt(0)
	v_mfma_f32_16x16x32_bf16 v[76:79], v[142:145], v[146:149], v[76:79]
	v_mfma_f32_16x16x32_bf16 v[72:75], v[150:153], v[146:149], v[72:75]
	v_mfma_f32_16x16x32_bf16 v[68:71], v[194:197], v[146:149], v[68:71]
	v_mfma_f32_16x16x32_bf16 v[64:67], v[198:201], v[146:149], v[64:67]
	ds_read_b128 v[146:149], v193 offset:8192
	s_waitcnt lgkmcnt(0)
	v_mfma_f32_16x16x32_bf16 v[60:63], v[142:145], v[146:149], v[60:63]
	v_mfma_f32_16x16x32_bf16 v[56:59], v[150:153], v[146:149], v[56:59]
	v_mfma_f32_16x16x32_bf16 v[52:55], v[194:197], v[146:149], v[52:55]
	v_mfma_f32_16x16x32_bf16 v[48:51], v[198:201], v[146:149], v[48:51]
	ds_read_b128 v[146:149], v193 offset:10240
	s_waitcnt lgkmcnt(0)
	v_mfma_f32_16x16x32_bf16 v[44:47], v[142:145], v[146:149], v[44:47]
	v_mfma_f32_16x16x32_bf16 v[40:43], v[150:153], v[146:149], v[40:43]
	v_mfma_f32_16x16x32_bf16 v[36:39], v[194:197], v[146:149], v[36:39]
	v_mfma_f32_16x16x32_bf16 v[32:35], v[198:201], v[146:149], v[32:35]
	ds_read_b128 v[146:149], v193 offset:12288
	s_waitcnt lgkmcnt(0)
	v_mfma_f32_16x16x32_bf16 v[28:31], v[142:145], v[146:149], v[28:31]
	v_mfma_f32_16x16x32_bf16 v[24:27], v[150:153], v[146:149], v[24:27]
	v_mfma_f32_16x16x32_bf16 v[20:23], v[194:197], v[146:149], v[20:23]
	v_mfma_f32_16x16x32_bf16 v[16:19], v[198:201], v[146:149], v[16:19]
	ds_read_b128 v[146:149], v193 offset:14336
	s_waitcnt lgkmcnt(0)
	v_mfma_f32_16x16x32_bf16 v[12:15], v[142:145], v[146:149], v[12:15]
	ds_read_b128 v[142:145], v139 offset:32768
	v_mfma_f32_16x16x32_bf16 v[8:11], v[150:153], v[146:149], v[8:11]
	ds_read_b128 v[150:153], v139 offset:34816
	v_mfma_f32_16x16x32_bf16 v[4:7], v[194:197], v[146:149], v[4:7]
	ds_read_b128 v[194:197], v139 offset:36864
	v_mfma_f32_16x16x32_bf16 v[0:3], v[198:201], v[146:149], v[0:3]
	ds_read_b128 v[198:201], v139 offset:38912
	ds_read_b128 v[146:149], v128
	s_waitcnt lgkmcnt(0)
	v_mfma_f32_16x16x32_bf16 v[124:127], v[142:145], v[146:149], v[124:127]
	v_mfma_f32_16x16x32_bf16 v[120:123], v[150:153], v[146:149], v[120:123]
	v_mfma_f32_16x16x32_bf16 v[116:119], v[194:197], v[146:149], v[116:119]
	v_mfma_f32_16x16x32_bf16 v[112:115], v[198:201], v[146:149], v[112:115]
	ds_read_b128 v[146:149], v128 offset:2048
	s_waitcnt lgkmcnt(0)
	v_mfma_f32_16x16x32_bf16 v[108:111], v[142:145], v[146:149], v[108:111]
	v_mfma_f32_16x16x32_bf16 v[104:107], v[150:153], v[146:149], v[104:107]
	v_mfma_f32_16x16x32_bf16 v[100:103], v[194:197], v[146:149], v[100:103]
	v_mfma_f32_16x16x32_bf16 v[96:99], v[198:201], v[146:149], v[96:99]
	ds_read_b128 v[146:149], v128 offset:4096
	s_waitcnt lgkmcnt(0)
	v_mfma_f32_16x16x32_bf16 v[92:95], v[142:145], v[146:149], v[92:95]
	v_mfma_f32_16x16x32_bf16 v[88:91], v[150:153], v[146:149], v[88:91]
	v_mfma_f32_16x16x32_bf16 v[84:87], v[194:197], v[146:149], v[84:87]
	v_mfma_f32_16x16x32_bf16 v[80:83], v[198:201], v[146:149], v[80:83]
	ds_read_b128 v[146:149], v128 offset:6144
	s_waitcnt lgkmcnt(0)
	v_mfma_f32_16x16x32_bf16 v[76:79], v[142:145], v[146:149], v[76:79]
	v_mfma_f32_16x16x32_bf16 v[72:75], v[150:153], v[146:149], v[72:75]
	v_mfma_f32_16x16x32_bf16 v[68:71], v[194:197], v[146:149], v[68:71]
	v_mfma_f32_16x16x32_bf16 v[64:67], v[198:201], v[146:149], v[64:67]
	ds_read_b128 v[146:149], v128 offset:8192
	s_waitcnt lgkmcnt(0)
	v_mfma_f32_16x16x32_bf16 v[60:63], v[142:145], v[146:149], v[60:63]
	v_mfma_f32_16x16x32_bf16 v[56:59], v[150:153], v[146:149], v[56:59]
	v_mfma_f32_16x16x32_bf16 v[52:55], v[194:197], v[146:149], v[52:55]
	v_mfma_f32_16x16x32_bf16 v[48:51], v[198:201], v[146:149], v[48:51]
	ds_read_b128 v[146:149], v128 offset:10240
	s_waitcnt lgkmcnt(0)
	v_mfma_f32_16x16x32_bf16 v[44:47], v[142:145], v[146:149], v[44:47]
	v_mfma_f32_16x16x32_bf16 v[40:43], v[150:153], v[146:149], v[40:43]
	v_mfma_f32_16x16x32_bf16 v[36:39], v[194:197], v[146:149], v[36:39]
	v_mfma_f32_16x16x32_bf16 v[32:35], v[198:201], v[146:149], v[32:35]
	ds_read_b128 v[146:149], v128 offset:12288
	s_waitcnt lgkmcnt(0)
	v_mfma_f32_16x16x32_bf16 v[28:31], v[142:145], v[146:149], v[28:31]
	v_mfma_f32_16x16x32_bf16 v[24:27], v[150:153], v[146:149], v[24:27]
	v_mfma_f32_16x16x32_bf16 v[20:23], v[194:197], v[146:149], v[20:23]
	v_mfma_f32_16x16x32_bf16 v[16:19], v[198:201], v[146:149], v[16:19]
	ds_read_b128 v[146:149], v128 offset:14336
	s_waitcnt vmcnt(0)
	s_waitcnt lgkmcnt(0)
	v_mfma_f32_16x16x32_bf16 v[12:15], v[142:145], v[146:149], v[12:15]
	s_barrier
	v_mfma_f32_16x16x32_bf16 v[8:11], v[150:153], v[146:149], v[8:11]
	v_mfma_f32_16x16x32_bf16 v[4:7], v[194:197], v[146:149], v[4:7]
	v_mfma_f32_16x16x32_bf16 v[0:3], v[198:201], v[146:149], v[0:3]
	s_cbranch_vccz .LBB0_78
	s_lshl_b64 s[2:3], s[2:3], 1
	s_add_u32 s4, s62, s2
	s_addc_u32 s5, s63, s3
	s_add_u32 s2, s64, s2
	s_addc_u32 s3, s65, s3
	s_add_i32 s0, s8, 0
	v_mov_b32_e32 v139, v129
	s_mov_b32 m0, s0
	v_mov_b32_e32 v141, v129
	v_lshl_add_u64 v[142:143], s[4:5], 0, v[138:139]
	global_load_lds_dwordx4 v138, s[4:5]
	s_add_i32 m0, s0, 0x8000
	v_lshl_add_u64 v[146:147], s[4:5], 0, v[140:141]
	s_mov_b64 s[4:5], 0x4000
	s_add_i32 s0, s11, 0
	global_load_lds_dwordx4 v138, s[2:3]
	v_lshl_add_u64 v[148:149], v[146:147], 0, s[4:5]
	s_mov_b32 m0, s0
	v_lshl_add_u64 v[144:145], s[2:3], 0, v[138:139]
	global_load_lds_dwordx4 v[148:149], off
	v_lshl_add_u64 v[148:149], s[2:3], 0, v[140:141]
	v_lshl_add_u64 v[150:151], v[148:149], 0, s[4:5]
	s_add_i32 m0, s0, 0x8000
	s_mov_b64 s[2:3], 0x8000
	s_add_i32 s0, s10, 0
	global_load_lds_dwordx4 v[150:151], off
	v_lshl_add_u64 v[142:143], v[142:143], 0, s[2:3]
	s_mov_b32 m0, s0
	s_nop 0
	global_load_lds_dwordx4 v[142:143], off
	v_lshl_add_u64 v[142:143], v[144:145], 0, s[2:3]
	s_add_i32 m0, s0, 0x8000
	s_mov_b64 s[2:3], 0xc000
	s_add_i32 s0, s9, 0
	global_load_lds_dwordx4 v[142:143], off
	v_lshl_add_u64 v[142:143], v[146:147], 0, s[2:3]
	s_mov_b32 m0, s0
	s_nop 0
	global_load_lds_dwordx4 v[142:143], off
	v_lshl_add_u64 v[142:143], v[148:149], 0, s[2:3]
	s_add_i32 m0, s0, 0x8000
	s_nop 0
	global_load_lds_dwordx4 v[142:143], off

.LBB0_531:
	s_lshr_b32 s0, s5, 1
	s_and_b32 s0, s0, 0x1ffff80
	v_or_b32_e32 v0, s0, v154
	s_and_b32 s0, s5, 0xc0
	s_mov_b32 s5, s15
	s_lshl_b64 s[4:5], s[4:5], 16
	v_lshlrev_b32_e32 v139, 7, v0
	v_or_b32_e32 v0, s0, v154
	s_add_u32 s12, s4, s74
	v_lshlrev_b32_e32 v128, 7, v0
	v_lshl_add_u64 v[0:1], s[66:67], 0, v[130:131]
	s_addc_u32 s13, s5, s75
	s_waitcnt vmcnt(16)
	v_lshl_add_u64 v[142:143], v[0:1], 0, s[12:13]
	s_add_u32 s6, s4, s76
	v_lshl_add_u64 v[0:1], s[66:67], 0, v[134:135]
	s_addc_u32 s7, s5, s77
	v_lshl_add_u64 v[144:145], v[0:1], 0, s[12:13]
	v_mov_b32_e32 v0, 0
	s_mov_b32 s12, 0
	s_mov_b64 s[4:5], 0
	v_mov_b32_e32 v1, v0
	v_mov_b32_e32 v2, v0
	v_mov_b32_e32 v3, v0
	v_mov_b32_e32 v4, v0
	v_mov_b32_e32 v5, v0
	v_mov_b32_e32 v6, v0
	v_mov_b32_e32 v7, v0
	v_mov_b32_e32 v8, v0
	v_mov_b32_e32 v9, v0
	v_mov_b32_e32 v10, v0
	v_mov_b32_e32 v11, v0
	v_mov_b32_e32 v12, v0
	v_mov_b32_e32 v13, v0
	v_mov_b32_e32 v14, v0
	v_mov_b32_e32 v15, v0
	v_mov_b32_e32 v16, v0
	v_mov_b32_e32 v17, v0
	v_mov_b32_e32 v18, v0
	v_mov_b32_e32 v19, v0
	v_mov_b32_e32 v20, v0
	v_mov_b32_e32 v21, v0
	v_mov_b32_e32 v22, v0
	v_mov_b32_e32 v23, v0
	v_mov_b32_e32 v24, v0
	v_mov_b32_e32 v25, v0
	v_mov_b32_e32 v26, v0
	v_mov_b32_e32 v27, v0
	v_mov_b32_e32 v28, v0
	v_mov_b32_e32 v29, v0
	v_mov_b32_e32 v30, v0
	v_mov_b32_e32 v31, v0
	v_mov_b32_e32 v32, v0
	v_mov_b32_e32 v33, v0
	v_mov_b32_e32 v34, v0
	v_mov_b32_e32 v35, v0
	v_mov_b32_e32 v36, v0
	v_mov_b32_e32 v37, v0
	v_mov_b32_e32 v38, v0
	v_mov_b32_e32 v39, v0
	v_mov_b32_e32 v40, v0
	v_mov_b32_e32 v41, v0
	v_mov_b32_e32 v42, v0
	v_mov_b32_e32 v43, v0
	v_mov_b32_e32 v44, v0
	v_mov_b32_e32 v45, v0
	v_mov_b32_e32 v46, v0
	v_mov_b32_e32 v47, v0
	v_mov_b32_e32 v48, v0
	v_mov_b32_e32 v49, v0
	v_mov_b32_e32 v50, v0
	v_mov_b32_e32 v51, v0
	v_mov_b32_e32 v52, v0
	v_mov_b32_e32 v53, v0
	v_mov_b32_e32 v54, v0
	v_mov_b32_e32 v55, v0
	v_mov_b32_e32 v56, v0
	v_mov_b32_e32 v57, v0
	v_mov_b32_e32 v58, v0
	v_mov_b32_e32 v59, v0
	v_mov_b32_e32 v60, v0
	v_mov_b32_e32 v61, v0
	v_mov_b32_e32 v62, v0
	v_mov_b32_e32 v63, v0
	v_mov_b32_e32 v64, v0
	v_mov_b32_e32 v65, v0
	v_mov_b32_e32 v66, v0
	v_mov_b32_e32 v67, v0
	v_mov_b32_e32 v68, v0
	v_mov_b32_e32 v69, v0
	v_mov_b32_e32 v70, v0
	v_mov_b32_e32 v71, v0
	v_mov_b32_e32 v72, v0
	v_mov_b32_e32 v73, v0
	v_mov_b32_e32 v74, v0
	v_mov_b32_e32 v75, v0
	v_mov_b32_e32 v76, v0
	v_mov_b32_e32 v77, v0
	v_mov_b32_e32 v78, v0
	v_mov_b32_e32 v79, v0
	v_mov_b32_e32 v80, v0
	v_mov_b32_e32 v81, v0
	v_mov_b32_e32 v82, v0
	v_mov_b32_e32 v83, v0
	v_mov_b32_e32 v84, v0
	v_mov_b32_e32 v85, v0
	v_mov_b32_e32 v86, v0
	v_mov_b32_e32 v87, v0
	v_mov_b32_e32 v88, v0
	v_mov_b32_e32 v89, v0
	v_mov_b32_e32 v90, v0
	v_mov_b32_e32 v91, v0
	v_mov_b32_e32 v92, v0
	v_mov_b32_e32 v93, v0
	v_mov_b32_e32 v94, v0
	v_mov_b32_e32 v95, v0
	v_mov_b32_e32 v96, v0
	v_mov_b32_e32 v97, v0
	v_mov_b32_e32 v98, v0
	v_mov_b32_e32 v99, v0
	v_mov_b32_e32 v100, v0
	v_mov_b32_e32 v101, v0
	v_mov_b32_e32 v102, v0
	v_mov_b32_e32 v103, v0
	v_mov_b32_e32 v104, v0
	v_mov_b32_e32 v105, v0
	v_mov_b32_e32 v106, v0
	v_mov_b32_e32 v107, v0
	v_mov_b32_e32 v108, v0
	v_mov_b32_e32 v109, v0
	v_mov_b32_e32 v110, v0
	v_mov_b32_e32 v111, v0
	v_mov_b32_e32 v112, v0
	v_mov_b32_e32 v113, v0
	v_mov_b32_e32 v114, v0
	v_mov_b32_e32 v115, v0
	v_mov_b32_e32 v116, v0
	v_mov_b32_e32 v117, v0
	v_mov_b32_e32 v118, v0
	v_mov_b32_e32 v119, v0
	v_mov_b32_e32 v120, v0
	v_mov_b32_e32 v121, v0
	v_mov_b32_e32 v122, v0
	v_mov_b32_e32 v123, v0
	v_mov_b32_e32 v124, v0
	v_mov_b32_e32 v125, v0
	v_mov_b32_e32 v126, v0
	v_mov_b32_e32 v127, v0
	v_lshl_add_u64 v[146:147], v[132:133], 0, s[6:7]
	v_lshl_add_u64 v[148:149], v[136:137], 0, s[6:7]
	s_waitcnt vmcnt(16) lgkmcnt(0)
	s_barrier
	v_readfirstlane_b32 s98, v178
	s_nop 3
	s_lshr_b32 s98, s98, 6
	s_cmp_ge_u32 s98, 4
	s_cbranch_scc0 .Lprio_done_2
	s_setprio 1
.Lprio_done_2:
	v_bfe_u32 v250, v178, 3, 3
	v_and_b32_e32 v251, 7, v178
	v_lshrrev_b32_e32 v252, 1, v250
	v_xor_b32_e32 v251, v251, v252
	v_lshlrev_b32_e32 v251, 4, v251
	v_lshl_or_b32 v250, v250, 11, v251
	v_xor_b32_e32 v251, 64, v250
	v_add_u32_e32 v251, 0x4000, v251
	v_add_u32_e32 v252, 0x8000, v250
	v_add_u32_e32 v253, 0x8000, v251
	v_lshl_add_u64 v[242:243], v[142:143], 0, s[4:5]
	v_lshl_add_u64 v[242:243], v[242:243], 0, s[38:39]
	v_lshl_add_u64 v[244:245], v[146:147], 0, s[4:5]
	v_lshl_add_u64 v[244:245], v[244:245], 0, s[40:41]
	v_add_u32_e32 v254, v139, v155
	v_add_u32_e32 v255, v128, v155
	v_readfirstlane_b32 s98, v242
	v_readfirstlane_b32 s99, v243
	v_readfirstlane_b32 s100, v244
	v_readfirstlane_b32 s101, v245
	ds_read_b128 v[206:209], v254
	ds_read_b128 v[210:213], v254 offset:2048
	ds_read_b128 v[150:153], v255 offset:32768
	ds_read_b128 v[194:197], v255 offset:34816
	ds_read_b128 v[198:201], v255 offset:36864
	ds_read_b128 v[202:205], v255 offset:38912
	s_nop 4
	s_lshl_b32 m0, s4, 9
	s_and_b32 m0, m0, 0x10000
	s_xor_b32 m0, m0, 0x10000
	s_add_i32 m0, m0, s8
	s_nop 0
	global_load_lds_dwordx4 v250, s[98:99]
	s_add_i32 m0, m0, 0x8000
	s_nop 0
	global_load_lds_dwordx4 v250, s[100:101]
	s_add_i32 m0, m0, 0xffff8400
	s_nop 0
	global_load_lds_dwordx4 v251, s[98:99]
	s_add_i32 m0, m0, 0x8000
	s_nop 0
	global_load_lds_dwordx4 v251, s[100:101]

.Lgx_532:
	s_setprio 0
	v_mfma_f32_16x16x32_bf16 v[28:31], v[242:245], v[150:153], v[28:31]
	v_mfma_f32_16x16x32_bf16 v[12:15], v[246:249], v[150:153], v[12:15]
	v_mfma_f32_16x16x32_bf16 v[24:27], v[242:245], v[194:197], v[24:27]
	v_mfma_f32_16x16x32_bf16 v[8:11], v[246:249], v[194:197], v[8:11]
	v_mfma_f32_16x16x32_bf16 v[20:23], v[242:245], v[198:201], v[20:23]
	v_mfma_f32_16x16x32_bf16 v[4:7], v[246:249], v[198:201], v[4:7]
	v_mfma_f32_16x16x32_bf16 v[16:19], v[242:245], v[202:205], v[16:19]
	v_mfma_f32_16x16x32_bf16 v[0:3], v[246:249], v[202:205], v[0:3]
	s_add_i32 s0, 0, 0x10000
	v_add_u32_e32 v139, s0, v139
	v_add_u32_e32 v141, v139, v155
	ds_read_b128 v[142:145], v141
	v_add_u32_e32 v128, s0, v128
	v_add_u32_e32 v193, v128, v155
	ds_read_b128 v[146:149], v193 offset:32768
	ds_read_b128 v[150:153], v193 offset:34816
	ds_read_b128 v[194:197], v193 offset:36864
	ds_read_b128 v[198:201], v193 offset:38912
	v_add_u32_e32 v139, v139, v156
	v_add_u32_e32 v128, v128, v156
	s_waitcnt lgkmcnt(3)
	v_mfma_f32_16x16x32_bf16 v[124:127], v[142:145], v[146:149], v[124:127]
	s_and_b64 vcc, exec, s[60:61]
	s_waitcnt lgkmcnt(2)
	v_mfma_f32_16x16x32_bf16 v[120:123], v[142:145], v[150:153], v[120:123]
	s_waitcnt lgkmcnt(1)
	v_mfma_f32_16x16x32_bf16 v[116:119], v[142:145], v[194:197], v[116:119]
	s_waitcnt lgkmcnt(0)
	v_mfma_f32_16x16x32_bf16 v[112:115], v[142:145], v[198:201], v[112:115]
	ds_read_b128 v[142:145], v141 offset:2048
	s_waitcnt lgkmcnt(0)
	v_mfma_f32_16x16x32_bf16 v[108:111], v[142:145], v[146:149], v[108:111]
	v_mfma_f32_16x16x32_bf16 v[104:107], v[142:145], v[150:153], v[104:107]
	v_mfma_f32_16x16x32_bf16 v[100:103], v[142:145], v[194:197], v[100:103]
	v_mfma_f32_16x16x32_bf16 v[96:99], v[142:145], v[198:201], v[96:99]
	ds_read_b128 v[142:145], v141 offset:4096
	s_waitcnt lgkmcnt(0)
	v_mfma_f32_16x16x32_bf16 v[92:95], v[142:145], v[146:149], v[92:95]
	v_mfma_f32_16x16x32_bf16 v[88:91], v[142:145], v[150:153], v[88:91]
	v_mfma_f32_16x16x32_bf16 v[84:87], v[142:145], v[194:197], v[84:87]
	v_mfma_f32_16x16x32_bf16 v[80:83], v[142:145], v[198:201], v[80:83]
	ds_read_b128 v[142:145], v141 offset:6144
	s_waitcnt lgkmcnt(0)
	v_mfma_f32_16x16x32_bf16 v[76:79], v[142:145], v[146:149], v[76:79]
	v_mfma_f32_16x16x32_bf16 v[72:75], v[142:145], v[150:153], v[72:75]
	v_mfma_f32_16x16x32_bf16 v[68:71], v[142:145], v[194:197], v[68:71]
	v_mfma_f32_16x16x32_bf16 v[64:67], v[142:145], v[198:201], v[64:67]
	ds_read_b128 v[142:145], v141 offset:8192
	s_waitcnt lgkmcnt(0)
	v_mfma_f32_16x16x32_bf16 v[60:63], v[142:145], v[146:149], v[60:63]
	v_mfma_f32_16x16x32_bf16 v[56:59], v[142:145], v[150:153], v[56:59]
	v_mfma_f32_16x16x32_bf16 v[52:55], v[142:145], v[194:197], v[52:55]
	v_mfma_f32_16x16x32_bf16 v[48:51], v[142:145], v[198:201], v[48:51]
	ds_read_b128 v[142:145], v141 offset:10240
	s_waitcnt lgkmcnt(0)
	v_mfma_f32_16x16x32_bf16 v[44:47], v[142:145], v[146:149], v[44:47]
	v_mfma_f32_16x16x32_bf16 v[40:43], v[142:145], v[150:153], v[40:43]
	v_mfma_f32_16x16x32_bf16 v[36:39], v[142:145], v[194:197], v[36:39]
	v_mfma_f32_16x16x32_bf16 v[32:35], v[142:145], v[198:201], v[32:35]
	ds_read_b128 v[142:145], v141 offset:12288
	s_waitcnt lgkmcnt(0)
	v_mfma_f32_16x16x32_bf16 v[28:31], v[142:145], v[146:149], v[28:31]
	v_mfma_f32_16x16x32_bf16 v[24:27], v[142:145], v[150:153], v[24:27]
	v_mfma_f32_16x16x32_bf16 v[20:23], v[142:145], v[194:197], v[20:23]
	v_mfma_f32_16x16x32_bf16 v[16:19], v[142:145], v[198:201], v[16:19]
	ds_read_b128 v[142:145], v141 offset:14336
	s_waitcnt lgkmcnt(0)
	v_mfma_f32_16x16x32_bf16 v[12:15], v[142:145], v[146:149], v[12:15]
	ds_read_b128 v[146:149], v139
	v_mfma_f32_16x16x32_bf16 v[8:11], v[142:145], v[150:153], v[8:11]
	ds_read_b128 v[150:153], v128 offset:34816
	v_mfma_f32_16x16x32_bf16 v[4:7], v[142:145], v[194:197], v[4:7]
	ds_read_b128 v[194:197], v128 offset:36864
	v_mfma_f32_16x16x32_bf16 v[0:3], v[142:145], v[198:201], v[0:3]
	ds_read_b128 v[142:145], v128 offset:32768
	ds_read_b128 v[198:201], v128 offset:38912
	s_waitcnt lgkmcnt(1)
	v_mfma_f32_16x16x32_bf16 v[124:127], v[146:149], v[142:145], v[124:127]
	v_mfma_f32_16x16x32_bf16 v[120:123], v[146:149], v[150:153], v[120:123]
	v_mfma_f32_16x16x32_bf16 v[116:119], v[146:149], v[194:197], v[116:119]
	s_waitcnt lgkmcnt(0)
	v_mfma_f32_16x16x32_bf16 v[112:115], v[146:149], v[198:201], v[112:115]
	ds_read_b128 v[146:149], v139 offset:2048
	s_waitcnt lgkmcnt(0)
	v_mfma_f32_16x16x32_bf16 v[108:111], v[146:149], v[142:145], v[108:111]
	v_mfma_f32_16x16x32_bf16 v[104:107], v[146:149], v[150:153], v[104:107]
	v_mfma_f32_16x16x32_bf16 v[100:103], v[146:149], v[194:197], v[100:103]
	v_mfma_f32_16x16x32_bf16 v[96:99], v[146:149], v[198:201], v[96:99]
	ds_read_b128 v[146:149], v139 offset:4096
	s_waitcnt lgkmcnt(0)
	v_mfma_f32_16x16x32_bf16 v[92:95], v[146:149], v[142:145], v[92:95]
	v_mfma_f32_16x16x32_bf16 v[88:91], v[146:149], v[150:153], v[88:91]
	v_mfma_f32_16x16x32_bf16 v[84:87], v[146:149], v[194:197], v[84:87]
	v_mfma_f32_16x16x32_bf16 v[80:83], v[146:149], v[198:201], v[80:83]
	ds_read_b128 v[146:149], v139 offset:6144
	s_waitcnt lgkmcnt(0)
	v_mfma_f32_16x16x32_bf16 v[76:79], v[146:149], v[142:145], v[76:79]
	v_mfma_f32_16x16x32_bf16 v[72:75], v[146:149], v[150:153], v[72:75]
	v_mfma_f32_16x16x32_bf16 v[68:71], v[146:149], v[194:197], v[68:71]
	v_mfma_f32_16x16x32_bf16 v[64:67], v[146:149], v[198:201], v[64:67]
	ds_read_b128 v[146:149], v139 offset:8192
	s_waitcnt lgkmcnt(0)
	v_mfma_f32_16x16x32_bf16 v[60:63], v[146:149], v[142:145], v[60:63]
	v_mfma_f32_16x16x32_bf16 v[56:59], v[146:149], v[150:153], v[56:59]
	v_mfma_f32_16x16x32_bf16 v[52:55], v[146:149], v[194:197], v[52:55]
	v_mfma_f32_16x16x32_bf16 v[48:51], v[146:149], v[198:201], v[48:51]
	ds_read_b128 v[146:149], v139 offset:10240
	s_waitcnt lgkmcnt(0)
	v_mfma_f32_16x16x32_bf16 v[44:47], v[146:149], v[142:145], v[44:47]
	v_mfma_f32_16x16x32_bf16 v[40:43], v[146:149], v[150:153], v[40:43]
	v_mfma_f32_16x16x32_bf16 v[36:39], v[146:149], v[194:197], v[36:39]
	v_mfma_f32_16x16x32_bf16 v[32:35], v[146:149], v[198:201], v[32:35]
	ds_read_b128 v[146:149], v139 offset:12288
	s_waitcnt lgkmcnt(0)
	v_mfma_f32_16x16x32_bf16 v[28:31], v[146:149], v[142:145], v[28:31]
	v_mfma_f32_16x16x32_bf16 v[24:27], v[146:149], v[150:153], v[24:27]
	v_mfma_f32_16x16x32_bf16 v[20:23], v[146:149], v[194:197], v[20:23]
	v_mfma_f32_16x16x32_bf16 v[16:19], v[146:149], v[198:201], v[16:19]
	ds_read_b128 v[146:149], v139 offset:14336
	s_waitcnt vmcnt(0)
	s_waitcnt lgkmcnt(0)
	v_mfma_f32_16x16x32_bf16 v[12:15], v[146:149], v[142:145], v[12:15]
	s_barrier
	v_mfma_f32_16x16x32_bf16 v[8:11], v[146:149], v[150:153], v[8:11]
	v_mfma_f32_16x16x32_bf16 v[4:7], v[146:149], v[194:197], v[4:7]
	v_mfma_f32_16x16x32_bf16 v[0:3], v[146:149], v[198:201], v[0:3]
	s_cbranch_vccz .LBB0_535
	s_lshl_b64 s[2:3], s[2:3], 1
	s_add_u32 s4, s62, s2
	s_addc_u32 s5, s63, s3
	s_add_u32 s2, s64, s2
	s_addc_u32 s3, s65, s3
	s_add_i32 s0, s8, 0
	v_mov_b32_e32 v139, v129
	s_mov_b32 m0, s0
	v_mov_b32_e32 v141, v129
	v_lshl_add_u64 v[142:143], s[4:5], 0, v[138:139]
	global_load_lds_dwordx4 v138, s[4:5]
	s_add_i32 m0, s0, 0x8000
	v_lshl_add_u64 v[146:147], s[4:5], 0, v[140:141]
	s_mov_b64 s[4:5], 0x4000
	s_add_i32 s0, s11, 0
	global_load_lds_dwordx4 v138, s[2:3]
	v_lshl_add_u64 v[148:149], v[146:147], 0, s[4:5]
	s_mov_b32 m0, s0
	v_lshl_add_u64 v[144:145], s[2:3], 0, v[138:139]
	global_load_lds_dwordx4 v[148:149], off
	v_lshl_add_u64 v[148:149], s[2:3], 0, v[140:141]
	v_lshl_add_u64 v[150:151], v[148:149], 0, s[4:5]
	s_add_i32 m0, s0, 0x8000
	s_mov_b64 s[2:3], 0x8000
	s_add_i32 s0, s10, 0
	global_load_lds_dwordx4 v[150:151], off
	v_lshl_add_u64 v[142:143], v[142:143], 0, s[2:3]
	s_mov_b32 m0, s0
	s_nop 0
	global_load_lds_dwordx4 v[142:143], off
	v_lshl_add_u64 v[142:143], v[144:145], 0, s[2:3]
	s_add_i32 m0, s0, 0x8000
	s_mov_b64 s[2:3], 0xc000
	s_add_i32 s0, s9, 0
	global_load_lds_dwordx4 v[142:143], off
	v_lshl_add_u64 v[142:143], v[146:147], 0, s[2:3]
	s_mov_b32 m0, s0
	s_nop 0
	global_load_lds_dwordx4 v[142:143], off
	v_lshl_add_u64 v[142:143], v[148:149], 0, s[2:3]
	s_add_i32 m0, s0, 0x8000
	s_nop 0
	global_load_lds_dwordx4 v[142:143], off

.LBB0_735:
	s_lshr_b32 s38, s37, 1
	s_and_b32 s38, s38, 0x1ffff80
	v_or_b32_e32 v0, s38, v148
	s_and_b32 s37, s37, 0xc0
	v_lshlrev_b32_e32 v139, 7, v0
	v_or_b32_e32 v0, s37, v148
	s_mov_b32 s37, s3
	s_lshl_b64 s[36:37], s[36:37], 16
	s_add_u32 s30, s36, s30
	v_lshlrev_b32_e32 v153, 7, v0
	v_lshl_add_u64 v[0:1], s[28:29], 0, v[130:131]
	s_addc_u32 s31, s37, s31
	s_waitcnt vmcnt(16)
	v_lshl_add_u64 v[140:141], v[0:1], 0, s[30:31]
	s_add_u32 s34, s36, s34
	v_lshl_add_u64 v[0:1], s[28:29], 0, v[134:135]
	s_addc_u32 s35, s37, s35
	v_lshl_add_u64 v[144:145], v[0:1], 0, s[30:31]
	v_mov_b32_e32 v0, 0
	v_lshl_add_u64 v[142:143], v[132:133], 0, s[34:35]
	v_lshl_add_u64 v[146:147], v[136:137], 0, s[34:35]
	s_mov_b64 s[28:29], 0
	s_mov_b32 s34, 0
	v_mov_b32_e32 v1, v0
	v_mov_b32_e32 v2, v0
	v_mov_b32_e32 v3, v0
	v_mov_b32_e32 v4, v0
	v_mov_b32_e32 v5, v0
	v_mov_b32_e32 v6, v0
	v_mov_b32_e32 v7, v0
	v_mov_b32_e32 v8, v0
	v_mov_b32_e32 v9, v0
	v_mov_b32_e32 v10, v0
	v_mov_b32_e32 v11, v0
	v_mov_b32_e32 v12, v0
	v_mov_b32_e32 v13, v0
	v_mov_b32_e32 v14, v0
	v_mov_b32_e32 v15, v0
	v_mov_b32_e32 v16, v0
	v_mov_b32_e32 v17, v0
	v_mov_b32_e32 v18, v0
	v_mov_b32_e32 v19, v0
	v_mov_b32_e32 v20, v0
	v_mov_b32_e32 v21, v0
	v_mov_b32_e32 v22, v0
	v_mov_b32_e32 v23, v0
	v_mov_b32_e32 v24, v0
	v_mov_b32_e32 v25, v0
	v_mov_b32_e32 v26, v0
	v_mov_b32_e32 v27, v0
	v_mov_b32_e32 v28, v0
	v_mov_b32_e32 v29, v0
	v_mov_b32_e32 v30, v0
	v_mov_b32_e32 v31, v0
	v_mov_b32_e32 v32, v0
	v_mov_b32_e32 v33, v0
	v_mov_b32_e32 v34, v0
	v_mov_b32_e32 v35, v0
	v_mov_b32_e32 v36, v0
	v_mov_b32_e32 v37, v0
	v_mov_b32_e32 v38, v0
	v_mov_b32_e32 v39, v0
	v_mov_b32_e32 v40, v0
	v_mov_b32_e32 v41, v0
	v_mov_b32_e32 v42, v0
	v_mov_b32_e32 v43, v0
	v_mov_b32_e32 v44, v0
	v_mov_b32_e32 v45, v0
	v_mov_b32_e32 v46, v0
	v_mov_b32_e32 v47, v0
	v_mov_b32_e32 v48, v0
	v_mov_b32_e32 v49, v0
	v_mov_b32_e32 v50, v0
	v_mov_b32_e32 v51, v0
	v_mov_b32_e32 v52, v0
	v_mov_b32_e32 v53, v0
	v_mov_b32_e32 v54, v0
	v_mov_b32_e32 v55, v0
	v_mov_b32_e32 v56, v0
	v_mov_b32_e32 v57, v0
	v_mov_b32_e32 v58, v0
	v_mov_b32_e32 v59, v0
	v_mov_b32_e32 v60, v0
	v_mov_b32_e32 v61, v0
	v_mov_b32_e32 v62, v0
	v_mov_b32_e32 v63, v0
	v_mov_b32_e32 v64, v0
	v_mov_b32_e32 v65, v0
	v_mov_b32_e32 v66, v0
	v_mov_b32_e32 v67, v0
	v_mov_b32_e32 v68, v0
	v_mov_b32_e32 v69, v0
	v_mov_b32_e32 v70, v0
	v_mov_b32_e32 v71, v0
	v_mov_b32_e32 v72, v0
	v_mov_b32_e32 v73, v0
	v_mov_b32_e32 v74, v0
	v_mov_b32_e32 v75, v0
	v_mov_b32_e32 v76, v0
	v_mov_b32_e32 v77, v0
	v_mov_b32_e32 v78, v0
	v_mov_b32_e32 v79, v0
	v_mov_b32_e32 v80, v0
	v_mov_b32_e32 v81, v0
	v_mov_b32_e32 v82, v0
	v_mov_b32_e32 v83, v0
	v_mov_b32_e32 v84, v0
	v_mov_b32_e32 v85, v0
	v_mov_b32_e32 v86, v0
	v_mov_b32_e32 v87, v0
	v_mov_b32_e32 v88, v0
	v_mov_b32_e32 v89, v0
	v_mov_b32_e32 v90, v0
	v_mov_b32_e32 v91, v0
	v_mov_b32_e32 v92, v0
	v_mov_b32_e32 v93, v0
	v_mov_b32_e32 v94, v0
	v_mov_b32_e32 v95, v0
	v_mov_b32_e32 v96, v0
	v_mov_b32_e32 v97, v0
	v_mov_b32_e32 v98, v0
	v_mov_b32_e32 v99, v0
	v_mov_b32_e32 v100, v0
	v_mov_b32_e32 v101, v0
	v_mov_b32_e32 v102, v0
	v_mov_b32_e32 v103, v0
	v_mov_b32_e32 v104, v0
	v_mov_b32_e32 v105, v0
	v_mov_b32_e32 v106, v0
	v_mov_b32_e32 v107, v0
	v_mov_b32_e32 v108, v0
	v_mov_b32_e32 v109, v0
	v_mov_b32_e32 v110, v0
	v_mov_b32_e32 v111, v0
	v_mov_b32_e32 v112, v0
	v_mov_b32_e32 v113, v0
	v_mov_b32_e32 v114, v0
	v_mov_b32_e32 v115, v0
	v_mov_b32_e32 v116, v0
	v_mov_b32_e32 v117, v0
	v_mov_b32_e32 v118, v0
	v_mov_b32_e32 v119, v0
	v_mov_b32_e32 v120, v0
	v_mov_b32_e32 v121, v0
	v_mov_b32_e32 v122, v0
	v_mov_b32_e32 v123, v0
	v_mov_b32_e32 v124, v0
	v_mov_b32_e32 v125, v0
	v_mov_b32_e32 v126, v0
	v_mov_b32_e32 v127, v0
	s_waitcnt vmcnt(16) lgkmcnt(0)
	s_barrier
	v_readfirstlane_b32 s98, v178
	s_nop 3
	s_lshr_b32 s98, s98, 6
	s_cmp_ge_u32 s98, 4
	s_cbranch_scc0 .Lprio_done_3
	s_setprio 1
.Lprio_done_3:
	v_bfe_u32 v250, v178, 3, 3
	v_and_b32_e32 v251, 7, v178
	v_lshrrev_b32_e32 v252, 1, v250
	v_xor_b32_e32 v251, v251, v252
	v_lshlrev_b32_e32 v251, 4, v251
	v_lshl_or_b32 v250, v250, 11, v251
	v_xor_b32_e32 v251, 64, v250
	v_add_u32_e32 v251, 0x4000, v251
	v_add_u32_e32 v252, 0x8000, v250
	v_add_u32_e32 v253, 0x8000, v251
	v_lshl_add_u64 v[242:243], v[140:141], 0, s[28:29]
	s_mov_b64 s[36:37], 0x80
	v_lshl_add_u64 v[242:243], v[242:243], 0, s[36:37]
	v_lshl_add_u64 v[244:245], v[142:143], 0, s[28:29]
	s_mov_b64 s[36:37], 0x12c00080
	v_lshl_add_u64 v[244:245], v[244:245], 0, s[36:37]
	v_add_u32_e32 v254, v139, v149
	v_add_u32_e32 v255, v153, v149
	v_readfirstlane_b32 s98, v242
	v_readfirstlane_b32 s99, v243
	v_readfirstlane_b32 s100, v244
	v_readfirstlane_b32 s101, v245
	ds_read_b128 v[170:173], v254
	ds_read_b128 v[174:177], v254 offset:2048
	ds_read_b128 v[154:157], v255 offset:32768
	ds_read_b128 v[158:161], v255 offset:34816
	ds_read_b128 v[162:165], v255 offset:36864
	ds_read_b128 v[166:169], v255 offset:38912
	s_nop 4
	s_lshl_b32 m0, s28, 9
	s_and_b32 m0, m0, 0x10000
	s_xor_b32 m0, m0, 0x10000
	s_add_i32 m0, m0, s2
	s_nop 0
	global_load_lds_dwordx4 v250, s[98:99]
	s_add_i32 m0, m0, 0x8000
	s_nop 0
	global_load_lds_dwordx4 v250, s[100:101]
	s_add_i32 m0, m0, 0xffff8400
	s_nop 0
	global_load_lds_dwordx4 v251, s[98:99]
	s_add_i32 m0, m0, 0x8000
	s_nop 0
	global_load_lds_dwordx4 v251, s[100:101]

.Lgx_736:
	s_setprio 0
	v_mfma_f32_16x16x32_bf16 v[28:31], v[154:157], v[242:245], v[28:31]
	v_mfma_f32_16x16x32_bf16 v[12:15], v[154:157], v[246:249], v[12:15]
	v_mfma_f32_16x16x32_bf16 v[24:27], v[158:161], v[242:245], v[24:27]
	v_mfma_f32_16x16x32_bf16 v[8:11], v[158:161], v[246:249], v[8:11]
	v_mfma_f32_16x16x32_bf16 v[20:23], v[162:165], v[242:245], v[20:23]
	v_mfma_f32_16x16x32_bf16 v[4:7], v[162:165], v[246:249], v[4:7]
	v_mfma_f32_16x16x32_bf16 v[16:19], v[166:169], v[242:245], v[16:19]
	v_mfma_f32_16x16x32_bf16 v[0:3], v[166:169], v[246:249], v[0:3]
	v_add_u32_e32 v153, s30, v153
	v_add_u32_e32 v166, v153, v149
	v_add_u32_e32 v139, s30, v139
	ds_read_b128 v[140:143], v166 offset:32768
	v_add_u32_e32 v170, v139, v149
	ds_read_b128 v[144:147], v166 offset:34816
	ds_read_b128 v[154:157], v170
	ds_read_b128 v[158:161], v170 offset:2048
	ds_read_b128 v[162:165], v166 offset:36864
	ds_read_b128 v[166:169], v166 offset:38912
	s_waitcnt lgkmcnt(3)
	v_mfma_f32_16x16x32_bf16 v[120:123], v[144:147], v[154:157], v[120:123]
	v_add_u32_e32 v153, v153, v150
	v_add_u32_e32 v139, v139, v150
	s_and_b64 vcc, exec, s[20:21]
	v_mfma_f32_16x16x32_bf16 v[124:127], v[140:143], v[154:157], v[124:127]
	s_waitcnt lgkmcnt(1)
	v_mfma_f32_16x16x32_bf16 v[116:119], v[162:165], v[154:157], v[116:119]
	s_waitcnt lgkmcnt(0)
	v_mfma_f32_16x16x32_bf16 v[112:115], v[166:169], v[154:157], v[112:115]
	v_mfma_f32_16x16x32_bf16 v[108:111], v[140:143], v[158:161], v[108:111]
	v_mfma_f32_16x16x32_bf16 v[104:107], v[144:147], v[158:161], v[104:107]
	v_mfma_f32_16x16x32_bf16 v[100:103], v[162:165], v[158:161], v[100:103]
	v_mfma_f32_16x16x32_bf16 v[96:99], v[166:169], v[158:161], v[96:99]
	ds_read_b128 v[154:157], v170 offset:4096
	ds_read_b128 v[158:161], v170 offset:6144
	s_waitcnt lgkmcnt(1)
	v_mfma_f32_16x16x32_bf16 v[92:95], v[140:143], v[154:157], v[92:95]
	v_mfma_f32_16x16x32_bf16 v[88:91], v[144:147], v[154:157], v[88:91]
	v_mfma_f32_16x16x32_bf16 v[84:87], v[162:165], v[154:157], v[84:87]
	v_mfma_f32_16x16x32_bf16 v[80:83], v[166:169], v[154:157], v[80:83]
	s_waitcnt lgkmcnt(0)
	v_mfma_f32_16x16x32_bf16 v[76:79], v[140:143], v[158:161], v[76:79]
	v_mfma_f32_16x16x32_bf16 v[72:75], v[144:147], v[158:161], v[72:75]
	v_mfma_f32_16x16x32_bf16 v[68:71], v[162:165], v[158:161], v[68:71]
	v_mfma_f32_16x16x32_bf16 v[64:67], v[166:169], v[158:161], v[64:67]
	ds_read_b128 v[154:157], v170 offset:8192
	ds_read_b128 v[158:161], v170 offset:10240
	s_waitcnt lgkmcnt(1)
	v_mfma_f32_16x16x32_bf16 v[60:63], v[140:143], v[154:157], v[60:63]
	v_mfma_f32_16x16x32_bf16 v[56:59], v[144:147], v[154:157], v[56:59]
	v_mfma_f32_16x16x32_bf16 v[52:55], v[162:165], v[154:157], v[52:55]
	v_mfma_f32_16x16x32_bf16 v[48:51], v[166:169], v[154:157], v[48:51]
	s_waitcnt lgkmcnt(0)
	v_mfma_f32_16x16x32_bf16 v[44:47], v[140:143], v[158:161], v[44:47]
	v_mfma_f32_16x16x32_bf16 v[40:43], v[144:147], v[158:161], v[40:43]
	v_mfma_f32_16x16x32_bf16 v[36:39], v[162:165], v[158:161], v[36:39]
	v_mfma_f32_16x16x32_bf16 v[32:35], v[166:169], v[158:161], v[32:35]
	ds_read_b128 v[154:157], v170 offset:12288
	ds_read_b128 v[158:161], v170 offset:14336
	s_waitcnt lgkmcnt(1)
	v_mfma_f32_16x16x32_bf16 v[28:31], v[140:143], v[154:157], v[28:31]
	v_mfma_f32_16x16x32_bf16 v[24:27], v[144:147], v[154:157], v[24:27]
	v_mfma_f32_16x16x32_bf16 v[20:23], v[162:165], v[154:157], v[20:23]
	v_mfma_f32_16x16x32_bf16 v[16:19], v[166:169], v[154:157], v[16:19]
	s_waitcnt lgkmcnt(0)
	v_mfma_f32_16x16x32_bf16 v[12:15], v[140:143], v[158:161], v[12:15]
	v_mfma_f32_16x16x32_bf16 v[8:11], v[144:147], v[158:161], v[8:11]
	ds_read_b128 v[144:147], v153 offset:34816
	v_mfma_f32_16x16x32_bf16 v[140:143], v[162:165], v[158:161], v[4:7]
	s_nop 2
	ds_read_b128 v[4:7], v153 offset:32768
	v_mfma_f32_16x16x32_bf16 v[0:3], v[166:169], v[158:161], v[0:3]
	ds_read_b128 v[154:157], v139
	ds_read_b128 v[158:161], v139 offset:2048
	ds_read_b128 v[162:165], v153 offset:36864
	ds_read_b128 v[166:169], v153 offset:38912
	s_waitcnt lgkmcnt(3)
	v_mfma_f32_16x16x32_bf16 v[124:127], v[4:7], v[154:157], v[124:127]
	v_mfma_f32_16x16x32_bf16 v[120:123], v[144:147], v[154:157], v[120:123]
	s_waitcnt lgkmcnt(1)
	v_mfma_f32_16x16x32_bf16 v[116:119], v[162:165], v[154:157], v[116:119]
	s_waitcnt lgkmcnt(0)
	v_mfma_f32_16x16x32_bf16 v[112:115], v[166:169], v[154:157], v[112:115]
	v_mfma_f32_16x16x32_bf16 v[108:111], v[4:7], v[158:161], v[108:111]
	v_mfma_f32_16x16x32_bf16 v[104:107], v[144:147], v[158:161], v[104:107]
	v_mfma_f32_16x16x32_bf16 v[100:103], v[162:165], v[158:161], v[100:103]
	v_mfma_f32_16x16x32_bf16 v[96:99], v[166:169], v[158:161], v[96:99]
	ds_read_b128 v[154:157], v139 offset:4096
	ds_read_b128 v[158:161], v139 offset:6144
	s_waitcnt lgkmcnt(1)
	v_mfma_f32_16x16x32_bf16 v[92:95], v[4:7], v[154:157], v[92:95]
	v_mfma_f32_16x16x32_bf16 v[88:91], v[144:147], v[154:157], v[88:91]
	v_mfma_f32_16x16x32_bf16 v[84:87], v[162:165], v[154:157], v[84:87]
	v_mfma_f32_16x16x32_bf16 v[80:83], v[166:169], v[154:157], v[80:83]
	s_waitcnt lgkmcnt(0)
	v_mfma_f32_16x16x32_bf16 v[76:79], v[4:7], v[158:161], v[76:79]
	v_mfma_f32_16x16x32_bf16 v[72:75], v[144:147], v[158:161], v[72:75]
	v_mfma_f32_16x16x32_bf16 v[68:71], v[162:165], v[158:161], v[68:71]
	v_mfma_f32_16x16x32_bf16 v[64:67], v[166:169], v[158:161], v[64:67]
	ds_read_b128 v[154:157], v139 offset:8192
	ds_read_b128 v[158:161], v139 offset:10240
	s_waitcnt lgkmcnt(1)
	v_mfma_f32_16x16x32_bf16 v[60:63], v[4:7], v[154:157], v[60:63]
	v_mfma_f32_16x16x32_bf16 v[56:59], v[144:147], v[154:157], v[56:59]
	v_mfma_f32_16x16x32_bf16 v[52:55], v[162:165], v[154:157], v[52:55]
	v_mfma_f32_16x16x32_bf16 v[48:51], v[166:169], v[154:157], v[48:51]
	s_waitcnt lgkmcnt(0)
	v_mfma_f32_16x16x32_bf16 v[44:47], v[4:7], v[158:161], v[44:47]
	v_mfma_f32_16x16x32_bf16 v[40:43], v[144:147], v[158:161], v[40:43]
	v_mfma_f32_16x16x32_bf16 v[36:39], v[162:165], v[158:161], v[36:39]
	v_mfma_f32_16x16x32_bf16 v[32:35], v[166:169], v[158:161], v[32:35]
	ds_read_b128 v[154:157], v139 offset:12288
	ds_read_b128 v[158:161], v139 offset:14336
	s_waitcnt vmcnt(0)
	s_waitcnt lgkmcnt(0)
	v_mfma_f32_16x16x32_bf16 v[28:31], v[4:7], v[154:157], v[28:31]
	s_barrier
	v_mfma_f32_16x16x32_bf16 v[24:27], v[144:147], v[154:157], v[24:27]
	v_mfma_f32_16x16x32_bf16 v[20:23], v[162:165], v[154:157], v[20:23]
	v_mfma_f32_16x16x32_bf16 v[16:19], v[166:169], v[154:157], v[16:19]
	v_mfma_f32_16x16x32_bf16 v[12:15], v[4:7], v[158:161], v[12:15]
	v_mfma_f32_16x16x32_bf16 v[4:7], v[144:147], v[158:161], v[8:11]
	v_mfma_f32_16x16x32_bf16 v[8:11], v[162:165], v[158:161], v[140:143]
	v_mfma_f32_16x16x32_bf16 v[0:3], v[166:169], v[158:161], v[0:3]
	s_cbranch_vccz .LBB0_728
	s_add_u32 s24, s44, s24
	s_addc_u32 s25, s45, s25
	s_lshl_b64 s[20:21], s[26:27], 1
	s_add_u32 s22, s22, s20
	s_addc_u32 s23, s23, s21
	s_add_u32 s20, s24, s20
	s_addc_u32 s21, s25, s21
	s_add_i32 s2, s2, 0
	s_mov_b32 m0, s2
	v_mov_b32_e32 v139, v129
	global_load_lds_dwordx4 v128, s[22:23]
	s_add_i32 m0, s2, 0x8000
	v_lshl_add_u64 v[144:145], s[22:23], 0, v[138:139]
	s_add_i32 s2, s53, 0
	global_load_lds_dwordx4 v128, s[20:21]
	v_lshl_add_u64 v[146:147], v[144:145], 0, s[4:5]
	s_mov_b32 m0, s2
	v_lshl_add_u64 v[140:141], s[22:23], 0, v[128:129]
	global_load_lds_dwordx4 v[146:147], off
	v_lshl_add_u64 v[146:147], s[20:21], 0, v[138:139]
	v_lshl_add_u64 v[154:155], v[146:147], 0, s[4:5]
	s_add_i32 m0, s2, 0x8000
	s_add_i32 s2, s52, 0
	v_lshl_add_u64 v[142:143], s[20:21], 0, v[128:129]
	global_load_lds_dwordx4 v[154:155], off
	v_lshl_add_u64 v[140:141], v[140:141], 0, s[6:7]
	s_mov_b32 m0, s2
	s_nop 0
	global_load_lds_dwordx4 v[140:141], off
	v_lshl_add_u64 v[140:141], v[142:143], 0, s[6:7]
	s_add_i32 m0, s2, 0x8000
	s_add_i32 s2, s19, 0
	global_load_lds_dwordx4 v[140:141], off
	v_lshl_add_u64 v[140:141], v[144:145], 0, s[8:9]
	s_mov_b32 m0, s2
	s_nop 0
	global_load_lds_dwordx4 v[140:141], off
	v_lshl_add_u64 v[140:141], v[146:147], 0, s[8:9]
	s_add_i32 m0, s2, 0x8000
	s_nop 0
	global_load_lds_dwordx4 v[140:141], off
	s_branch .LBB0_728

.LBB0_791:
	s_lshr_b32 s46, s45, 1
	s_and_b32 s46, s46, 0x1ffff80
	v_or_b32_e32 v0, s46, v148
	s_and_b32 s45, s45, 0xc0
	v_lshlrev_b32_e32 v139, 7, v0
	v_or_b32_e32 v0, s45, v148
	s_mov_b32 s45, s11
	s_lshl_b64 s[44:45], s[44:45], 16
	s_add_u32 s40, s44, s40
	s_addc_u32 s41, s45, s41
	s_waitcnt vmcnt(16)
	v_lshlrev_b32_e32 v153, 7, v0
	v_lshl_add_u64 v[0:1], s[38:39], 0, v[130:131]
	s_add_u32 s42, s44, s42
	v_lshl_add_u64 v[140:141], v[0:1], 0, s[40:41]
	s_addc_u32 s43, s45, s43
	v_lshl_add_u64 v[0:1], s[38:39], 0, v[134:135]
	v_mov_b32_e32 v88, 0
	v_lshl_add_u64 v[142:143], v[132:133], 0, s[42:43]
	v_lshl_add_u64 v[144:145], v[0:1], 0, s[40:41]
	v_lshl_add_u64 v[146:147], v[136:137], 0, s[42:43]
	s_mov_b64 s[38:39], 0
	s_mov_b32 s40, 0
	v_mov_b32_e32 v89, v88
	v_mov_b32_e32 v90, v88
	v_mov_b32_e32 v91, v88
	v_mov_b32_e32 v104, v88
	v_mov_b32_e32 v105, v88
	v_mov_b32_e32 v106, v88
	v_mov_b32_e32 v107, v88
	v_mov_b32_e32 v0, v88
	v_mov_b32_e32 v1, v88
	v_mov_b32_e32 v2, v88
	v_mov_b32_e32 v3, v88
	v_mov_b32_e32 v4, v88
	v_mov_b32_e32 v5, v88
	v_mov_b32_e32 v6, v88
	v_mov_b32_e32 v7, v88
	v_mov_b32_e32 v8, v88
	v_mov_b32_e32 v9, v88
	v_mov_b32_e32 v10, v88
	v_mov_b32_e32 v11, v88
	v_mov_b32_e32 v12, v88
	v_mov_b32_e32 v13, v88
	v_mov_b32_e32 v14, v88
	v_mov_b32_e32 v15, v88
	v_mov_b32_e32 v16, v88
	v_mov_b32_e32 v17, v88
	v_mov_b32_e32 v18, v88
	v_mov_b32_e32 v19, v88
	v_mov_b32_e32 v20, v88
	v_mov_b32_e32 v21, v88
	v_mov_b32_e32 v22, v88
	v_mov_b32_e32 v23, v88
	v_mov_b32_e32 v24, v88
	v_mov_b32_e32 v25, v88
	v_mov_b32_e32 v26, v88
	v_mov_b32_e32 v27, v88
	v_mov_b32_e32 v28, v88
	v_mov_b32_e32 v29, v88
	v_mov_b32_e32 v30, v88
	v_mov_b32_e32 v31, v88
	v_mov_b32_e32 v32, v88
	v_mov_b32_e32 v33, v88
	v_mov_b32_e32 v34, v88
	v_mov_b32_e32 v35, v88
	v_mov_b32_e32 v36, v88
	v_mov_b32_e32 v37, v88
	v_mov_b32_e32 v38, v88
	v_mov_b32_e32 v39, v88
	v_mov_b32_e32 v40, v88
	v_mov_b32_e32 v41, v88
	v_mov_b32_e32 v42, v88
	v_mov_b32_e32 v43, v88
	v_mov_b32_e32 v44, v88
	v_mov_b32_e32 v45, v88
	v_mov_b32_e32 v46, v88
	v_mov_b32_e32 v47, v88
	v_mov_b32_e32 v48, v88
	v_mov_b32_e32 v49, v88
	v_mov_b32_e32 v50, v88
	v_mov_b32_e32 v51, v88
	v_mov_b32_e32 v52, v88
	v_mov_b32_e32 v53, v88
	v_mov_b32_e32 v54, v88
	v_mov_b32_e32 v55, v88
	v_mov_b32_e32 v56, v88
	v_mov_b32_e32 v57, v88
	v_mov_b32_e32 v58, v88
	v_mov_b32_e32 v59, v88
	v_mov_b32_e32 v60, v88
	v_mov_b32_e32 v61, v88
	v_mov_b32_e32 v62, v88
	v_mov_b32_e32 v63, v88
	v_mov_b32_e32 v64, v88
	v_mov_b32_e32 v65, v88
	v_mov_b32_e32 v66, v88
	v_mov_b32_e32 v67, v88
	v_mov_b32_e32 v68, v88
	v_mov_b32_e32 v69, v88
	v_mov_b32_e32 v70, v88
	v_mov_b32_e32 v71, v88
	v_mov_b32_e32 v72, v88
	v_mov_b32_e32 v73, v88
	v_mov_b32_e32 v74, v88
	v_mov_b32_e32 v75, v88
	v_mov_b32_e32 v76, v88
	v_mov_b32_e32 v77, v88
	v_mov_b32_e32 v78, v88
	v_mov_b32_e32 v79, v88
	v_mov_b32_e32 v80, v88
	v_mov_b32_e32 v81, v88
	v_mov_b32_e32 v82, v88
	v_mov_b32_e32 v83, v88
	v_mov_b32_e32 v84, v88
	v_mov_b32_e32 v85, v88
	v_mov_b32_e32 v86, v88
	v_mov_b32_e32 v87, v88
	v_mov_b32_e32 v92, v88
	v_mov_b32_e32 v93, v88
	v_mov_b32_e32 v94, v88
	v_mov_b32_e32 v95, v88
	v_mov_b32_e32 v96, v88
	v_mov_b32_e32 v97, v88
	v_mov_b32_e32 v98, v88
	v_mov_b32_e32 v99, v88
	v_mov_b32_e32 v100, v88
	v_mov_b32_e32 v101, v88
	v_mov_b32_e32 v102, v88
	v_mov_b32_e32 v103, v88
	v_mov_b32_e32 v108, v88
	v_mov_b32_e32 v109, v88
	v_mov_b32_e32 v110, v88
	v_mov_b32_e32 v111, v88
	v_mov_b32_e32 v112, v88
	v_mov_b32_e32 v113, v88
	v_mov_b32_e32 v114, v88
	v_mov_b32_e32 v115, v88
	v_mov_b32_e32 v116, v88
	v_mov_b32_e32 v117, v88
	v_mov_b32_e32 v118, v88
	v_mov_b32_e32 v119, v88
	v_mov_b32_e32 v120, v88
	v_mov_b32_e32 v121, v88
	v_mov_b32_e32 v122, v88
	v_mov_b32_e32 v123, v88
	v_mov_b32_e32 v124, v88
	v_mov_b32_e32 v125, v88
	v_mov_b32_e32 v126, v88
	v_mov_b32_e32 v127, v88
	s_waitcnt vmcnt(16) lgkmcnt(0)
	s_barrier
	v_readfirstlane_b32 s98, v178
	s_nop 3
	s_lshr_b32 s98, s98, 6
	s_cmp_ge_u32 s98, 4
	s_cbranch_scc0 .Lprio_done_4
	s_setprio 1
.Lprio_done_4:
	v_bfe_u32 v250, v178, 3, 3
	v_and_b32_e32 v251, 7, v178
	v_lshrrev_b32_e32 v252, 1, v250
	v_xor_b32_e32 v251, v251, v252
	v_lshlrev_b32_e32 v251, 4, v251
	v_lshl_or_b32 v250, v250, 11, v251
	v_xor_b32_e32 v251, 64, v250
	v_add_u32_e32 v251, 0x4000, v251
	v_add_u32_e32 v252, 0x8000, v250
	v_add_u32_e32 v253, 0x8000, v251
	v_lshl_add_u64 v[242:243], v[140:141], 0, s[38:39]
	s_mov_b64 s[40:41], 0x80
	v_lshl_add_u64 v[242:243], v[242:243], 0, s[40:41]
	v_lshl_add_u64 v[244:245], v[142:143], 0, s[38:39]
	s_mov_b64 s[44:45], 0x12000080
	v_lshl_add_u64 v[244:245], v[244:245], 0, s[44:45]
	v_add_u32_e32 v254, v139, v149
	v_add_u32_e32 v255, v153, v149
	v_readfirstlane_b32 s98, v242
	v_readfirstlane_b32 s99, v243
	v_readfirstlane_b32 s100, v244
	v_readfirstlane_b32 s101, v245
	ds_read_b128 v[162:165], v254
	ds_read_b128 v[166:169], v254 offset:2048
	ds_read_b128 v[154:157], v255 offset:32768
	ds_read_b128 v[158:161], v255 offset:34816
	ds_read_b128 v[170:173], v255 offset:36864
	ds_read_b128 v[174:177], v255 offset:38912
	s_nop 4
	s_lshl_b32 m0, s38, 9
	s_and_b32 m0, m0, 0x10000
	s_xor_b32 m0, m0, 0x10000
	s_add_i32 m0, m0, s10
	s_nop 0
	global_load_lds_dwordx4 v250, s[98:99]
	s_add_i32 m0, m0, 0x8000
	s_nop 0
	global_load_lds_dwordx4 v250, s[100:101]
	s_add_i32 m0, m0, 0xffff8400
	s_nop 0
	global_load_lds_dwordx4 v251, s[98:99]
	s_add_i32 m0, m0, 0x8000
	s_nop 0
	global_load_lds_dwordx4 v251, s[100:101]

.Lgx_792:
	s_setprio 0
	v_mfma_f32_16x16x32_bf16 v[20:23], v[154:157], v[242:245], v[20:23]
	v_mfma_f32_16x16x32_bf16 v[4:7], v[154:157], v[246:249], v[4:7]
	v_mfma_f32_16x16x32_bf16 v[16:19], v[158:161], v[242:245], v[16:19]
	v_mfma_f32_16x16x32_bf16 v[0:3], v[158:161], v[246:249], v[0:3]
	v_mfma_f32_16x16x32_bf16 v[12:15], v[170:173], v[242:245], v[12:15]
	v_mfma_f32_16x16x32_bf16 v[104:107], v[170:173], v[246:249], v[104:107]
	v_mfma_f32_16x16x32_bf16 v[8:11], v[174:177], v[242:245], v[8:11]
	v_mfma_f32_16x16x32_bf16 v[88:91], v[174:177], v[246:249], v[88:91]
	v_add_u32_e32 v153, s41, v153
	v_add_u32_e32 v166, v153, v149
	v_add_u32_e32 v139, s41, v139
	ds_read_b128 v[140:143], v166 offset:32768
	v_add_u32_e32 v170, v139, v149
	ds_read_b128 v[144:147], v166 offset:34816
	ds_read_b128 v[154:157], v170
	ds_read_b128 v[158:161], v170 offset:2048
	ds_read_b128 v[162:165], v166 offset:36864
	ds_read_b128 v[166:169], v166 offset:38912
	s_waitcnt lgkmcnt(3)
	v_mfma_f32_16x16x32_bf16 v[120:123], v[144:147], v[154:157], v[120:123]
	v_add_u32_e32 v139, v139, v150
	s_and_b64 vcc, exec, s[2:3]
	v_mfma_f32_16x16x32_bf16 v[124:127], v[140:143], v[154:157], v[124:127]
	s_waitcnt lgkmcnt(1)
	v_mfma_f32_16x16x32_bf16 v[116:119], v[162:165], v[154:157], v[116:119]
	s_waitcnt lgkmcnt(0)
	v_mfma_f32_16x16x32_bf16 v[112:115], v[166:169], v[154:157], v[112:115]
	v_mfma_f32_16x16x32_bf16 v[108:111], v[140:143], v[158:161], v[108:111]
	v_mfma_f32_16x16x32_bf16 v[100:103], v[144:147], v[158:161], v[100:103]
	v_mfma_f32_16x16x32_bf16 v[96:99], v[162:165], v[158:161], v[96:99]
	v_mfma_f32_16x16x32_bf16 v[92:95], v[166:169], v[158:161], v[92:95]
	ds_read_b128 v[154:157], v170 offset:4096
	ds_read_b128 v[158:161], v170 offset:6144
	s_waitcnt lgkmcnt(1)
	v_mfma_f32_16x16x32_bf16 v[84:87], v[140:143], v[154:157], v[84:87]
	v_mfma_f32_16x16x32_bf16 v[80:83], v[144:147], v[154:157], v[80:83]
	v_mfma_f32_16x16x32_bf16 v[76:79], v[162:165], v[154:157], v[76:79]
	v_mfma_f32_16x16x32_bf16 v[72:75], v[166:169], v[154:157], v[72:75]
	s_waitcnt lgkmcnt(0)
	v_mfma_f32_16x16x32_bf16 v[68:71], v[140:143], v[158:161], v[68:71]
	v_mfma_f32_16x16x32_bf16 v[64:67], v[144:147], v[158:161], v[64:67]
	v_mfma_f32_16x16x32_bf16 v[60:63], v[162:165], v[158:161], v[60:63]
	v_mfma_f32_16x16x32_bf16 v[56:59], v[166:169], v[158:161], v[56:59]
	ds_read_b128 v[154:157], v170 offset:8192
	ds_read_b128 v[158:161], v170 offset:10240
	s_waitcnt lgkmcnt(1)
	v_mfma_f32_16x16x32_bf16 v[52:55], v[140:143], v[154:157], v[52:55]
	v_mfma_f32_16x16x32_bf16 v[48:51], v[144:147], v[154:157], v[48:51]
	v_mfma_f32_16x16x32_bf16 v[44:47], v[162:165], v[154:157], v[44:47]
	v_mfma_f32_16x16x32_bf16 v[40:43], v[166:169], v[154:157], v[40:43]
	s_waitcnt lgkmcnt(0)
	v_mfma_f32_16x16x32_bf16 v[36:39], v[140:143], v[158:161], v[36:39]
	v_mfma_f32_16x16x32_bf16 v[32:35], v[144:147], v[158:161], v[32:35]
	v_mfma_f32_16x16x32_bf16 v[28:31], v[162:165], v[158:161], v[28:31]
	v_mfma_f32_16x16x32_bf16 v[24:27], v[166:169], v[158:161], v[24:27]
	ds_read_b128 v[154:157], v170 offset:12288
	ds_read_b128 v[158:161], v170 offset:14336
	s_waitcnt lgkmcnt(1)
	v_mfma_f32_16x16x32_bf16 v[20:23], v[140:143], v[154:157], v[20:23]
	s_waitcnt lgkmcnt(0)
	v_mfma_f32_16x16x32_bf16 v[4:7], v[140:143], v[158:161], v[4:7]
	v_mfma_f32_16x16x32_bf16 v[140:143], v[162:165], v[158:161], v[104:107]
	s_nop 2
	v_add_u32_e32 v104, v153, v150
	v_mfma_f32_16x16x32_bf16 v[16:19], v[144:147], v[154:157], v[16:19]
	v_mfma_f32_16x16x32_bf16 v[12:15], v[162:165], v[154:157], v[12:15]
	v_mfma_f32_16x16x32_bf16 v[8:11], v[166:169], v[154:157], v[8:11]
	v_mfma_f32_16x16x32_bf16 v[0:3], v[144:147], v[158:161], v[0:3]
	ds_read_b128 v[144:147], v104 offset:32768
	v_mfma_f32_16x16x32_bf16 v[154:157], v[166:169], v[158:161], v[88:91]
	ds_read_b128 v[158:161], v104 offset:34816
	s_nop 1
	ds_read_b128 v[88:91], v139
	ds_read_b128 v[162:165], v139 offset:2048
	ds_read_b128 v[166:169], v104 offset:36864
	ds_read_b128 v[170:173], v104 offset:38912
	s_waitcnt lgkmcnt(2)
	v_mfma_f32_16x16x32_bf16 v[108:111], v[144:147], v[162:165], v[108:111]
	v_mfma_f32_16x16x32_bf16 v[104:107], v[158:161], v[162:165], v[100:103]
	s_waitcnt lgkmcnt(1)
	v_mfma_f32_16x16x32_bf16 v[100:103], v[166:169], v[162:165], v[96:99]
	s_waitcnt lgkmcnt(0)
	v_mfma_f32_16x16x32_bf16 v[96:99], v[170:173], v[162:165], v[92:95]
	ds_read_b128 v[162:165], v139 offset:4096
	ds_read_b128 v[174:177], v139 offset:6144
	v_mfma_f32_16x16x32_bf16 v[124:127], v[144:147], v[88:91], v[124:127]
	v_mfma_f32_16x16x32_bf16 v[120:123], v[158:161], v[88:91], v[120:123]
	v_mfma_f32_16x16x32_bf16 v[116:119], v[166:169], v[88:91], v[116:119]
	v_mfma_f32_16x16x32_bf16 v[112:115], v[170:173], v[88:91], v[112:115]
	s_waitcnt lgkmcnt(1)
	v_mfma_f32_16x16x32_bf16 v[92:95], v[144:147], v[162:165], v[84:87]
	v_mfma_f32_16x16x32_bf16 v[88:91], v[158:161], v[162:165], v[80:83]
	v_mfma_f32_16x16x32_bf16 v[84:87], v[166:169], v[162:165], v[76:79]
	v_mfma_f32_16x16x32_bf16 v[80:83], v[170:173], v[162:165], v[72:75]
	s_waitcnt lgkmcnt(0)
	v_mfma_f32_16x16x32_bf16 v[76:79], v[144:147], v[174:177], v[68:71]
	v_mfma_f32_16x16x32_bf16 v[72:75], v[158:161], v[174:177], v[64:67]
	v_mfma_f32_16x16x32_bf16 v[68:71], v[166:169], v[174:177], v[60:63]
	v_mfma_f32_16x16x32_bf16 v[64:67], v[170:173], v[174:177], v[56:59]
	ds_read_b128 v[162:165], v139 offset:8192
	ds_read_b128 v[174:177], v139 offset:10240
	s_waitcnt lgkmcnt(1)
	v_mfma_f32_16x16x32_bf16 v[60:63], v[144:147], v[162:165], v[52:55]
	v_mfma_f32_16x16x32_bf16 v[56:59], v[158:161], v[162:165], v[48:51]
	v_mfma_f32_16x16x32_bf16 v[52:55], v[166:169], v[162:165], v[44:47]
	v_mfma_f32_16x16x32_bf16 v[48:51], v[170:173], v[162:165], v[40:43]
	s_waitcnt lgkmcnt(0)
	v_mfma_f32_16x16x32_bf16 v[44:47], v[144:147], v[174:177], v[36:39]
	v_mfma_f32_16x16x32_bf16 v[40:43], v[158:161], v[174:177], v[32:35]
	v_mfma_f32_16x16x32_bf16 v[36:39], v[166:169], v[174:177], v[28:31]
	v_mfma_f32_16x16x32_bf16 v[32:35], v[170:173], v[174:177], v[24:27]
	ds_read_b128 v[162:165], v139 offset:12288
	ds_read_b128 v[174:177], v139 offset:14336
	s_waitcnt vmcnt(0)
	s_waitcnt lgkmcnt(0)
	v_mfma_f32_16x16x32_bf16 v[28:31], v[144:147], v[162:165], v[20:23]
	s_barrier
	v_mfma_f32_16x16x32_bf16 v[24:27], v[158:161], v[162:165], v[16:19]
	v_mfma_f32_16x16x32_bf16 v[20:23], v[166:169], v[162:165], v[12:15]
	v_mfma_f32_16x16x32_bf16 v[16:19], v[170:173], v[162:165], v[8:11]
	v_mfma_f32_16x16x32_bf16 v[12:15], v[144:147], v[174:177], v[4:7]
	v_mfma_f32_16x16x32_bf16 v[8:11], v[158:161], v[174:177], v[0:3]
	v_mfma_f32_16x16x32_bf16 v[4:7], v[166:169], v[174:177], v[140:143]
	v_mfma_f32_16x16x32_bf16 v[0:3], v[170:173], v[174:177], v[154:157]
	s_cbranch_vccz .LBB0_795
	s_add_u32 s6, s56, s6
	s_addc_u32 s7, s57, s7
	s_lshl_b64 s[2:3], s[8:9], 1
	s_add_u32 s4, s4, s2
	s_addc_u32 s5, s5, s3
	s_add_u32 s2, s6, s2
	s_addc_u32 s3, s7, s3
	s_add_i32 s6, s10, 0
	s_mov_b32 m0, s6
	v_mov_b32_e32 v139, v129
	v_lshl_add_u64 v[140:141], s[4:5], 0, v[128:129]
	global_load_lds_dwordx4 v128, s[4:5]
	s_add_i32 m0, s6, 0x8000
	v_lshl_add_u64 v[144:145], s[4:5], 0, v[138:139]
	s_add_i32 s4, s51, 0
	global_load_lds_dwordx4 v128, s[2:3]
	v_lshl_add_u64 v[146:147], v[144:145], 0, s[12:13]
	s_mov_b32 m0, s4
	v_lshl_add_u64 v[142:143], s[2:3], 0, v[128:129]
	global_load_lds_dwordx4 v[146:147], off
	v_lshl_add_u64 v[146:147], s[2:3], 0, v[138:139]
	v_lshl_add_u64 v[154:155], v[146:147], 0, s[12:13]
	s_add_i32 m0, s4, 0x8000
	s_add_i32 s2, s50, 0
	global_load_lds_dwordx4 v[154:155], off
	v_lshl_add_u64 v[140:141], v[140:141], 0, s[14:15]
	s_mov_b32 m0, s2
	s_nop 0
	global_load_lds_dwordx4 v[140:141], off
	v_lshl_add_u64 v[140:141], v[142:143], 0, s[14:15]
	s_add_i32 m0, s2, 0x8000
	s_add_i32 s2, s37, 0
	global_load_lds_dwordx4 v[140:141], off
	v_lshl_add_u64 v[140:141], v[144:145], 0, s[16:17]
	s_mov_b32 m0, s2
	s_nop 0
	global_load_lds_dwordx4 v[140:141], off
	v_lshl_add_u64 v[140:141], v[146:147], 0, s[16:17]
	s_add_i32 m0, s2, 0x8000
	s_nop 0
	global_load_lds_dwordx4 v[140:141], off

.LBB0_1139:
	s_lshr_b32 s48, s47, 1
	s_and_b32 s48, s48, 0x1ffff80
	v_or_b32_e32 v0, s48, v148
	s_and_b32 s47, s47, 0xc0
	v_lshlrev_b32_e32 v139, 7, v0
	v_or_b32_e32 v0, s47, v148
	s_mov_b32 s47, s3
	s_lshl_b64 s[46:47], s[46:47], 16
	s_add_u32 s42, s46, s42
	s_addc_u32 s43, s47, s43
	s_waitcnt vmcnt(16)
	v_lshlrev_b32_e32 v153, 7, v0
	v_lshl_add_u64 v[0:1], s[40:41], 0, v[130:131]
	s_add_u32 s44, s46, s44
	v_lshl_add_u64 v[140:141], v[0:1], 0, s[42:43]
	s_addc_u32 s45, s47, s45
	v_lshl_add_u64 v[0:1], s[40:41], 0, v[134:135]
	v_mov_b32_e32 v88, 0
	v_lshl_add_u64 v[142:143], v[132:133], 0, s[44:45]
	v_lshl_add_u64 v[144:145], v[0:1], 0, s[42:43]
	v_lshl_add_u64 v[146:147], v[136:137], 0, s[44:45]
	s_mov_b64 s[40:41], 0
	s_mov_b32 s42, 0
	v_mov_b32_e32 v89, v88
	v_mov_b32_e32 v90, v88
	v_mov_b32_e32 v91, v88
	v_mov_b32_e32 v104, v88
	v_mov_b32_e32 v105, v88
	v_mov_b32_e32 v106, v88
	v_mov_b32_e32 v107, v88
	v_mov_b32_e32 v0, v88
	v_mov_b32_e32 v1, v88
	v_mov_b32_e32 v2, v88
	v_mov_b32_e32 v3, v88
	v_mov_b32_e32 v4, v88
	v_mov_b32_e32 v5, v88
	v_mov_b32_e32 v6, v88
	v_mov_b32_e32 v7, v88
	v_mov_b32_e32 v8, v88
	v_mov_b32_e32 v9, v88
	v_mov_b32_e32 v10, v88
	v_mov_b32_e32 v11, v88
	v_mov_b32_e32 v12, v88
	v_mov_b32_e32 v13, v88
	v_mov_b32_e32 v14, v88
	v_mov_b32_e32 v15, v88
	v_mov_b32_e32 v16, v88
	v_mov_b32_e32 v17, v88
	v_mov_b32_e32 v18, v88
	v_mov_b32_e32 v19, v88
	v_mov_b32_e32 v20, v88
	v_mov_b32_e32 v21, v88
	v_mov_b32_e32 v22, v88
	v_mov_b32_e32 v23, v88
	v_mov_b32_e32 v24, v88
	v_mov_b32_e32 v25, v88
	v_mov_b32_e32 v26, v88
	v_mov_b32_e32 v27, v88
	v_mov_b32_e32 v28, v88
	v_mov_b32_e32 v29, v88
	v_mov_b32_e32 v30, v88
	v_mov_b32_e32 v31, v88
	v_mov_b32_e32 v32, v88
	v_mov_b32_e32 v33, v88
	v_mov_b32_e32 v34, v88
	v_mov_b32_e32 v35, v88
	v_mov_b32_e32 v36, v88
	v_mov_b32_e32 v37, v88
	v_mov_b32_e32 v38, v88
	v_mov_b32_e32 v39, v88
	v_mov_b32_e32 v40, v88
	v_mov_b32_e32 v41, v88
	v_mov_b32_e32 v42, v88
	v_mov_b32_e32 v43, v88
	v_mov_b32_e32 v44, v88
	v_mov_b32_e32 v45, v88
	v_mov_b32_e32 v46, v88
	v_mov_b32_e32 v47, v88
	v_mov_b32_e32 v48, v88
	v_mov_b32_e32 v49, v88
	v_mov_b32_e32 v50, v88
	v_mov_b32_e32 v51, v88
	v_mov_b32_e32 v52, v88
	v_mov_b32_e32 v53, v88
	v_mov_b32_e32 v54, v88
	v_mov_b32_e32 v55, v88
	v_mov_b32_e32 v56, v88
	v_mov_b32_e32 v57, v88
	v_mov_b32_e32 v58, v88
	v_mov_b32_e32 v59, v88
	v_mov_b32_e32 v60, v88
	v_mov_b32_e32 v61, v88
	v_mov_b32_e32 v62, v88
	v_mov_b32_e32 v63, v88
	v_mov_b32_e32 v64, v88
	v_mov_b32_e32 v65, v88
	v_mov_b32_e32 v66, v88
	v_mov_b32_e32 v67, v88
	v_mov_b32_e32 v68, v88
	v_mov_b32_e32 v69, v88
	v_mov_b32_e32 v70, v88
	v_mov_b32_e32 v71, v88
	v_mov_b32_e32 v72, v88
	v_mov_b32_e32 v73, v88
	v_mov_b32_e32 v74, v88
	v_mov_b32_e32 v75, v88
	v_mov_b32_e32 v76, v88
	v_mov_b32_e32 v77, v88
	v_mov_b32_e32 v78, v88
	v_mov_b32_e32 v79, v88
	v_mov_b32_e32 v80, v88
	v_mov_b32_e32 v81, v88
	v_mov_b32_e32 v82, v88
	v_mov_b32_e32 v83, v88
	v_mov_b32_e32 v84, v88
	v_mov_b32_e32 v85, v88
	v_mov_b32_e32 v86, v88
	v_mov_b32_e32 v87, v88
	v_mov_b32_e32 v92, v88
	v_mov_b32_e32 v93, v88
	v_mov_b32_e32 v94, v88
	v_mov_b32_e32 v95, v88
	v_mov_b32_e32 v96, v88
	v_mov_b32_e32 v97, v88
	v_mov_b32_e32 v98, v88
	v_mov_b32_e32 v99, v88
	v_mov_b32_e32 v100, v88
	v_mov_b32_e32 v101, v88
	v_mov_b32_e32 v102, v88
	v_mov_b32_e32 v103, v88
	v_mov_b32_e32 v108, v88
	v_mov_b32_e32 v109, v88
	v_mov_b32_e32 v110, v88
	v_mov_b32_e32 v111, v88
	v_mov_b32_e32 v112, v88
	v_mov_b32_e32 v113, v88
	v_mov_b32_e32 v114, v88
	v_mov_b32_e32 v115, v88
	v_mov_b32_e32 v116, v88
	v_mov_b32_e32 v117, v88
	v_mov_b32_e32 v118, v88
	v_mov_b32_e32 v119, v88
	v_mov_b32_e32 v120, v88
	v_mov_b32_e32 v121, v88
	v_mov_b32_e32 v122, v88
	v_mov_b32_e32 v123, v88
	v_mov_b32_e32 v124, v88
	v_mov_b32_e32 v125, v88
	v_mov_b32_e32 v126, v88
	v_mov_b32_e32 v127, v88
	s_waitcnt vmcnt(16) lgkmcnt(0)
	s_barrier
	v_readfirstlane_b32 s98, v178
	s_nop 3
	s_lshr_b32 s98, s98, 6
	s_cmp_ge_u32 s98, 4
	s_cbranch_scc0 .Lprio_done_5
	s_setprio 1
.Lprio_done_5:
	v_bfe_u32 v250, v178, 3, 3
	v_and_b32_e32 v251, 7, v178
	v_lshrrev_b32_e32 v252, 1, v250
	v_xor_b32_e32 v251, v251, v252
	v_lshlrev_b32_e32 v251, 4, v251
	v_lshl_or_b32 v250, v250, 11, v251
	v_xor_b32_e32 v251, 64, v250
	v_add_u32_e32 v251, 0x4000, v251
	v_add_u32_e32 v252, 0x8000, v250
	v_add_u32_e32 v253, 0x8000, v251
	v_lshl_add_u64 v[242:243], v[140:141], 0, s[40:41]
	v_lshl_add_u64 v[242:243], v[242:243], 0, s[10:11]
	v_lshl_add_u64 v[244:245], v[142:143], 0, s[40:41]
	v_lshl_add_u64 v[244:245], v[244:245], 0, s[12:13]
	v_add_u32_e32 v254, v139, v149
	v_add_u32_e32 v255, v153, v149
	v_readfirstlane_b32 s98, v242
	v_readfirstlane_b32 s99, v243
	v_readfirstlane_b32 s100, v244
	v_readfirstlane_b32 s101, v245
	ds_read_b128 v[162:165], v254
	ds_read_b128 v[166:169], v254 offset:2048
	ds_read_b128 v[154:157], v255 offset:32768
	ds_read_b128 v[158:161], v255 offset:34816
	ds_read_b128 v[170:173], v255 offset:36864
	ds_read_b128 v[174:177], v255 offset:38912
	s_nop 4
	s_lshl_b32 m0, s40, 9
	s_and_b32 m0, m0, 0x10000
	s_xor_b32 m0, m0, 0x10000
	s_add_i32 m0, m0, s2
	s_nop 0
	global_load_lds_dwordx4 v250, s[98:99]
	s_add_i32 m0, m0, 0x8000
	s_nop 0
	global_load_lds_dwordx4 v250, s[100:101]
	s_add_i32 m0, m0, 0xffff8400
	s_nop 0
	global_load_lds_dwordx4 v251, s[98:99]
	s_add_i32 m0, m0, 0x8000
	s_nop 0
	global_load_lds_dwordx4 v251, s[100:101]

.Lgx_1140:
	s_setprio 0
	v_mfma_f32_16x16x32_bf16 v[20:23], v[154:157], v[242:245], v[20:23]
	v_mfma_f32_16x16x32_bf16 v[4:7], v[154:157], v[246:249], v[4:7]
	v_mfma_f32_16x16x32_bf16 v[16:19], v[158:161], v[242:245], v[16:19]
	v_mfma_f32_16x16x32_bf16 v[0:3], v[158:161], v[246:249], v[0:3]
	v_mfma_f32_16x16x32_bf16 v[12:15], v[170:173], v[242:245], v[12:15]
	v_mfma_f32_16x16x32_bf16 v[104:107], v[170:173], v[246:249], v[104:107]
	v_mfma_f32_16x16x32_bf16 v[8:11], v[174:177], v[242:245], v[8:11]
	v_mfma_f32_16x16x32_bf16 v[88:91], v[174:177], v[246:249], v[88:91]
	v_add_u32_e32 v153, s43, v153
	v_add_u32_e32 v166, v153, v149
	v_add_u32_e32 v139, s43, v139
	ds_read_b128 v[140:143], v166 offset:32768
	v_add_u32_e32 v170, v139, v149
	ds_read_b128 v[144:147], v166 offset:34816
	ds_read_b128 v[154:157], v170
	ds_read_b128 v[158:161], v170 offset:2048
	ds_read_b128 v[162:165], v166 offset:36864
	ds_read_b128 v[166:169], v166 offset:38912
	s_waitcnt lgkmcnt(3)
	v_mfma_f32_16x16x32_bf16 v[120:123], v[144:147], v[154:157], v[120:123]
	v_add_u32_e32 v139, v139, v150
	s_and_b64 vcc, exec, s[30:31]
	v_mfma_f32_16x16x32_bf16 v[124:127], v[140:143], v[154:157], v[124:127]
	s_waitcnt lgkmcnt(1)
	v_mfma_f32_16x16x32_bf16 v[116:119], v[162:165], v[154:157], v[116:119]
	s_waitcnt lgkmcnt(0)
	v_mfma_f32_16x16x32_bf16 v[112:115], v[166:169], v[154:157], v[112:115]
	v_mfma_f32_16x16x32_bf16 v[108:111], v[140:143], v[158:161], v[108:111]
	v_mfma_f32_16x16x32_bf16 v[100:103], v[144:147], v[158:161], v[100:103]
	v_mfma_f32_16x16x32_bf16 v[96:99], v[162:165], v[158:161], v[96:99]
	v_mfma_f32_16x16x32_bf16 v[92:95], v[166:169], v[158:161], v[92:95]
	ds_read_b128 v[154:157], v170 offset:4096
	ds_read_b128 v[158:161], v170 offset:6144
	s_waitcnt lgkmcnt(1)
	v_mfma_f32_16x16x32_bf16 v[84:87], v[140:143], v[154:157], v[84:87]
	v_mfma_f32_16x16x32_bf16 v[80:83], v[144:147], v[154:157], v[80:83]
	v_mfma_f32_16x16x32_bf16 v[76:79], v[162:165], v[154:157], v[76:79]
	v_mfma_f32_16x16x32_bf16 v[72:75], v[166:169], v[154:157], v[72:75]
	s_waitcnt lgkmcnt(0)
	v_mfma_f32_16x16x32_bf16 v[68:71], v[140:143], v[158:161], v[68:71]
	v_mfma_f32_16x16x32_bf16 v[64:67], v[144:147], v[158:161], v[64:67]
	v_mfma_f32_16x16x32_bf16 v[60:63], v[162:165], v[158:161], v[60:63]
	v_mfma_f32_16x16x32_bf16 v[56:59], v[166:169], v[158:161], v[56:59]
	ds_read_b128 v[154:157], v170 offset:8192
	ds_read_b128 v[158:161], v170 offset:10240
	s_waitcnt lgkmcnt(1)
	v_mfma_f32_16x16x32_bf16 v[52:55], v[140:143], v[154:157], v[52:55]
	v_mfma_f32_16x16x32_bf16 v[48:51], v[144:147], v[154:157], v[48:51]
	v_mfma_f32_16x16x32_bf16 v[44:47], v[162:165], v[154:157], v[44:47]
	v_mfma_f32_16x16x32_bf16 v[40:43], v[166:169], v[154:157], v[40:43]
	s_waitcnt lgkmcnt(0)
	v_mfma_f32_16x16x32_bf16 v[36:39], v[140:143], v[158:161], v[36:39]
	v_mfma_f32_16x16x32_bf16 v[32:35], v[144:147], v[158:161], v[32:35]
	v_mfma_f32_16x16x32_bf16 v[28:31], v[162:165], v[158:161], v[28:31]
	v_mfma_f32_16x16x32_bf16 v[24:27], v[166:169], v[158:161], v[24:27]
	ds_read_b128 v[154:157], v170 offset:12288
	ds_read_b128 v[158:161], v170 offset:14336
	s_waitcnt lgkmcnt(1)
	v_mfma_f32_16x16x32_bf16 v[20:23], v[140:143], v[154:157], v[20:23]
	s_waitcnt lgkmcnt(0)
	v_mfma_f32_16x16x32_bf16 v[4:7], v[140:143], v[158:161], v[4:7]
	v_mfma_f32_16x16x32_bf16 v[140:143], v[162:165], v[158:161], v[104:107]
	s_nop 2
	v_add_u32_e32 v104, v153, v150
	v_mfma_f32_16x16x32_bf16 v[16:19], v[144:147], v[154:157], v[16:19]
	v_mfma_f32_16x16x32_bf16 v[12:15], v[162:165], v[154:157], v[12:15]
	v_mfma_f32_16x16x32_bf16 v[8:11], v[166:169], v[154:157], v[8:11]
	v_mfma_f32_16x16x32_bf16 v[0:3], v[144:147], v[158:161], v[0:3]
	ds_read_b128 v[144:147], v104 offset:32768
	v_mfma_f32_16x16x32_bf16 v[154:157], v[166:169], v[158:161], v[88:91]
	ds_read_b128 v[158:161], v104 offset:34816
	s_nop 1
	ds_read_b128 v[88:91], v139
	ds_read_b128 v[162:165], v139 offset:2048
	ds_read_b128 v[166:169], v104 offset:36864
	ds_read_b128 v[170:173], v104 offset:38912
	s_waitcnt lgkmcnt(2)
	v_mfma_f32_16x16x32_bf16 v[108:111], v[144:147], v[162:165], v[108:111]
	v_mfma_f32_16x16x32_bf16 v[104:107], v[158:161], v[162:165], v[100:103]
	s_waitcnt lgkmcnt(1)
	v_mfma_f32_16x16x32_bf16 v[100:103], v[166:169], v[162:165], v[96:99]
	s_waitcnt lgkmcnt(0)
	v_mfma_f32_16x16x32_bf16 v[96:99], v[170:173], v[162:165], v[92:95]
	ds_read_b128 v[162:165], v139 offset:4096
	ds_read_b128 v[174:177], v139 offset:6144
	v_mfma_f32_16x16x32_bf16 v[124:127], v[144:147], v[88:91], v[124:127]
	v_mfma_f32_16x16x32_bf16 v[120:123], v[158:161], v[88:91], v[120:123]
	v_mfma_f32_16x16x32_bf16 v[116:119], v[166:169], v[88:91], v[116:119]
	v_mfma_f32_16x16x32_bf16 v[112:115], v[170:173], v[88:91], v[112:115]
	s_waitcnt lgkmcnt(1)
	v_mfma_f32_16x16x32_bf16 v[92:95], v[144:147], v[162:165], v[84:87]
	v_mfma_f32_16x16x32_bf16 v[88:91], v[158:161], v[162:165], v[80:83]
	v_mfma_f32_16x16x32_bf16 v[84:87], v[166:169], v[162:165], v[76:79]
	v_mfma_f32_16x16x32_bf16 v[80:83], v[170:173], v[162:165], v[72:75]
	s_waitcnt lgkmcnt(0)
	v_mfma_f32_16x16x32_bf16 v[76:79], v[144:147], v[174:177], v[68:71]
	v_mfma_f32_16x16x32_bf16 v[72:75], v[158:161], v[174:177], v[64:67]
	v_mfma_f32_16x16x32_bf16 v[68:71], v[166:169], v[174:177], v[60:63]
	v_mfma_f32_16x16x32_bf16 v[64:67], v[170:173], v[174:177], v[56:59]
	ds_read_b128 v[162:165], v139 offset:8192
	ds_read_b128 v[174:177], v139 offset:10240
	s_waitcnt lgkmcnt(1)
	v_mfma_f32_16x16x32_bf16 v[60:63], v[144:147], v[162:165], v[52:55]
	v_mfma_f32_16x16x32_bf16 v[56:59], v[158:161], v[162:165], v[48:51]
	v_mfma_f32_16x16x32_bf16 v[52:55], v[166:169], v[162:165], v[44:47]
	v_mfma_f32_16x16x32_bf16 v[48:51], v[170:173], v[162:165], v[40:43]
	s_waitcnt lgkmcnt(0)
	v_mfma_f32_16x16x32_bf16 v[44:47], v[144:147], v[174:177], v[36:39]
	v_mfma_f32_16x16x32_bf16 v[40:43], v[158:161], v[174:177], v[32:35]
	v_mfma_f32_16x16x32_bf16 v[36:39], v[166:169], v[174:177], v[28:31]
	v_mfma_f32_16x16x32_bf16 v[32:35], v[170:173], v[174:177], v[24:27]
	ds_read_b128 v[162:165], v139 offset:12288
	ds_read_b128 v[174:177], v139 offset:14336
	s_waitcnt vmcnt(0)
	s_waitcnt lgkmcnt(0)
	v_mfma_f32_16x16x32_bf16 v[28:31], v[144:147], v[162:165], v[20:23]
	s_barrier
	v_mfma_f32_16x16x32_bf16 v[24:27], v[158:161], v[162:165], v[16:19]
	v_mfma_f32_16x16x32_bf16 v[20:23], v[166:169], v[162:165], v[12:15]
	v_mfma_f32_16x16x32_bf16 v[16:19], v[170:173], v[162:165], v[8:11]
	v_mfma_f32_16x16x32_bf16 v[12:15], v[144:147], v[174:177], v[4:7]
	v_mfma_f32_16x16x32_bf16 v[8:11], v[158:161], v[174:177], v[0:3]
	v_mfma_f32_16x16x32_bf16 v[4:7], v[166:169], v[174:177], v[140:143]
	v_mfma_f32_16x16x32_bf16 v[0:3], v[170:173], v[174:177], v[154:157]
	s_cbranch_vccz .LBB0_1128
	s_add_u32 s36, s59, s36
	s_addc_u32 s37, s60, s37
	s_lshl_b64 s[30:31], s[38:39], 1
	s_add_u32 s34, s34, s30
	s_addc_u32 s35, s35, s31
	s_add_u32 s30, s36, s30
	s_addc_u32 s31, s37, s31
	s_add_i32 s2, s2, 0
	s_mov_b32 m0, s2
	v_mov_b32_e32 v139, v129
	global_load_lds_dwordx4 v128, s[34:35]
	s_add_i32 m0, s2, 0x8000
	v_lshl_add_u64 v[144:145], s[34:35], 0, v[138:139]
	s_add_i32 s2, s53, 0
	global_load_lds_dwordx4 v128, s[30:31]
	v_lshl_add_u64 v[146:147], v[144:145], 0, s[4:5]
	s_mov_b32 m0, s2
	v_lshl_add_u64 v[140:141], s[34:35], 0, v[128:129]
	global_load_lds_dwordx4 v[146:147], off
	v_lshl_add_u64 v[146:147], s[30:31], 0, v[138:139]
	v_lshl_add_u64 v[154:155], v[146:147], 0, s[4:5]
	s_add_i32 m0, s2, 0x8000
	s_add_i32 s2, s52, 0
	v_lshl_add_u64 v[142:143], s[30:31], 0, v[128:129]
	global_load_lds_dwordx4 v[154:155], off
	v_lshl_add_u64 v[140:141], v[140:141], 0, s[6:7]
	s_mov_b32 m0, s2
	s_nop 0
	global_load_lds_dwordx4 v[140:141], off
	v_lshl_add_u64 v[140:141], v[142:143], 0, s[6:7]
	s_add_i32 m0, s2, 0x8000
	s_add_i32 s2, s29, 0
	global_load_lds_dwordx4 v[140:141], off
	v_lshl_add_u64 v[140:141], v[144:145], 0, s[8:9]
	s_mov_b32 m0, s2
	s_nop 0
	global_load_lds_dwordx4 v[140:141], off
	v_lshl_add_u64 v[140:141], v[146:147], 0, s[8:9]
	s_add_i32 m0, s2, 0x8000
	s_nop 0
	global_load_lds_dwordx4 v[140:141], off
	s_branch .LBB0_1128

.LBB0_1186:
	s_lshr_b32 s50, s49, 1
	s_and_b32 s50, s50, 0x1ffff80
	v_or_b32_e32 v0, s50, v148
	s_and_b32 s49, s49, 0xc0
	v_lshlrev_b32_e32 v139, 7, v0
	v_or_b32_e32 v0, s49, v148
	s_mov_b32 s49, s3
	s_lshl_b64 s[48:49], s[48:49], 17
	s_add_u32 s44, s48, s44
	s_addc_u32 s45, s49, s45
	s_waitcnt vmcnt(16)
	v_lshlrev_b32_e32 v153, 7, v0
	v_lshl_add_u64 v[0:1], s[42:43], 0, v[130:131]
	s_add_u32 s46, s48, s46
	v_lshl_add_u64 v[140:141], v[0:1], 0, s[44:45]
	s_addc_u32 s47, s49, s47
	v_lshl_add_u64 v[0:1], s[42:43], 0, v[134:135]
	v_mov_b32_e32 v88, 0
	v_lshl_add_u64 v[142:143], v[132:133], 0, s[46:47]
	v_lshl_add_u64 v[144:145], v[0:1], 0, s[44:45]
	v_lshl_add_u64 v[146:147], v[136:137], 0, s[46:47]
	s_mov_b64 s[42:43], 0
	s_mov_b32 s44, 0
	v_mov_b32_e32 v89, v88
	v_mov_b32_e32 v90, v88
	v_mov_b32_e32 v91, v88
	v_mov_b32_e32 v104, v88
	v_mov_b32_e32 v105, v88
	v_mov_b32_e32 v106, v88
	v_mov_b32_e32 v107, v88
	v_mov_b32_e32 v0, v88
	v_mov_b32_e32 v1, v88
	v_mov_b32_e32 v2, v88
	v_mov_b32_e32 v3, v88
	v_mov_b32_e32 v4, v88
	v_mov_b32_e32 v5, v88
	v_mov_b32_e32 v6, v88
	v_mov_b32_e32 v7, v88
	v_mov_b32_e32 v8, v88
	v_mov_b32_e32 v9, v88
	v_mov_b32_e32 v10, v88
	v_mov_b32_e32 v11, v88
	v_mov_b32_e32 v12, v88
	v_mov_b32_e32 v13, v88
	v_mov_b32_e32 v14, v88
	v_mov_b32_e32 v15, v88
	v_mov_b32_e32 v16, v88
	v_mov_b32_e32 v17, v88
	v_mov_b32_e32 v18, v88
	v_mov_b32_e32 v19, v88
	v_mov_b32_e32 v20, v88
	v_mov_b32_e32 v21, v88
	v_mov_b32_e32 v22, v88
	v_mov_b32_e32 v23, v88
	v_mov_b32_e32 v24, v88
	v_mov_b32_e32 v25, v88
	v_mov_b32_e32 v26, v88
	v_mov_b32_e32 v27, v88
	v_mov_b32_e32 v28, v88
	v_mov_b32_e32 v29, v88
	v_mov_b32_e32 v30, v88
	v_mov_b32_e32 v31, v88
	v_mov_b32_e32 v32, v88
	v_mov_b32_e32 v33, v88
	v_mov_b32_e32 v34, v88
	v_mov_b32_e32 v35, v88
	v_mov_b32_e32 v36, v88
	v_mov_b32_e32 v37, v88
	v_mov_b32_e32 v38, v88
	v_mov_b32_e32 v39, v88
	v_mov_b32_e32 v40, v88
	v_mov_b32_e32 v41, v88
	v_mov_b32_e32 v42, v88
	v_mov_b32_e32 v43, v88
	v_mov_b32_e32 v44, v88
	v_mov_b32_e32 v45, v88
	v_mov_b32_e32 v46, v88
	v_mov_b32_e32 v47, v88
	v_mov_b32_e32 v48, v88
	v_mov_b32_e32 v49, v88
	v_mov_b32_e32 v50, v88
	v_mov_b32_e32 v51, v88
	v_mov_b32_e32 v52, v88
	v_mov_b32_e32 v53, v88
	v_mov_b32_e32 v54, v88
	v_mov_b32_e32 v55, v88
	v_mov_b32_e32 v56, v88
	v_mov_b32_e32 v57, v88
	v_mov_b32_e32 v58, v88
	v_mov_b32_e32 v59, v88
	v_mov_b32_e32 v60, v88
	v_mov_b32_e32 v61, v88
	v_mov_b32_e32 v62, v88
	v_mov_b32_e32 v63, v88
	v_mov_b32_e32 v64, v88
	v_mov_b32_e32 v65, v88
	v_mov_b32_e32 v66, v88
	v_mov_b32_e32 v67, v88
	v_mov_b32_e32 v68, v88
	v_mov_b32_e32 v69, v88
	v_mov_b32_e32 v70, v88
	v_mov_b32_e32 v71, v88
	v_mov_b32_e32 v72, v88
	v_mov_b32_e32 v73, v88
	v_mov_b32_e32 v74, v88
	v_mov_b32_e32 v75, v88
	v_mov_b32_e32 v76, v88
	v_mov_b32_e32 v77, v88
	v_mov_b32_e32 v78, v88
	v_mov_b32_e32 v79, v88
	v_mov_b32_e32 v80, v88
	v_mov_b32_e32 v81, v88
	v_mov_b32_e32 v82, v88
	v_mov_b32_e32 v83, v88
	v_mov_b32_e32 v84, v88
	v_mov_b32_e32 v85, v88
	v_mov_b32_e32 v86, v88
	v_mov_b32_e32 v87, v88
	v_mov_b32_e32 v92, v88
	v_mov_b32_e32 v93, v88
	v_mov_b32_e32 v94, v88
	v_mov_b32_e32 v95, v88
	v_mov_b32_e32 v96, v88
	v_mov_b32_e32 v97, v88
	v_mov_b32_e32 v98, v88
	v_mov_b32_e32 v99, v88
	v_mov_b32_e32 v100, v88
	v_mov_b32_e32 v101, v88
	v_mov_b32_e32 v102, v88
	v_mov_b32_e32 v103, v88
	v_mov_b32_e32 v108, v88
	v_mov_b32_e32 v109, v88
	v_mov_b32_e32 v110, v88
	v_mov_b32_e32 v111, v88
	v_mov_b32_e32 v112, v88
	v_mov_b32_e32 v113, v88
	v_mov_b32_e32 v114, v88
	v_mov_b32_e32 v115, v88
	v_mov_b32_e32 v116, v88
	v_mov_b32_e32 v117, v88
	v_mov_b32_e32 v118, v88
	v_mov_b32_e32 v119, v88
	v_mov_b32_e32 v120, v88
	v_mov_b32_e32 v121, v88
	v_mov_b32_e32 v122, v88
	v_mov_b32_e32 v123, v88
	v_mov_b32_e32 v124, v88
	v_mov_b32_e32 v125, v88
	v_mov_b32_e32 v126, v88
	v_mov_b32_e32 v127, v88
	s_waitcnt vmcnt(16) lgkmcnt(0)
	s_barrier
	v_readfirstlane_b32 s98, v178
	s_nop 3
	s_lshr_b32 s98, s98, 6
	s_cmp_ge_u32 s98, 4
	s_cbranch_scc0 .Lprio_done_6
	s_setprio 1
.Lprio_done_6:
	v_bfe_u32 v250, v178, 3, 3
	v_and_b32_e32 v251, 7, v178
	v_lshrrev_b32_e32 v252, 1, v250
	v_xor_b32_e32 v251, v251, v252
	v_lshlrev_b32_e32 v251, 4, v251
	v_lshl_or_b32 v250, v250, 12, v251
	v_xor_b32_e32 v251, 64, v250
	v_add_u32_e32 v251, 0x8000, v251
	v_add_u32_e32 v252, 0x10000, v250
	v_add_u32_e32 v253, 0x10000, v251
	v_lshl_add_u64 v[242:243], v[140:141], 0, s[42:43]
	v_lshl_add_u64 v[242:243], v[242:243], 0, s[12:13]
	v_lshl_add_u64 v[244:245], v[142:143], 0, s[42:43]
	v_lshl_add_u64 v[244:245], v[244:245], 0, s[14:15]
	v_add_u32_e32 v254, v139, v149
	v_add_u32_e32 v255, v153, v149
	v_readfirstlane_b32 s98, v242
	v_readfirstlane_b32 s99, v243
	v_readfirstlane_b32 s100, v244
	v_readfirstlane_b32 s101, v245
	ds_read_b128 v[162:165], v254
	ds_read_b128 v[166:169], v254 offset:2048
	ds_read_b128 v[154:157], v255 offset:32768
	ds_read_b128 v[158:161], v255 offset:34816
	ds_read_b128 v[170:173], v255 offset:36864
	ds_read_b128 v[174:177], v255 offset:38912
	s_nop 4
	s_lshl_b32 m0, s42, 9
	s_and_b32 m0, m0, 0x10000
	s_xor_b32 m0, m0, 0x10000
	s_add_i32 m0, m0, s2
	s_nop 0
	global_load_lds_dwordx4 v250, s[98:99]
	s_add_i32 m0, m0, 0x8000
	s_nop 0
	global_load_lds_dwordx4 v250, s[100:101]
	s_add_i32 m0, m0, 0xffff8400
	s_nop 0
	global_load_lds_dwordx4 v251, s[98:99]
	s_add_i32 m0, m0, 0x8000
	s_nop 0
	global_load_lds_dwordx4 v251, s[100:101]

.Lgx_1187:
	s_setprio 0
	v_mfma_f32_16x16x32_bf16 v[20:23], v[154:157], v[242:245], v[20:23]
	v_mfma_f32_16x16x32_bf16 v[4:7], v[154:157], v[246:249], v[4:7]
	v_mfma_f32_16x16x32_bf16 v[16:19], v[158:161], v[242:245], v[16:19]
	v_mfma_f32_16x16x32_bf16 v[0:3], v[158:161], v[246:249], v[0:3]
	v_mfma_f32_16x16x32_bf16 v[12:15], v[170:173], v[242:245], v[12:15]
	v_mfma_f32_16x16x32_bf16 v[104:107], v[170:173], v[246:249], v[104:107]
	v_mfma_f32_16x16x32_bf16 v[8:11], v[174:177], v[242:245], v[8:11]
	v_mfma_f32_16x16x32_bf16 v[88:91], v[174:177], v[246:249], v[88:91]
	v_add_u32_e32 v153, s45, v153
	v_add_u32_e32 v166, v153, v149
	v_add_u32_e32 v139, s45, v139
	ds_read_b128 v[140:143], v166 offset:32768
	v_add_u32_e32 v170, v139, v149
	ds_read_b128 v[144:147], v166 offset:34816
	ds_read_b128 v[154:157], v170
	ds_read_b128 v[158:161], v170 offset:2048
	ds_read_b128 v[162:165], v166 offset:36864
	ds_read_b128 v[166:169], v166 offset:38912
	s_waitcnt lgkmcnt(3)
	v_mfma_f32_16x16x32_bf16 v[120:123], v[144:147], v[154:157], v[120:123]
	v_add_u32_e32 v139, v139, v150
	s_and_b64 vcc, exec, s[34:35]
	v_mfma_f32_16x16x32_bf16 v[124:127], v[140:143], v[154:157], v[124:127]
	s_waitcnt lgkmcnt(1)
	v_mfma_f32_16x16x32_bf16 v[116:119], v[162:165], v[154:157], v[116:119]
	s_waitcnt lgkmcnt(0)
	v_mfma_f32_16x16x32_bf16 v[112:115], v[166:169], v[154:157], v[112:115]
	v_mfma_f32_16x16x32_bf16 v[108:111], v[140:143], v[158:161], v[108:111]
	v_mfma_f32_16x16x32_bf16 v[100:103], v[144:147], v[158:161], v[100:103]
	v_mfma_f32_16x16x32_bf16 v[96:99], v[162:165], v[158:161], v[96:99]
	v_mfma_f32_16x16x32_bf16 v[92:95], v[166:169], v[158:161], v[92:95]
	ds_read_b128 v[154:157], v170 offset:4096
	ds_read_b128 v[158:161], v170 offset:6144
	s_waitcnt lgkmcnt(1)
	v_mfma_f32_16x16x32_bf16 v[84:87], v[140:143], v[154:157], v[84:87]
	v_mfma_f32_16x16x32_bf16 v[80:83], v[144:147], v[154:157], v[80:83]
	v_mfma_f32_16x16x32_bf16 v[76:79], v[162:165], v[154:157], v[76:79]
	v_mfma_f32_16x16x32_bf16 v[72:75], v[166:169], v[154:157], v[72:75]
	s_waitcnt lgkmcnt(0)
	v_mfma_f32_16x16x32_bf16 v[68:71], v[140:143], v[158:161], v[68:71]
	v_mfma_f32_16x16x32_bf16 v[64:67], v[144:147], v[158:161], v[64:67]
	v_mfma_f32_16x16x32_bf16 v[60:63], v[162:165], v[158:161], v[60:63]
	v_mfma_f32_16x16x32_bf16 v[56:59], v[166:169], v[158:161], v[56:59]
	ds_read_b128 v[154:157], v170 offset:8192
	ds_read_b128 v[158:161], v170 offset:10240
	s_waitcnt lgkmcnt(1)
	v_mfma_f32_16x16x32_bf16 v[52:55], v[140:143], v[154:157], v[52:55]
	v_mfma_f32_16x16x32_bf16 v[48:51], v[144:147], v[154:157], v[48:51]
	v_mfma_f32_16x16x32_bf16 v[44:47], v[162:165], v[154:157], v[44:47]
	v_mfma_f32_16x16x32_bf16 v[40:43], v[166:169], v[154:157], v[40:43]
	s_waitcnt lgkmcnt(0)
	v_mfma_f32_16x16x32_bf16 v[36:39], v[140:143], v[158:161], v[36:39]
	v_mfma_f32_16x16x32_bf16 v[32:35], v[144:147], v[158:161], v[32:35]
	v_mfma_f32_16x16x32_bf16 v[28:31], v[162:165], v[158:161], v[28:31]
	v_mfma_f32_16x16x32_bf16 v[24:27], v[166:169], v[158:161], v[24:27]
	ds_read_b128 v[154:157], v170 offset:12288
	ds_read_b128 v[158:161], v170 offset:14336
	s_waitcnt lgkmcnt(1)
	v_mfma_f32_16x16x32_bf16 v[20:23], v[140:143], v[154:157], v[20:23]
	s_waitcnt lgkmcnt(0)
	v_mfma_f32_16x16x32_bf16 v[4:7], v[140:143], v[158:161], v[4:7]
	v_mfma_f32_16x16x32_bf16 v[140:143], v[162:165], v[158:161], v[104:107]
	s_nop 2
	v_add_u32_e32 v104, v153, v150
	v_mfma_f32_16x16x32_bf16 v[16:19], v[144:147], v[154:157], v[16:19]
	v_mfma_f32_16x16x32_bf16 v[12:15], v[162:165], v[154:157], v[12:15]
	v_mfma_f32_16x16x32_bf16 v[8:11], v[166:169], v[154:157], v[8:11]
	v_mfma_f32_16x16x32_bf16 v[0:3], v[144:147], v[158:161], v[0:3]
	ds_read_b128 v[144:147], v104 offset:32768
	v_mfma_f32_16x16x32_bf16 v[154:157], v[166:169], v[158:161], v[88:91]
	ds_read_b128 v[158:161], v104 offset:34816
	s_nop 1
	ds_read_b128 v[88:91], v139
	ds_read_b128 v[162:165], v139 offset:2048
	ds_read_b128 v[166:169], v104 offset:36864
	ds_read_b128 v[170:173], v104 offset:38912
	s_waitcnt lgkmcnt(2)
	v_mfma_f32_16x16x32_bf16 v[108:111], v[144:147], v[162:165], v[108:111]
	v_mfma_f32_16x16x32_bf16 v[104:107], v[158:161], v[162:165], v[100:103]
	s_waitcnt lgkmcnt(1)
	v_mfma_f32_16x16x32_bf16 v[100:103], v[166:169], v[162:165], v[96:99]
	s_waitcnt lgkmcnt(0)
	v_mfma_f32_16x16x32_bf16 v[96:99], v[170:173], v[162:165], v[92:95]
	ds_read_b128 v[162:165], v139 offset:4096
	ds_read_b128 v[174:177], v139 offset:6144
	v_mfma_f32_16x16x32_bf16 v[124:127], v[144:147], v[88:91], v[124:127]
	v_mfma_f32_16x16x32_bf16 v[120:123], v[158:161], v[88:91], v[120:123]
	v_mfma_f32_16x16x32_bf16 v[116:119], v[166:169], v[88:91], v[116:119]
	v_mfma_f32_16x16x32_bf16 v[112:115], v[170:173], v[88:91], v[112:115]
	s_waitcnt lgkmcnt(1)
	v_mfma_f32_16x16x32_bf16 v[92:95], v[144:147], v[162:165], v[84:87]
	v_mfma_f32_16x16x32_bf16 v[88:91], v[158:161], v[162:165], v[80:83]
	v_mfma_f32_16x16x32_bf16 v[84:87], v[166:169], v[162:165], v[76:79]
	v_mfma_f32_16x16x32_bf16 v[80:83], v[170:173], v[162:165], v[72:75]
	s_waitcnt lgkmcnt(0)
	v_mfma_f32_16x16x32_bf16 v[76:79], v[144:147], v[174:177], v[68:71]
	v_mfma_f32_16x16x32_bf16 v[72:75], v[158:161], v[174:177], v[64:67]
	v_mfma_f32_16x16x32_bf16 v[68:71], v[166:169], v[174:177], v[60:63]
	v_mfma_f32_16x16x32_bf16 v[64:67], v[170:173], v[174:177], v[56:59]
	ds_read_b128 v[162:165], v139 offset:8192
	ds_read_b128 v[174:177], v139 offset:10240
	s_waitcnt lgkmcnt(1)
	v_mfma_f32_16x16x32_bf16 v[60:63], v[144:147], v[162:165], v[52:55]
	v_mfma_f32_16x16x32_bf16 v[56:59], v[158:161], v[162:165], v[48:51]
	v_mfma_f32_16x16x32_bf16 v[52:55], v[166:169], v[162:165], v[44:47]
	v_mfma_f32_16x16x32_bf16 v[48:51], v[170:173], v[162:165], v[40:43]
	s_waitcnt lgkmcnt(0)
	v_mfma_f32_16x16x32_bf16 v[44:47], v[144:147], v[174:177], v[36:39]
	v_mfma_f32_16x16x32_bf16 v[40:43], v[158:161], v[174:177], v[32:35]
	v_mfma_f32_16x16x32_bf16 v[36:39], v[166:169], v[174:177], v[28:31]
	v_mfma_f32_16x16x32_bf16 v[32:35], v[170:173], v[174:177], v[24:27]
	ds_read_b128 v[162:165], v139 offset:12288
	ds_read_b128 v[174:177], v139 offset:14336
	s_waitcnt vmcnt(0)
	s_waitcnt lgkmcnt(0)
	v_mfma_f32_16x16x32_bf16 v[28:31], v[144:147], v[162:165], v[20:23]
	s_barrier
	v_mfma_f32_16x16x32_bf16 v[24:27], v[158:161], v[162:165], v[16:19]
	v_mfma_f32_16x16x32_bf16 v[20:23], v[166:169], v[162:165], v[12:15]
	v_mfma_f32_16x16x32_bf16 v[16:19], v[170:173], v[162:165], v[8:11]
	v_mfma_f32_16x16x32_bf16 v[12:15], v[144:147], v[174:177], v[4:7]
	v_mfma_f32_16x16x32_bf16 v[4:7], v[158:161], v[174:177], v[0:3]
	v_mfma_f32_16x16x32_bf16 v[8:11], v[166:169], v[174:177], v[140:143]
	v_mfma_f32_16x16x32_bf16 v[0:3], v[170:173], v[174:177], v[154:157]
	s_cbranch_vccz .LBB0_1179
	s_add_u32 s38, s56, s38
	s_addc_u32 s39, s57, s39
	s_lshl_b64 s[34:35], s[40:41], 1
	s_add_u32 s36, s36, s34
	s_addc_u32 s37, s37, s35
	s_add_u32 s34, s38, s34
	s_addc_u32 s35, s39, s35
	s_add_i32 s2, s2, 0
	s_mov_b32 m0, s2
	v_mov_b32_e32 v139, v129
	global_load_lds_dwordx4 v128, s[36:37]
	s_add_i32 m0, s2, 0x8000
	v_lshl_add_u64 v[144:145], s[36:37], 0, v[138:139]
	s_add_i32 s2, s65, 0
	global_load_lds_dwordx4 v128, s[34:35]
	v_lshl_add_u64 v[146:147], v[144:145], 0, s[6:7]
	s_mov_b32 m0, s2
	v_lshl_add_u64 v[140:141], s[36:37], 0, v[128:129]
	global_load_lds_dwordx4 v[146:147], off
	v_lshl_add_u64 v[146:147], s[34:35], 0, v[138:139]
	v_lshl_add_u64 v[154:155], v[146:147], 0, s[6:7]
	s_add_i32 m0, s2, 0x8000
	s_add_i32 s2, s64, 0
	v_lshl_add_u64 v[142:143], s[34:35], 0, v[128:129]
	global_load_lds_dwordx4 v[154:155], off
	v_lshl_add_u64 v[140:141], v[140:141], 0, s[8:9]
	s_mov_b32 m0, s2
	s_nop 0
	global_load_lds_dwordx4 v[140:141], off
	v_lshl_add_u64 v[140:141], v[142:143], 0, s[8:9]
	s_add_i32 m0, s2, 0x8000
	s_add_i32 s2, s31, 0
	global_load_lds_dwordx4 v[140:141], off
	v_lshl_add_u64 v[140:141], v[144:145], 0, s[10:11]
	s_mov_b32 m0, s2
	s_nop 0
	global_load_lds_dwordx4 v[140:141], off
	v_lshl_add_u64 v[140:141], v[146:147], 0, s[10:11]
	s_add_i32 m0, s2, 0x8000
	s_nop 0
	global_load_lds_dwordx4 v[140:141], off
	s_branch .LBB0_1179

.LBB0_1242:
	s_lshr_b32 s48, s47, 1
	s_and_b32 s48, s48, 0x1ffff80
	v_or_b32_e32 v0, s48, v150
	s_and_b32 s47, s47, 0xc0
	v_lshlrev_b32_e32 v128, 7, v0
	v_or_b32_e32 v0, s47, v150
	s_mov_b32 s47, s11
	s_lshl_b64 s[46:47], s[46:47], 16
	s_add_u32 s42, s46, s42
	s_addc_u32 s43, s47, s43
	s_waitcnt vmcnt(16)
	v_lshlrev_b32_e32 v139, 7, v0
	v_lshl_add_u64 v[0:1], s[40:41], 0, v[130:131]
	s_add_u32 s44, s46, s44
	v_lshl_add_u64 v[142:143], v[0:1], 0, s[42:43]
	s_addc_u32 s45, s47, s45
	v_lshl_add_u64 v[0:1], s[40:41], 0, v[134:135]
	v_mov_b32_e32 v88, 0
	v_lshl_add_u64 v[144:145], v[132:133], 0, s[44:45]
	v_lshl_add_u64 v[146:147], v[0:1], 0, s[42:43]
	v_lshl_add_u64 v[148:149], v[136:137], 0, s[44:45]
	s_mov_b64 s[40:41], 0
	s_mov_b32 s42, 0
	v_mov_b32_e32 v89, v88
	v_mov_b32_e32 v90, v88
	v_mov_b32_e32 v91, v88
	v_mov_b32_e32 v104, v88
	v_mov_b32_e32 v105, v88
	v_mov_b32_e32 v106, v88
	v_mov_b32_e32 v107, v88
	v_mov_b32_e32 v0, v88
	v_mov_b32_e32 v1, v88
	v_mov_b32_e32 v2, v88
	v_mov_b32_e32 v3, v88
	v_mov_b32_e32 v4, v88
	v_mov_b32_e32 v5, v88
	v_mov_b32_e32 v6, v88
	v_mov_b32_e32 v7, v88
	v_mov_b32_e32 v8, v88
	v_mov_b32_e32 v9, v88
	v_mov_b32_e32 v10, v88
	v_mov_b32_e32 v11, v88
	v_mov_b32_e32 v12, v88
	v_mov_b32_e32 v13, v88
	v_mov_b32_e32 v14, v88
	v_mov_b32_e32 v15, v88
	v_mov_b32_e32 v16, v88
	v_mov_b32_e32 v17, v88
	v_mov_b32_e32 v18, v88
	v_mov_b32_e32 v19, v88
	v_mov_b32_e32 v20, v88
	v_mov_b32_e32 v21, v88
	v_mov_b32_e32 v22, v88
	v_mov_b32_e32 v23, v88
	v_mov_b32_e32 v24, v88
	v_mov_b32_e32 v25, v88
	v_mov_b32_e32 v26, v88
	v_mov_b32_e32 v27, v88
	v_mov_b32_e32 v28, v88
	v_mov_b32_e32 v29, v88
	v_mov_b32_e32 v30, v88
	v_mov_b32_e32 v31, v88
	v_mov_b32_e32 v32, v88
	v_mov_b32_e32 v33, v88
	v_mov_b32_e32 v34, v88
	v_mov_b32_e32 v35, v88
	v_mov_b32_e32 v36, v88
	v_mov_b32_e32 v37, v88
	v_mov_b32_e32 v38, v88
	v_mov_b32_e32 v39, v88
	v_mov_b32_e32 v40, v88
	v_mov_b32_e32 v41, v88
	v_mov_b32_e32 v42, v88
	v_mov_b32_e32 v43, v88
	v_mov_b32_e32 v44, v88
	v_mov_b32_e32 v45, v88
	v_mov_b32_e32 v46, v88
	v_mov_b32_e32 v47, v88
	v_mov_b32_e32 v48, v88
	v_mov_b32_e32 v49, v88
	v_mov_b32_e32 v50, v88
	v_mov_b32_e32 v51, v88
	v_mov_b32_e32 v52, v88
	v_mov_b32_e32 v53, v88
	v_mov_b32_e32 v54, v88
	v_mov_b32_e32 v55, v88
	v_mov_b32_e32 v56, v88
	v_mov_b32_e32 v57, v88
	v_mov_b32_e32 v58, v88
	v_mov_b32_e32 v59, v88
	v_mov_b32_e32 v60, v88
	v_mov_b32_e32 v61, v88
	v_mov_b32_e32 v62, v88
	v_mov_b32_e32 v63, v88
	v_mov_b32_e32 v64, v88
	v_mov_b32_e32 v65, v88
	v_mov_b32_e32 v66, v88
	v_mov_b32_e32 v67, v88
	v_mov_b32_e32 v68, v88
	v_mov_b32_e32 v69, v88
	v_mov_b32_e32 v70, v88
	v_mov_b32_e32 v71, v88
	v_mov_b32_e32 v72, v88
	v_mov_b32_e32 v73, v88
	v_mov_b32_e32 v74, v88
	v_mov_b32_e32 v75, v88
	v_mov_b32_e32 v76, v88
	v_mov_b32_e32 v77, v88
	v_mov_b32_e32 v78, v88
	v_mov_b32_e32 v79, v88
	v_mov_b32_e32 v80, v88
	v_mov_b32_e32 v81, v88
	v_mov_b32_e32 v82, v88
	v_mov_b32_e32 v83, v88
	v_mov_b32_e32 v84, v88
	v_mov_b32_e32 v85, v88
	v_mov_b32_e32 v86, v88
	v_mov_b32_e32 v87, v88
	v_mov_b32_e32 v92, v88
	v_mov_b32_e32 v93, v88
	v_mov_b32_e32 v94, v88
	v_mov_b32_e32 v95, v88
	v_mov_b32_e32 v96, v88
	v_mov_b32_e32 v97, v88
	v_mov_b32_e32 v98, v88
	v_mov_b32_e32 v99, v88
	v_mov_b32_e32 v100, v88
	v_mov_b32_e32 v101, v88
	v_mov_b32_e32 v102, v88
	v_mov_b32_e32 v103, v88
	v_mov_b32_e32 v108, v88
	v_mov_b32_e32 v109, v88
	v_mov_b32_e32 v110, v88
	v_mov_b32_e32 v111, v88
	v_mov_b32_e32 v112, v88
	v_mov_b32_e32 v113, v88
	v_mov_b32_e32 v114, v88
	v_mov_b32_e32 v115, v88
	v_mov_b32_e32 v116, v88
	v_mov_b32_e32 v117, v88
	v_mov_b32_e32 v118, v88
	v_mov_b32_e32 v119, v88
	v_mov_b32_e32 v120, v88
	v_mov_b32_e32 v121, v88
	v_mov_b32_e32 v122, v88
	v_mov_b32_e32 v123, v88
	v_mov_b32_e32 v124, v88
	v_mov_b32_e32 v125, v88
	v_mov_b32_e32 v126, v88
	v_mov_b32_e32 v127, v88
	s_waitcnt vmcnt(16) lgkmcnt(0)
	s_barrier
	v_readfirstlane_b32 s98, v178
	s_nop 3
	s_lshr_b32 s98, s98, 6
	s_cmp_ge_u32 s98, 4
	s_cbranch_scc0 .Lprio_done_7
	s_setprio 1
.Lprio_done_7:
	v_bfe_u32 v250, v178, 3, 3
	v_and_b32_e32 v251, 7, v178
	v_lshrrev_b32_e32 v252, 1, v250
	v_xor_b32_e32 v251, v251, v252
	v_lshlrev_b32_e32 v251, 4, v251
	v_lshl_or_b32 v250, v250, 11, v251
	v_xor_b32_e32 v251, 64, v250
	v_add_u32_e32 v251, 0x4000, v251
	v_add_u32_e32 v252, 0x8000, v250
	v_add_u32_e32 v253, 0x8000, v251
	v_lshl_add_u64 v[242:243], v[142:143], 0, s[40:41]
	v_lshl_add_u64 v[242:243], v[242:243], 0, s[18:19]
	v_lshl_add_u64 v[244:245], v[144:145], 0, s[40:41]
	v_lshl_add_u64 v[244:245], v[244:245], 0, s[20:21]
	v_add_u32_e32 v254, v128, v151
	v_add_u32_e32 v255, v139, v151
	v_readfirstlane_b32 s98, v242
	v_readfirstlane_b32 s99, v243
	v_readfirstlane_b32 s100, v244
	v_readfirstlane_b32 s101, v245
	ds_read_b128 v[164:167], v254
	ds_read_b128 v[168:171], v254 offset:2048
	ds_read_b128 v[156:159], v255 offset:32768
	ds_read_b128 v[160:163], v255 offset:34816
	ds_read_b128 v[172:175], v255 offset:36864
	ds_read_b128 v[188:191], v255 offset:38912
	s_nop 4
	s_lshl_b32 m0, s40, 9
	s_and_b32 m0, m0, 0x10000
	s_xor_b32 m0, m0, 0x10000
	s_add_i32 m0, m0, s10
	s_nop 0
	global_load_lds_dwordx4 v250, s[98:99]
	s_add_i32 m0, m0, 0x8000
	s_nop 0
	global_load_lds_dwordx4 v250, s[100:101]
	s_add_i32 m0, m0, 0xffff8400
	s_nop 0
	global_load_lds_dwordx4 v251, s[98:99]
	s_add_i32 m0, m0, 0x8000
	s_nop 0
	global_load_lds_dwordx4 v251, s[100:101]

.Lgx_1243:
	s_setprio 0
	v_mfma_f32_16x16x32_bf16 v[20:23], v[156:159], v[242:245], v[20:23]
	v_mfma_f32_16x16x32_bf16 v[4:7], v[156:159], v[246:249], v[4:7]
	v_mfma_f32_16x16x32_bf16 v[16:19], v[160:163], v[242:245], v[16:19]
	v_mfma_f32_16x16x32_bf16 v[0:3], v[160:163], v[246:249], v[0:3]
	v_mfma_f32_16x16x32_bf16 v[12:15], v[172:175], v[242:245], v[12:15]
	v_mfma_f32_16x16x32_bf16 v[104:107], v[172:175], v[246:249], v[104:107]
	v_mfma_f32_16x16x32_bf16 v[8:11], v[188:191], v[242:245], v[8:11]
	v_mfma_f32_16x16x32_bf16 v[88:91], v[188:191], v[246:249], v[88:91]
	v_add_u32_e32 v139, s43, v139
	v_add_u32_e32 v141, v139, v151
	v_add_u32_e32 v128, s43, v128
	ds_read_b128 v[142:145], v141 offset:32768
	v_add_u32_e32 v155, v128, v151
	ds_read_b128 v[146:149], v141 offset:34816
	ds_read_b128 v[156:159], v155
	ds_read_b128 v[160:163], v155 offset:2048
	ds_read_b128 v[164:167], v141 offset:36864
	ds_read_b128 v[168:171], v141 offset:38912
	s_waitcnt lgkmcnt(3)
	v_mfma_f32_16x16x32_bf16 v[120:123], v[146:149], v[156:159], v[120:123]
	v_add_u32_e32 v128, v128, v152
	s_and_b64 vcc, exec, s[2:3]
	v_mfma_f32_16x16x32_bf16 v[124:127], v[142:145], v[156:159], v[124:127]
	s_waitcnt lgkmcnt(1)
	v_mfma_f32_16x16x32_bf16 v[116:119], v[164:167], v[156:159], v[116:119]
	s_waitcnt lgkmcnt(0)
	v_mfma_f32_16x16x32_bf16 v[112:115], v[168:171], v[156:159], v[112:115]
	v_mfma_f32_16x16x32_bf16 v[108:111], v[142:145], v[160:163], v[108:111]
	v_mfma_f32_16x16x32_bf16 v[100:103], v[146:149], v[160:163], v[100:103]
	v_mfma_f32_16x16x32_bf16 v[96:99], v[164:167], v[160:163], v[96:99]
	v_mfma_f32_16x16x32_bf16 v[92:95], v[168:171], v[160:163], v[92:95]
	ds_read_b128 v[156:159], v155 offset:4096
	ds_read_b128 v[160:163], v155 offset:6144
	s_waitcnt lgkmcnt(1)
	v_mfma_f32_16x16x32_bf16 v[84:87], v[142:145], v[156:159], v[84:87]
	v_mfma_f32_16x16x32_bf16 v[80:83], v[146:149], v[156:159], v[80:83]
	v_mfma_f32_16x16x32_bf16 v[76:79], v[164:167], v[156:159], v[76:79]
	v_mfma_f32_16x16x32_bf16 v[72:75], v[168:171], v[156:159], v[72:75]
	s_waitcnt lgkmcnt(0)
	v_mfma_f32_16x16x32_bf16 v[68:71], v[142:145], v[160:163], v[68:71]
	v_mfma_f32_16x16x32_bf16 v[64:67], v[146:149], v[160:163], v[64:67]
	v_mfma_f32_16x16x32_bf16 v[60:63], v[164:167], v[160:163], v[60:63]
	v_mfma_f32_16x16x32_bf16 v[56:59], v[168:171], v[160:163], v[56:59]
	ds_read_b128 v[156:159], v155 offset:8192
	ds_read_b128 v[160:163], v155 offset:10240
	s_waitcnt lgkmcnt(1)
	v_mfma_f32_16x16x32_bf16 v[52:55], v[142:145], v[156:159], v[52:55]
	v_mfma_f32_16x16x32_bf16 v[48:51], v[146:149], v[156:159], v[48:51]
	v_mfma_f32_16x16x32_bf16 v[44:47], v[164:167], v[156:159], v[44:47]
	v_mfma_f32_16x16x32_bf16 v[40:43], v[168:171], v[156:159], v[40:43]
	s_waitcnt lgkmcnt(0)
	v_mfma_f32_16x16x32_bf16 v[36:39], v[142:145], v[160:163], v[36:39]
	v_mfma_f32_16x16x32_bf16 v[32:35], v[146:149], v[160:163], v[32:35]
	v_mfma_f32_16x16x32_bf16 v[28:31], v[164:167], v[160:163], v[28:31]
	v_mfma_f32_16x16x32_bf16 v[24:27], v[168:171], v[160:163], v[24:27]
	ds_read_b128 v[156:159], v155 offset:12288
	ds_read_b128 v[160:163], v155 offset:14336
	s_waitcnt lgkmcnt(1)
	v_mfma_f32_16x16x32_bf16 v[20:23], v[142:145], v[156:159], v[20:23]
	s_waitcnt lgkmcnt(0)
	v_mfma_f32_16x16x32_bf16 v[4:7], v[142:145], v[160:163], v[4:7]
	v_mfma_f32_16x16x32_bf16 v[142:145], v[164:167], v[160:163], v[104:107]
	s_nop 2
	v_add_u32_e32 v104, v139, v152
	v_mfma_f32_16x16x32_bf16 v[16:19], v[146:149], v[156:159], v[16:19]
	v_mfma_f32_16x16x32_bf16 v[12:15], v[164:167], v[156:159], v[12:15]
	v_mfma_f32_16x16x32_bf16 v[8:11], v[168:171], v[156:159], v[8:11]
	v_mfma_f32_16x16x32_bf16 v[0:3], v[146:149], v[160:163], v[0:3]
	ds_read_b128 v[146:149], v104 offset:32768
	v_mfma_f32_16x16x32_bf16 v[156:159], v[168:171], v[160:163], v[88:91]
	ds_read_b128 v[160:163], v104 offset:34816
	s_nop 1
	ds_read_b128 v[88:91], v128
	ds_read_b128 v[164:167], v128 offset:2048
	ds_read_b128 v[168:171], v104 offset:36864
	ds_read_b128 v[172:175], v104 offset:38912
	s_waitcnt lgkmcnt(2)
	v_mfma_f32_16x16x32_bf16 v[108:111], v[146:149], v[164:167], v[108:111]
	v_mfma_f32_16x16x32_bf16 v[104:107], v[160:163], v[164:167], v[100:103]
	s_waitcnt lgkmcnt(1)
	v_mfma_f32_16x16x32_bf16 v[100:103], v[168:171], v[164:167], v[96:99]
	s_waitcnt lgkmcnt(0)
	v_mfma_f32_16x16x32_bf16 v[96:99], v[172:175], v[164:167], v[92:95]
	ds_read_b128 v[164:167], v128 offset:4096
	ds_read_b128 v[188:191], v128 offset:6144
	v_mfma_f32_16x16x32_bf16 v[124:127], v[146:149], v[88:91], v[124:127]
	v_mfma_f32_16x16x32_bf16 v[120:123], v[160:163], v[88:91], v[120:123]
	v_mfma_f32_16x16x32_bf16 v[116:119], v[168:171], v[88:91], v[116:119]
	v_mfma_f32_16x16x32_bf16 v[112:115], v[172:175], v[88:91], v[112:115]
	s_waitcnt lgkmcnt(1)
	v_mfma_f32_16x16x32_bf16 v[92:95], v[146:149], v[164:167], v[84:87]
	v_mfma_f32_16x16x32_bf16 v[88:91], v[160:163], v[164:167], v[80:83]
	v_mfma_f32_16x16x32_bf16 v[84:87], v[168:171], v[164:167], v[76:79]
	v_mfma_f32_16x16x32_bf16 v[80:83], v[172:175], v[164:167], v[72:75]
	s_waitcnt lgkmcnt(0)
	v_mfma_f32_16x16x32_bf16 v[76:79], v[146:149], v[188:191], v[68:71]
	v_mfma_f32_16x16x32_bf16 v[72:75], v[160:163], v[188:191], v[64:67]
	v_mfma_f32_16x16x32_bf16 v[68:71], v[168:171], v[188:191], v[60:63]
	v_mfma_f32_16x16x32_bf16 v[64:67], v[172:175], v[188:191], v[56:59]
	ds_read_b128 v[164:167], v128 offset:8192
	ds_read_b128 v[188:191], v128 offset:10240
	s_waitcnt lgkmcnt(1)
	v_mfma_f32_16x16x32_bf16 v[60:63], v[146:149], v[164:167], v[52:55]
	v_mfma_f32_16x16x32_bf16 v[56:59], v[160:163], v[164:167], v[48:51]
	v_mfma_f32_16x16x32_bf16 v[52:55], v[168:171], v[164:167], v[44:47]
	v_mfma_f32_16x16x32_bf16 v[48:51], v[172:175], v[164:167], v[40:43]
	s_waitcnt lgkmcnt(0)
	v_mfma_f32_16x16x32_bf16 v[44:47], v[146:149], v[188:191], v[36:39]
	v_mfma_f32_16x16x32_bf16 v[40:43], v[160:163], v[188:191], v[32:35]
	v_mfma_f32_16x16x32_bf16 v[36:39], v[168:171], v[188:191], v[28:31]
	v_mfma_f32_16x16x32_bf16 v[32:35], v[172:175], v[188:191], v[24:27]
	ds_read_b128 v[164:167], v128 offset:12288
	ds_read_b128 v[188:191], v128 offset:14336
	s_waitcnt vmcnt(0)
	s_waitcnt lgkmcnt(0)
	v_mfma_f32_16x16x32_bf16 v[28:31], v[146:149], v[164:167], v[20:23]
	s_barrier
	v_mfma_f32_16x16x32_bf16 v[24:27], v[160:163], v[164:167], v[16:19]
	v_mfma_f32_16x16x32_bf16 v[20:23], v[168:171], v[164:167], v[12:15]
	v_mfma_f32_16x16x32_bf16 v[16:19], v[172:175], v[164:167], v[8:11]
	v_mfma_f32_16x16x32_bf16 v[12:15], v[146:149], v[188:191], v[4:7]
	v_mfma_f32_16x16x32_bf16 v[8:11], v[160:163], v[188:191], v[0:3]
	v_mfma_f32_16x16x32_bf16 v[4:7], v[168:171], v[188:191], v[142:145]
	v_mfma_f32_16x16x32_bf16 v[0:3], v[172:175], v[188:191], v[156:159]
	s_cbranch_vccz .LBB0_1246
	s_add_u32 s6, s60, s6
	s_addc_u32 s7, s61, s7
	s_lshl_b64 s[2:3], s[8:9], 1
	s_add_u32 s4, s4, s2
	s_addc_u32 s5, s5, s3
	s_add_u32 s2, s6, s2
	s_addc_u32 s3, s7, s3
	s_add_i32 s6, s10, 0
	v_mov_b32_e32 v139, v129
	s_mov_b32 m0, s6
	v_mov_b32_e32 v141, v129
	v_lshl_add_u64 v[142:143], s[4:5], 0, v[138:139]
	global_load_lds_dwordx4 v138, s[4:5]
	s_add_i32 m0, s6, 0x8000
	v_lshl_add_u64 v[146:147], s[4:5], 0, v[140:141]
	s_add_i32 s4, s53, 0
	global_load_lds_dwordx4 v138, s[2:3]
	v_lshl_add_u64 v[148:149], v[146:147], 0, s[12:13]
	s_mov_b32 m0, s4
	v_lshl_add_u64 v[144:145], s[2:3], 0, v[138:139]
	global_load_lds_dwordx4 v[148:149], off
	v_lshl_add_u64 v[148:149], s[2:3], 0, v[140:141]
	v_lshl_add_u64 v[156:157], v[148:149], 0, s[12:13]
	s_add_i32 m0, s4, 0x8000
	s_add_i32 s2, s52, 0
	global_load_lds_dwordx4 v[156:157], off
	v_lshl_add_u64 v[142:143], v[142:143], 0, s[14:15]
	s_mov_b32 m0, s2
	s_nop 0
	global_load_lds_dwordx4 v[142:143], off
	v_lshl_add_u64 v[142:143], v[144:145], 0, s[14:15]
	s_add_i32 m0, s2, 0x8000
	s_add_i32 s2, s39, 0
	global_load_lds_dwordx4 v[142:143], off
	v_lshl_add_u64 v[142:143], v[146:147], 0, s[16:17]
	s_mov_b32 m0, s2
	s_nop 0
	global_load_lds_dwordx4 v[142:143], off
	v_lshl_add_u64 v[142:143], v[148:149], 0, s[16:17]
	s_add_i32 m0, s2, 0x8000
	s_nop 0
	global_load_lds_dwordx4 v[142:143], off

.Lgx_1555:
	s_setprio 0
	v_mfma_f32_16x16x32_bf16 v[20:23], v[154:157], v[242:245], v[20:23]
	v_mfma_f32_16x16x32_bf16 v[4:7], v[154:157], v[246:249], v[4:7]
	v_mfma_f32_16x16x32_bf16 v[16:19], v[158:161], v[242:245], v[16:19]
	v_mfma_f32_16x16x32_bf16 v[0:3], v[158:161], v[246:249], v[0:3]
	v_mfma_f32_16x16x32_bf16 v[12:15], v[170:173], v[242:245], v[12:15]
	v_mfma_f32_16x16x32_bf16 v[104:107], v[170:173], v[246:249], v[104:107]
	v_mfma_f32_16x16x32_bf16 v[8:11], v[174:177], v[242:245], v[8:11]
	v_mfma_f32_16x16x32_bf16 v[88:91], v[174:177], v[246:249], v[88:91]
	v_add_u32_e32 v153, s43, v153
	v_add_u32_e32 v166, v153, v149
	v_add_u32_e32 v139, s43, v139
	ds_read_b128 v[140:143], v166 offset:32768
	v_add_u32_e32 v170, v139, v149
	ds_read_b128 v[144:147], v166 offset:34816
	ds_read_b128 v[154:157], v170
	ds_read_b128 v[158:161], v170 offset:2048
	ds_read_b128 v[162:165], v166 offset:36864
	ds_read_b128 v[166:169], v166 offset:38912
	s_waitcnt lgkmcnt(3)
	v_mfma_f32_16x16x32_bf16 v[120:123], v[144:147], v[154:157], v[120:123]
	v_add_u32_e32 v139, v139, v150
	s_and_b64 vcc, exec, s[30:31]
	v_mfma_f32_16x16x32_bf16 v[124:127], v[140:143], v[154:157], v[124:127]
	s_waitcnt lgkmcnt(1)
	v_mfma_f32_16x16x32_bf16 v[116:119], v[162:165], v[154:157], v[116:119]
	s_waitcnt lgkmcnt(0)
	v_mfma_f32_16x16x32_bf16 v[112:115], v[166:169], v[154:157], v[112:115]
	v_mfma_f32_16x16x32_bf16 v[108:111], v[140:143], v[158:161], v[108:111]
	v_mfma_f32_16x16x32_bf16 v[100:103], v[144:147], v[158:161], v[100:103]
	v_mfma_f32_16x16x32_bf16 v[96:99], v[162:165], v[158:161], v[96:99]
	v_mfma_f32_16x16x32_bf16 v[92:95], v[166:169], v[158:161], v[92:95]
	ds_read_b128 v[154:157], v170 offset:4096
	ds_read_b128 v[158:161], v170 offset:6144
	s_waitcnt lgkmcnt(1)
	v_mfma_f32_16x16x32_bf16 v[84:87], v[140:143], v[154:157], v[84:87]
	v_mfma_f32_16x16x32_bf16 v[80:83], v[144:147], v[154:157], v[80:83]
	v_mfma_f32_16x16x32_bf16 v[76:79], v[162:165], v[154:157], v[76:79]
	v_mfma_f32_16x16x32_bf16 v[72:75], v[166:169], v[154:157], v[72:75]
	s_waitcnt lgkmcnt(0)
	v_mfma_f32_16x16x32_bf16 v[68:71], v[140:143], v[158:161], v[68:71]
	v_mfma_f32_16x16x32_bf16 v[64:67], v[144:147], v[158:161], v[64:67]
	v_mfma_f32_16x16x32_bf16 v[60:63], v[162:165], v[158:161], v[60:63]
	v_mfma_f32_16x16x32_bf16 v[56:59], v[166:169], v[158:161], v[56:59]
	ds_read_b128 v[154:157], v170 offset:8192
	ds_read_b128 v[158:161], v170 offset:10240
	s_waitcnt lgkmcnt(1)
	v_mfma_f32_16x16x32_bf16 v[52:55], v[140:143], v[154:157], v[52:55]
	v_mfma_f32_16x16x32_bf16 v[48:51], v[144:147], v[154:157], v[48:51]
	v_mfma_f32_16x16x32_bf16 v[44:47], v[162:165], v[154:157], v[44:47]
	v_mfma_f32_16x16x32_bf16 v[40:43], v[166:169], v[154:157], v[40:43]
	s_waitcnt lgkmcnt(0)
	v_mfma_f32_16x16x32_bf16 v[36:39], v[140:143], v[158:161], v[36:39]
	v_mfma_f32_16x16x32_bf16 v[32:35], v[144:147], v[158:161], v[32:35]
	v_mfma_f32_16x16x32_bf16 v[28:31], v[162:165], v[158:161], v[28:31]
	v_mfma_f32_16x16x32_bf16 v[24:27], v[166:169], v[158:161], v[24:27]
	ds_read_b128 v[154:157], v170 offset:12288
	ds_read_b128 v[158:161], v170 offset:14336
	s_waitcnt lgkmcnt(1)
	v_mfma_f32_16x16x32_bf16 v[20:23], v[140:143], v[154:157], v[20:23]
	s_waitcnt lgkmcnt(0)
	v_mfma_f32_16x16x32_bf16 v[4:7], v[140:143], v[158:161], v[4:7]
	v_mfma_f32_16x16x32_bf16 v[140:143], v[162:165], v[158:161], v[104:107]
	s_nop 2
	v_add_u32_e32 v104, v153, v150
	v_mfma_f32_16x16x32_bf16 v[16:19], v[144:147], v[154:157], v[16:19]
	v_mfma_f32_16x16x32_bf16 v[12:15], v[162:165], v[154:157], v[12:15]
	v_mfma_f32_16x16x32_bf16 v[8:11], v[166:169], v[154:157], v[8:11]
	v_mfma_f32_16x16x32_bf16 v[0:3], v[144:147], v[158:161], v[0:3]
	ds_read_b128 v[144:147], v104 offset:32768
	v_mfma_f32_16x16x32_bf16 v[154:157], v[166:169], v[158:161], v[88:91]
	ds_read_b128 v[158:161], v104 offset:34816
	s_nop 1
	ds_read_b128 v[88:91], v139
	ds_read_b128 v[162:165], v139 offset:2048
	ds_read_b128 v[166:169], v104 offset:36864
	ds_read_b128 v[170:173], v104 offset:38912
	s_waitcnt lgkmcnt(2)
	v_mfma_f32_16x16x32_bf16 v[108:111], v[144:147], v[162:165], v[108:111]
	v_mfma_f32_16x16x32_bf16 v[104:107], v[158:161], v[162:165], v[100:103]
	s_waitcnt lgkmcnt(1)
	v_mfma_f32_16x16x32_bf16 v[100:103], v[166:169], v[162:165], v[96:99]
	s_waitcnt lgkmcnt(0)
	v_mfma_f32_16x16x32_bf16 v[96:99], v[170:173], v[162:165], v[92:95]
	ds_read_b128 v[162:165], v139 offset:4096
	ds_read_b128 v[174:177], v139 offset:6144
	v_mfma_f32_16x16x32_bf16 v[124:127], v[144:147], v[88:91], v[124:127]
	v_mfma_f32_16x16x32_bf16 v[120:123], v[158:161], v[88:91], v[120:123]
	v_mfma_f32_16x16x32_bf16 v[116:119], v[166:169], v[88:91], v[116:119]
	v_mfma_f32_16x16x32_bf16 v[112:115], v[170:173], v[88:91], v[112:115]
	s_waitcnt lgkmcnt(1)
	v_mfma_f32_16x16x32_bf16 v[92:95], v[144:147], v[162:165], v[84:87]
	v_mfma_f32_16x16x32_bf16 v[88:91], v[158:161], v[162:165], v[80:83]
	v_mfma_f32_16x16x32_bf16 v[84:87], v[166:169], v[162:165], v[76:79]
	v_mfma_f32_16x16x32_bf16 v[80:83], v[170:173], v[162:165], v[72:75]
	s_waitcnt lgkmcnt(0)
	v_mfma_f32_16x16x32_bf16 v[76:79], v[144:147], v[174:177], v[68:71]
	v_mfma_f32_16x16x32_bf16 v[72:75], v[158:161], v[174:177], v[64:67]
	v_mfma_f32_16x16x32_bf16 v[68:71], v[166:169], v[174:177], v[60:63]
	v_mfma_f32_16x16x32_bf16 v[64:67], v[170:173], v[174:177], v[56:59]
	ds_read_b128 v[162:165], v139 offset:8192
	ds_read_b128 v[174:177], v139 offset:10240
	s_waitcnt lgkmcnt(1)
	v_mfma_f32_16x16x32_bf16 v[60:63], v[144:147], v[162:165], v[52:55]
	v_mfma_f32_16x16x32_bf16 v[56:59], v[158:161], v[162:165], v[48:51]
	v_mfma_f32_16x16x32_bf16 v[52:55], v[166:169], v[162:165], v[44:47]
	v_mfma_f32_16x16x32_bf16 v[48:51], v[170:173], v[162:165], v[40:43]
	s_waitcnt lgkmcnt(0)
	v_mfma_f32_16x16x32_bf16 v[44:47], v[144:147], v[174:177], v[36:39]
	v_mfma_f32_16x16x32_bf16 v[40:43], v[158:161], v[174:177], v[32:35]
	v_mfma_f32_16x16x32_bf16 v[36:39], v[166:169], v[174:177], v[28:31]
	v_mfma_f32_16x16x32_bf16 v[32:35], v[170:173], v[174:177], v[24:27]
	ds_read_b128 v[162:165], v139 offset:12288
	ds_read_b128 v[174:177], v139 offset:14336
	s_waitcnt vmcnt(0)
	s_waitcnt lgkmcnt(0)
	v_mfma_f32_16x16x32_bf16 v[28:31], v[144:147], v[162:165], v[20:23]
	s_barrier
	v_mfma_f32_16x16x32_bf16 v[24:27], v[158:161], v[162:165], v[16:19]
	v_mfma_f32_16x16x32_bf16 v[20:23], v[166:169], v[162:165], v[12:15]
	v_mfma_f32_16x16x32_bf16 v[16:19], v[170:173], v[162:165], v[8:11]
	v_mfma_f32_16x16x32_bf16 v[12:15], v[144:147], v[174:177], v[4:7]
	v_mfma_f32_16x16x32_bf16 v[4:7], v[158:161], v[174:177], v[0:3]
	v_mfma_f32_16x16x32_bf16 v[8:11], v[166:169], v[174:177], v[140:143]
	v_mfma_f32_16x16x32_bf16 v[0:3], v[170:173], v[174:177], v[154:157]
	s_cbranch_vccz .LBB0_1547
	s_add_u32 s36, s54, s36
	s_addc_u32 s37, s55, s37
	s_lshl_b64 s[30:31], s[38:39], 1
	s_add_u32 s34, s34, s30
	s_addc_u32 s35, s35, s31
	s_add_u32 s30, s36, s30
	s_addc_u32 s31, s37, s31
	s_add_i32 s2, s2, 0
	s_mov_b32 m0, s2
	v_mov_b32_e32 v139, v129
	global_load_lds_dwordx4 v128, s[34:35]
	s_add_i32 m0, s2, 0x8000
	v_lshl_add_u64 v[144:145], s[34:35], 0, v[138:139]
	s_add_i32 s2, s63, 0
	global_load_lds_dwordx4 v128, s[30:31]
	v_lshl_add_u64 v[146:147], v[144:145], 0, s[4:5]
	s_mov_b32 m0, s2
	v_lshl_add_u64 v[140:141], s[34:35], 0, v[128:129]
	global_load_lds_dwordx4 v[146:147], off
	v_lshl_add_u64 v[146:147], s[30:31], 0, v[138:139]
	v_lshl_add_u64 v[154:155], v[146:147], 0, s[4:5]
	s_add_i32 m0, s2, 0x8000
	s_add_i32 s2, s62, 0
	v_lshl_add_u64 v[142:143], s[30:31], 0, v[128:129]
	global_load_lds_dwordx4 v[154:155], off
	v_lshl_add_u64 v[140:141], v[140:141], 0, s[6:7]
	s_mov_b32 m0, s2
	s_nop 0
	global_load_lds_dwordx4 v[140:141], off
	v_lshl_add_u64 v[140:141], v[142:143], 0, s[6:7]
	s_add_i32 m0, s2, 0x8000
	s_add_i32 s2, s29, 0
	global_load_lds_dwordx4 v[140:141], off
	v_lshl_add_u64 v[140:141], v[144:145], 0, s[8:9]
	s_mov_b32 m0, s2
	s_nop 0
	global_load_lds_dwordx4 v[140:141], off
	v_lshl_add_u64 v[140:141], v[146:147], 0, s[8:9]
	s_add_i32 m0, s2, 0x8000
	s_nop 0
	global_load_lds_dwordx4 v[140:141], off
	s_branch .LBB0_1547

.LBB0_1613:
	s_lshr_b32 s4, s3, 1
	s_and_b32 s4, s4, 0x1ffff80
	v_or_b32_e32 v0, s4, v154
	s_and_b32 s3, s3, 0xc0
	v_lshlrev_b32_e32 v128, 7, v0
	v_or_b32_e32 v0, s3, v154
	s_mov_b32 s3, s15
	s_lshl_b64 s[2:3], s[2:3], 16
	s_add_u32 s4, s2, s74
	v_lshlrev_b32_e32 v139, 7, v0
	v_lshl_add_u64 v[0:1], s[66:67], 0, v[130:131]
	s_addc_u32 s5, s3, s75
	s_waitcnt vmcnt(16)
	v_lshl_add_u64 v[142:143], v[0:1], 0, s[4:5]
	s_add_u32 s2, s2, s76
	v_lshl_add_u64 v[0:1], s[66:67], 0, v[134:135]
	s_addc_u32 s3, s3, s77
	v_lshl_add_u64 v[146:147], v[0:1], 0, s[4:5]
	v_mov_b32_e32 v0, 0
	v_lshl_add_u64 v[144:145], v[132:133], 0, s[2:3]
	v_lshl_add_u64 v[148:149], v[136:137], 0, s[2:3]
	s_mov_b64 s[2:3], 0
	s_mov_b32 s10, 0
	v_mov_b32_e32 v1, v0
	v_mov_b32_e32 v2, v0
	v_mov_b32_e32 v3, v0
	v_mov_b32_e32 v4, v0
	v_mov_b32_e32 v5, v0
	v_mov_b32_e32 v6, v0
	v_mov_b32_e32 v7, v0
	v_mov_b32_e32 v8, v0
	v_mov_b32_e32 v9, v0
	v_mov_b32_e32 v10, v0
	v_mov_b32_e32 v11, v0
	v_mov_b32_e32 v12, v0
	v_mov_b32_e32 v13, v0
	v_mov_b32_e32 v14, v0
	v_mov_b32_e32 v15, v0
	v_mov_b32_e32 v16, v0
	v_mov_b32_e32 v17, v0
	v_mov_b32_e32 v18, v0
	v_mov_b32_e32 v19, v0
	v_mov_b32_e32 v20, v0
	v_mov_b32_e32 v21, v0
	v_mov_b32_e32 v22, v0
	v_mov_b32_e32 v23, v0
	v_mov_b32_e32 v24, v0
	v_mov_b32_e32 v25, v0
	v_mov_b32_e32 v26, v0
	v_mov_b32_e32 v27, v0
	v_mov_b32_e32 v28, v0
	v_mov_b32_e32 v29, v0
	v_mov_b32_e32 v30, v0
	v_mov_b32_e32 v31, v0
	v_mov_b32_e32 v32, v0
	v_mov_b32_e32 v33, v0
	v_mov_b32_e32 v34, v0
	v_mov_b32_e32 v35, v0
	v_mov_b32_e32 v36, v0
	v_mov_b32_e32 v37, v0
	v_mov_b32_e32 v38, v0
	v_mov_b32_e32 v39, v0
	v_mov_b32_e32 v40, v0
	v_mov_b32_e32 v41, v0
	v_mov_b32_e32 v42, v0
	v_mov_b32_e32 v43, v0
	v_mov_b32_e32 v44, v0
	v_mov_b32_e32 v45, v0
	v_mov_b32_e32 v46, v0
	v_mov_b32_e32 v47, v0
	v_mov_b32_e32 v48, v0
	v_mov_b32_e32 v49, v0
	v_mov_b32_e32 v50, v0
	v_mov_b32_e32 v51, v0
	v_mov_b32_e32 v52, v0
	v_mov_b32_e32 v53, v0
	v_mov_b32_e32 v54, v0
	v_mov_b32_e32 v55, v0
	v_mov_b32_e32 v56, v0
	v_mov_b32_e32 v57, v0
	v_mov_b32_e32 v58, v0
	v_mov_b32_e32 v59, v0
	v_mov_b32_e32 v60, v0
	v_mov_b32_e32 v61, v0
	v_mov_b32_e32 v62, v0
	v_mov_b32_e32 v63, v0
	v_mov_b32_e32 v64, v0
	v_mov_b32_e32 v65, v0
	v_mov_b32_e32 v66, v0
	v_mov_b32_e32 v67, v0
	v_mov_b32_e32 v68, v0
	v_mov_b32_e32 v69, v0
	v_mov_b32_e32 v70, v0
	v_mov_b32_e32 v71, v0
	v_mov_b32_e32 v72, v0
	v_mov_b32_e32 v73, v0
	v_mov_b32_e32 v74, v0
	v_mov_b32_e32 v75, v0
	v_mov_b32_e32 v76, v0
	v_mov_b32_e32 v77, v0
	v_mov_b32_e32 v78, v0
	v_mov_b32_e32 v79, v0
	v_mov_b32_e32 v80, v0
	v_mov_b32_e32 v81, v0
	v_mov_b32_e32 v82, v0
	v_mov_b32_e32 v83, v0
	v_mov_b32_e32 v84, v0
	v_mov_b32_e32 v85, v0
	v_mov_b32_e32 v86, v0
	v_mov_b32_e32 v87, v0
	v_mov_b32_e32 v88, v0
	v_mov_b32_e32 v89, v0
	v_mov_b32_e32 v90, v0
	v_mov_b32_e32 v91, v0
	v_mov_b32_e32 v92, v0
	v_mov_b32_e32 v93, v0
	v_mov_b32_e32 v94, v0
	v_mov_b32_e32 v95, v0
	v_mov_b32_e32 v96, v0
	v_mov_b32_e32 v97, v0
	v_mov_b32_e32 v98, v0
	v_mov_b32_e32 v99, v0
	v_mov_b32_e32 v100, v0
	v_mov_b32_e32 v101, v0
	v_mov_b32_e32 v102, v0
	v_mov_b32_e32 v103, v0
	v_mov_b32_e32 v104, v0
	v_mov_b32_e32 v105, v0
	v_mov_b32_e32 v106, v0
	v_mov_b32_e32 v107, v0
	v_mov_b32_e32 v108, v0
	v_mov_b32_e32 v109, v0
	v_mov_b32_e32 v110, v0
	v_mov_b32_e32 v111, v0
	v_mov_b32_e32 v112, v0
	v_mov_b32_e32 v113, v0
	v_mov_b32_e32 v114, v0
	v_mov_b32_e32 v115, v0
	v_mov_b32_e32 v116, v0
	v_mov_b32_e32 v117, v0
	v_mov_b32_e32 v118, v0
	v_mov_b32_e32 v119, v0
	v_mov_b32_e32 v120, v0
	v_mov_b32_e32 v121, v0
	v_mov_b32_e32 v122, v0
	v_mov_b32_e32 v123, v0
	v_mov_b32_e32 v124, v0
	v_mov_b32_e32 v125, v0
	v_mov_b32_e32 v126, v0
	v_mov_b32_e32 v127, v0
	s_waitcnt vmcnt(16) lgkmcnt(0)
	s_barrier
	v_readfirstlane_b32 s98, v178
	s_nop 3
	s_lshr_b32 s98, s98, 6
	s_cmp_ge_u32 s98, 4
	s_cbranch_scc0 .Lprio_done_9
	s_setprio 1
.Lprio_done_9:
	v_bfe_u32 v250, v178, 3, 3
	v_and_b32_e32 v251, 7, v178
	v_lshrrev_b32_e32 v252, 1, v250
	v_xor_b32_e32 v251, v251, v252
	v_lshlrev_b32_e32 v251, 4, v251
	v_lshl_or_b32 v250, v250, 11, v251
	v_xor_b32_e32 v251, 64, v250
	v_add_u32_e32 v251, 0x4000, v251
	v_add_u32_e32 v252, 0x8000, v250
	v_add_u32_e32 v253, 0x8000, v251
	v_lshl_add_u64 v[242:243], v[142:143], 0, s[2:3]
	v_lshl_add_u64 v[242:243], v[242:243], 0, s[38:39]
	v_lshl_add_u64 v[244:245], v[144:145], 0, s[2:3]
	v_lshl_add_u64 v[244:245], v[244:245], 0, s[40:41]
	v_add_u32_e32 v254, v128, v155
	v_add_u32_e32 v255, v139, v155
	v_readfirstlane_b32 s98, v242
	v_readfirstlane_b32 s99, v243
	v_readfirstlane_b32 s100, v244
	v_readfirstlane_b32 s101, v245
	ds_read_b128 v[208:211], v254
	ds_read_b128 v[212:215], v254 offset:2048
	ds_read_b128 v[150:153], v255 offset:32768
	ds_read_b128 v[196:199], v255 offset:34816
	ds_read_b128 v[200:203], v255 offset:36864
	ds_read_b128 v[204:207], v255 offset:38912
	s_nop 4
	s_lshl_b32 m0, s2, 9
	s_and_b32 m0, m0, 0x10000
	s_xor_b32 m0, m0, 0x10000
	s_add_i32 m0, m0, s6
	s_nop 0
	global_load_lds_dwordx4 v250, s[98:99]
	s_add_i32 m0, m0, 0x8000
	s_nop 0
	global_load_lds_dwordx4 v250, s[100:101]
	s_add_i32 m0, m0, 0xffff8400
	s_nop 0
	global_load_lds_dwordx4 v251, s[98:99]
	s_add_i32 m0, m0, 0x8000
	s_nop 0
	global_load_lds_dwordx4 v251, s[100:101]

.Lgx_1614:
	s_setprio 0
	v_mfma_f32_16x16x32_bf16 v[28:31], v[150:153], v[242:245], v[28:31]
	v_mfma_f32_16x16x32_bf16 v[12:15], v[150:153], v[246:249], v[12:15]
	v_mfma_f32_16x16x32_bf16 v[24:27], v[196:199], v[242:245], v[24:27]
	v_mfma_f32_16x16x32_bf16 v[8:11], v[196:199], v[246:249], v[8:11]
	v_mfma_f32_16x16x32_bf16 v[20:23], v[200:203], v[242:245], v[20:23]
	v_mfma_f32_16x16x32_bf16 v[4:7], v[200:203], v[246:249], v[4:7]
	v_mfma_f32_16x16x32_bf16 v[16:19], v[204:207], v[242:245], v[16:19]
	v_mfma_f32_16x16x32_bf16 v[0:3], v[204:207], v[246:249], v[0:3]
	v_add_u32_e32 v139, s4, v139
	v_add_u32_e32 v141, v139, v155
	ds_read_b128 v[142:145], v141 offset:32768
	ds_read_b128 v[150:153], v141 offset:34816
	ds_read_b128 v[196:199], v141 offset:36864
	ds_read_b128 v[200:203], v141 offset:38912
	v_add_u32_e32 v128, s4, v128
	v_add_u32_e32 v195, v128, v155
	ds_read_b128 v[146:149], v195
	v_add_u32_e32 v139, v139, v156
	v_add_u32_e32 v128, v128, v156
	s_waitcnt lgkmcnt(0)
	v_mfma_f32_16x16x32_bf16 v[124:127], v[142:145], v[146:149], v[124:127]
	s_and_b64 vcc, exec, s[60:61]
	v_mfma_f32_16x16x32_bf16 v[120:123], v[150:153], v[146:149], v[120:123]
	v_mfma_f32_16x16x32_bf16 v[116:119], v[196:199], v[146:149], v[116:119]
	v_mfma_f32_16x16x32_bf16 v[112:115], v[200:203], v[146:149], v[112:115]
	ds_read_b128 v[146:149], v195 offset:2048
	s_waitcnt lgkmcnt(0)
	v_mfma_f32_16x16x32_bf16 v[108:111], v[142:145], v[146:149], v[108:111]
	v_mfma_f32_16x16x32_bf16 v[104:107], v[150:153], v[146:149], v[104:107]
	v_mfma_f32_16x16x32_bf16 v[100:103], v[196:199], v[146:149], v[100:103]
	v_mfma_f32_16x16x32_bf16 v[96:99], v[200:203], v[146:149], v[96:99]
	ds_read_b128 v[146:149], v195 offset:4096
	s_waitcnt lgkmcnt(0)
	v_mfma_f32_16x16x32_bf16 v[92:95], v[142:145], v[146:149], v[92:95]
	v_mfma_f32_16x16x32_bf16 v[88:91], v[150:153], v[146:149], v[88:91]
	v_mfma_f32_16x16x32_bf16 v[84:87], v[196:199], v[146:149], v[84:87]
	v_mfma_f32_16x16x32_bf16 v[80:83], v[200:203], v[146:149], v[80:83]
	ds_read_b128 v[146:149], v195 offset:6144
	s_waitcnt lgkmcnt(0)
	v_mfma_f32_16x16x32_bf16 v[76:79], v[142:145], v[146:149], v[76:79]
	v_mfma_f32_16x16x32_bf16 v[72:75], v[150:153], v[146:149], v[72:75]
	v_mfma_f32_16x16x32_bf16 v[68:71], v[196:199], v[146:149], v[68:71]
	v_mfma_f32_16x16x32_bf16 v[64:67], v[200:203], v[146:149], v[64:67]
	ds_read_b128 v[146:149], v195 offset:8192
	s_waitcnt lgkmcnt(0)
	v_mfma_f32_16x16x32_bf16 v[60:63], v[142:145], v[146:149], v[60:63]
	v_mfma_f32_16x16x32_bf16 v[56:59], v[150:153], v[146:149], v[56:59]
	v_mfma_f32_16x16x32_bf16 v[52:55], v[196:199], v[146:149], v[52:55]
	v_mfma_f32_16x16x32_bf16 v[48:51], v[200:203], v[146:149], v[48:51]
	ds_read_b128 v[146:149], v195 offset:10240
	s_waitcnt lgkmcnt(0)
	v_mfma_f32_16x16x32_bf16 v[44:47], v[142:145], v[146:149], v[44:47]
	v_mfma_f32_16x16x32_bf16 v[40:43], v[150:153], v[146:149], v[40:43]
	v_mfma_f32_16x16x32_bf16 v[36:39], v[196:199], v[146:149], v[36:39]
	v_mfma_f32_16x16x32_bf16 v[32:35], v[200:203], v[146:149], v[32:35]
	ds_read_b128 v[146:149], v195 offset:12288
	s_waitcnt lgkmcnt(0)
	v_mfma_f32_16x16x32_bf16 v[28:31], v[142:145], v[146:149], v[28:31]
	v_mfma_f32_16x16x32_bf16 v[24:27], v[150:153], v[146:149], v[24:27]
	v_mfma_f32_16x16x32_bf16 v[20:23], v[196:199], v[146:149], v[20:23]
	v_mfma_f32_16x16x32_bf16 v[16:19], v[200:203], v[146:149], v[16:19]
	ds_read_b128 v[146:149], v195 offset:14336
	s_waitcnt lgkmcnt(0)
	v_mfma_f32_16x16x32_bf16 v[12:15], v[142:145], v[146:149], v[12:15]
	ds_read_b128 v[142:145], v139 offset:32768
	v_mfma_f32_16x16x32_bf16 v[8:11], v[150:153], v[146:149], v[8:11]
	ds_read_b128 v[150:153], v139 offset:34816
	v_mfma_f32_16x16x32_bf16 v[4:7], v[196:199], v[146:149], v[4:7]
	ds_read_b128 v[196:199], v139 offset:36864
	v_mfma_f32_16x16x32_bf16 v[0:3], v[200:203], v[146:149], v[0:3]
	ds_read_b128 v[200:203], v139 offset:38912
	ds_read_b128 v[146:149], v128
	s_waitcnt lgkmcnt(0)
	v_mfma_f32_16x16x32_bf16 v[124:127], v[142:145], v[146:149], v[124:127]
	v_mfma_f32_16x16x32_bf16 v[120:123], v[150:153], v[146:149], v[120:123]
	v_mfma_f32_16x16x32_bf16 v[116:119], v[196:199], v[146:149], v[116:119]
	v_mfma_f32_16x16x32_bf16 v[112:115], v[200:203], v[146:149], v[112:115]
	ds_read_b128 v[146:149], v128 offset:2048
	s_waitcnt lgkmcnt(0)
	v_mfma_f32_16x16x32_bf16 v[108:111], v[142:145], v[146:149], v[108:111]
	v_mfma_f32_16x16x32_bf16 v[104:107], v[150:153], v[146:149], v[104:107]
	v_mfma_f32_16x16x32_bf16 v[100:103], v[196:199], v[146:149], v[100:103]
	v_mfma_f32_16x16x32_bf16 v[96:99], v[200:203], v[146:149], v[96:99]
	ds_read_b128 v[146:149], v128 offset:4096
	s_waitcnt lgkmcnt(0)
	v_mfma_f32_16x16x32_bf16 v[92:95], v[142:145], v[146:149], v[92:95]
	v_mfma_f32_16x16x32_bf16 v[88:91], v[150:153], v[146:149], v[88:91]
	v_mfma_f32_16x16x32_bf16 v[84:87], v[196:199], v[146:149], v[84:87]
	v_mfma_f32_16x16x32_bf16 v[80:83], v[200:203], v[146:149], v[80:83]
	ds_read_b128 v[146:149], v128 offset:6144
	s_waitcnt lgkmcnt(0)
	v_mfma_f32_16x16x32_bf16 v[76:79], v[142:145], v[146:149], v[76:79]
	v_mfma_f32_16x16x32_bf16 v[72:75], v[150:153], v[146:149], v[72:75]
	v_mfma_f32_16x16x32_bf16 v[68:71], v[196:199], v[146:149], v[68:71]
	v_mfma_f32_16x16x32_bf16 v[64:67], v[200:203], v[146:149], v[64:67]
	ds_read_b128 v[146:149], v128 offset:8192
	s_waitcnt lgkmcnt(0)
	v_mfma_f32_16x16x32_bf16 v[60:63], v[142:145], v[146:149], v[60:63]
	v_mfma_f32_16x16x32_bf16 v[56:59], v[150:153], v[146:149], v[56:59]
	v_mfma_f32_16x16x32_bf16 v[52:55], v[196:199], v[146:149], v[52:55]
	v_mfma_f32_16x16x32_bf16 v[48:51], v[200:203], v[146:149], v[48:51]
	ds_read_b128 v[146:149], v128 offset:10240
	s_waitcnt lgkmcnt(0)
	v_mfma_f32_16x16x32_bf16 v[44:47], v[142:145], v[146:149], v[44:47]
	v_mfma_f32_16x16x32_bf16 v[40:43], v[150:153], v[146:149], v[40:43]
	v_mfma_f32_16x16x32_bf16 v[36:39], v[196:199], v[146:149], v[36:39]
	v_mfma_f32_16x16x32_bf16 v[32:35], v[200:203], v[146:149], v[32:35]
	ds_read_b128 v[146:149], v128 offset:12288
	s_waitcnt lgkmcnt(0)
	v_mfma_f32_16x16x32_bf16 v[28:31], v[142:145], v[146:149], v[28:31]
	v_mfma_f32_16x16x32_bf16 v[24:27], v[150:153], v[146:149], v[24:27]
	v_mfma_f32_16x16x32_bf16 v[20:23], v[196:199], v[146:149], v[20:23]
	v_mfma_f32_16x16x32_bf16 v[16:19], v[200:203], v[146:149], v[16:19]
	ds_read_b128 v[146:149], v128 offset:14336
	s_waitcnt vmcnt(0)
	s_waitcnt lgkmcnt(0)
	v_mfma_f32_16x16x32_bf16 v[12:15], v[142:145], v[146:149], v[12:15]
	s_barrier
	v_mfma_f32_16x16x32_bf16 v[8:11], v[150:153], v[146:149], v[8:11]
	v_mfma_f32_16x16x32_bf16 v[4:7], v[196:199], v[146:149], v[4:7]
	v_mfma_f32_16x16x32_bf16 v[0:3], v[200:203], v[146:149], v[0:3]
	s_cbranch_vccz .LBB0_1617
	s_lshl_b64 s[0:1], s[0:1], 1
	s_add_u32 s2, s62, s0
	s_addc_u32 s3, s63, s1
	s_add_u32 s0, s64, s0
	s_addc_u32 s1, s65, s1
	s_add_i32 s4, s6, 0
	v_mov_b32_e32 v139, v129
	s_mov_b32 m0, s4
	v_mov_b32_e32 v141, v129
	v_lshl_add_u64 v[142:143], s[2:3], 0, v[138:139]
	global_load_lds_dwordx4 v138, s[2:3]
	s_add_i32 m0, s4, 0x8000
	v_lshl_add_u64 v[146:147], s[2:3], 0, v[140:141]
	s_mov_b64 s[4:5], 0x4000
	s_add_i32 s2, s9, 0
	global_load_lds_dwordx4 v138, s[0:1]
	v_lshl_add_u64 v[148:149], v[146:147], 0, s[4:5]
	s_mov_b32 m0, s2
	v_lshl_add_u64 v[144:145], s[0:1], 0, v[138:139]
	global_load_lds_dwordx4 v[148:149], off
	v_lshl_add_u64 v[148:149], s[0:1], 0, v[140:141]
	v_lshl_add_u64 v[150:151], v[148:149], 0, s[4:5]
	s_add_i32 m0, s2, 0x8000
	s_mov_b64 s[2:3], 0x8000
	s_add_i32 s0, s8, 0
	global_load_lds_dwordx4 v[150:151], off
	v_lshl_add_u64 v[142:143], v[142:143], 0, s[2:3]
	s_mov_b32 m0, s0
	s_nop 0
	global_load_lds_dwordx4 v[142:143], off
	v_lshl_add_u64 v[142:143], v[144:145], 0, s[2:3]
	s_add_i32 m0, s0, 0x8000
	s_mov_b64 s[2:3], 0xc000
	s_add_i32 s0, s7, 0
	global_load_lds_dwordx4 v[142:143], off
	v_lshl_add_u64 v[142:143], v[146:147], 0, s[2:3]
	s_mov_b32 m0, s0
	s_nop 0
	global_load_lds_dwordx4 v[142:143], off
	v_lshl_add_u64 v[142:143], v[148:149], 0, s[2:3]
	s_add_i32 m0, s0, 0x8000
	s_nop 0
	global_load_lds_dwordx4 v[142:143], off

.LBB0_2070:
	s_lshr_b32 s4, s3, 1
	s_and_b32 s4, s4, 0x1ffff80
	v_or_b32_e32 v0, s4, v154
	s_and_b32 s3, s3, 0xc0
	v_lshlrev_b32_e32 v139, 7, v0
	v_or_b32_e32 v0, s3, v154
	s_mov_b32 s3, s15
	s_lshl_b64 s[2:3], s[2:3], 16
	s_add_u32 s4, s2, s74
	s_addc_u32 s5, s3, s75
	s_waitcnt vmcnt(16)
	v_lshlrev_b32_e32 v128, 7, v0
	v_lshl_add_u64 v[0:1], s[66:67], 0, v[130:131]
	s_add_u32 s2, s2, s76
	v_lshl_add_u64 v[142:143], v[0:1], 0, s[4:5]
	s_addc_u32 s3, s3, s77
	v_lshl_add_u64 v[0:1], s[66:67], 0, v[134:135]
	v_mov_b32_e32 v72, 0
	v_lshl_add_u64 v[144:145], v[132:133], 0, s[2:3]
	v_lshl_add_u64 v[146:147], v[0:1], 0, s[4:5]
	v_lshl_add_u64 v[148:149], v[136:137], 0, s[2:3]
	s_mov_b32 s4, 0
	s_mov_b64 s[2:3], 0
	v_mov_b32_e32 v73, v72
	v_mov_b32_e32 v74, v72
	v_mov_b32_e32 v75, v72
	v_mov_b32_e32 v88, v72
	v_mov_b32_e32 v89, v72
	v_mov_b32_e32 v90, v72
	v_mov_b32_e32 v91, v72
	v_mov_b32_e32 v0, v72
	v_mov_b32_e32 v1, v72
	v_mov_b32_e32 v2, v72
	v_mov_b32_e32 v3, v72
	v_mov_b32_e32 v4, v72
	v_mov_b32_e32 v5, v72
	v_mov_b32_e32 v6, v72
	v_mov_b32_e32 v7, v72
	v_mov_b32_e32 v8, v72
	v_mov_b32_e32 v9, v72
	v_mov_b32_e32 v10, v72
	v_mov_b32_e32 v11, v72
	v_mov_b32_e32 v12, v72
	v_mov_b32_e32 v13, v72
	v_mov_b32_e32 v14, v72
	v_mov_b32_e32 v15, v72
	v_mov_b32_e32 v16, v72
	v_mov_b32_e32 v17, v72
	v_mov_b32_e32 v18, v72
	v_mov_b32_e32 v19, v72
	v_mov_b32_e32 v20, v72
	v_mov_b32_e32 v21, v72
	v_mov_b32_e32 v22, v72
	v_mov_b32_e32 v23, v72
	v_mov_b32_e32 v24, v72
	v_mov_b32_e32 v25, v72
	v_mov_b32_e32 v26, v72
	v_mov_b32_e32 v27, v72
	v_mov_b32_e32 v28, v72
	v_mov_b32_e32 v29, v72
	v_mov_b32_e32 v30, v72
	v_mov_b32_e32 v31, v72
	v_mov_b32_e32 v32, v72
	v_mov_b32_e32 v33, v72
	v_mov_b32_e32 v34, v72
	v_mov_b32_e32 v35, v72
	v_mov_b32_e32 v36, v72
	v_mov_b32_e32 v37, v72
	v_mov_b32_e32 v38, v72
	v_mov_b32_e32 v39, v72
	v_mov_b32_e32 v40, v72
	v_mov_b32_e32 v41, v72
	v_mov_b32_e32 v42, v72
	v_mov_b32_e32 v43, v72
	v_mov_b32_e32 v44, v72
	v_mov_b32_e32 v45, v72
	v_mov_b32_e32 v46, v72
	v_mov_b32_e32 v47, v72
	v_mov_b32_e32 v48, v72
	v_mov_b32_e32 v49, v72
	v_mov_b32_e32 v50, v72
	v_mov_b32_e32 v51, v72
	v_mov_b32_e32 v52, v72
	v_mov_b32_e32 v53, v72
	v_mov_b32_e32 v54, v72
	v_mov_b32_e32 v55, v72
	v_mov_b32_e32 v56, v72
	v_mov_b32_e32 v57, v72
	v_mov_b32_e32 v58, v72
	v_mov_b32_e32 v59, v72
	v_mov_b32_e32 v60, v72
	v_mov_b32_e32 v61, v72
	v_mov_b32_e32 v62, v72
	v_mov_b32_e32 v63, v72
	v_mov_b32_e32 v64, v72
	v_mov_b32_e32 v65, v72
	v_mov_b32_e32 v66, v72
	v_mov_b32_e32 v67, v72
	v_mov_b32_e32 v68, v72
	v_mov_b32_e32 v69, v72
	v_mov_b32_e32 v70, v72
	v_mov_b32_e32 v71, v72
	v_mov_b32_e32 v76, v72
	v_mov_b32_e32 v77, v72
	v_mov_b32_e32 v78, v72
	v_mov_b32_e32 v79, v72
	v_mov_b32_e32 v80, v72
	v_mov_b32_e32 v81, v72
	v_mov_b32_e32 v82, v72
	v_mov_b32_e32 v83, v72
	v_mov_b32_e32 v84, v72
	v_mov_b32_e32 v85, v72
	v_mov_b32_e32 v86, v72
	v_mov_b32_e32 v87, v72
	v_mov_b32_e32 v92, v72
	v_mov_b32_e32 v93, v72
	v_mov_b32_e32 v94, v72
	v_mov_b32_e32 v95, v72
	v_mov_b32_e32 v96, v72
	v_mov_b32_e32 v97, v72
	v_mov_b32_e32 v98, v72
	v_mov_b32_e32 v99, v72
	v_mov_b32_e32 v100, v72
	v_mov_b32_e32 v101, v72
	v_mov_b32_e32 v102, v72
	v_mov_b32_e32 v103, v72
	v_mov_b32_e32 v104, v72
	v_mov_b32_e32 v105, v72
	v_mov_b32_e32 v106, v72
	v_mov_b32_e32 v107, v72
	v_mov_b32_e32 v108, v72
	v_mov_b32_e32 v109, v72
	v_mov_b32_e32 v110, v72
	v_mov_b32_e32 v111, v72
	v_mov_b32_e32 v112, v72
	v_mov_b32_e32 v113, v72
	v_mov_b32_e32 v114, v72
	v_mov_b32_e32 v115, v72
	v_mov_b32_e32 v116, v72
	v_mov_b32_e32 v117, v72
	v_mov_b32_e32 v118, v72
	v_mov_b32_e32 v119, v72
	v_mov_b32_e32 v120, v72
	v_mov_b32_e32 v121, v72
	v_mov_b32_e32 v122, v72
	v_mov_b32_e32 v123, v72
	v_mov_b32_e32 v124, v72
	v_mov_b32_e32 v125, v72
	v_mov_b32_e32 v126, v72
	v_mov_b32_e32 v127, v72
	s_waitcnt vmcnt(16) lgkmcnt(0)
	s_barrier
	v_readfirstlane_b32 s98, v178
	s_nop 3
	s_lshr_b32 s98, s98, 6
	s_cmp_ge_u32 s98, 4
	s_cbranch_scc0 .Lprio_done_10
	s_setprio 1
.Lprio_done_10:
	v_bfe_u32 v250, v178, 3, 3
	v_and_b32_e32 v251, 7, v178
	v_lshrrev_b32_e32 v252, 1, v250
	v_xor_b32_e32 v251, v251, v252
	v_lshlrev_b32_e32 v251, 4, v251
	v_lshl_or_b32 v250, v250, 11, v251
	v_xor_b32_e32 v251, 64, v250
	v_add_u32_e32 v251, 0x4000, v251
	v_add_u32_e32 v252, 0x8000, v250
	v_add_u32_e32 v253, 0x8000, v251
	v_lshl_add_u64 v[242:243], v[142:143], 0, s[2:3]
	v_lshl_add_u64 v[242:243], v[242:243], 0, s[38:39]
	v_lshl_add_u64 v[244:245], v[144:145], 0, s[2:3]
	v_lshl_add_u64 v[244:245], v[244:245], 0, s[40:41]
	v_add_u32_e32 v254, v139, v155
	v_add_u32_e32 v255, v128, v155
	v_readfirstlane_b32 s98, v242
	v_readfirstlane_b32 s99, v243
	v_readfirstlane_b32 s100, v244
	v_readfirstlane_b32 s101, v245
	ds_read_b128 v[150:153], v254
	ds_read_b128 v[204:207], v254 offset:2048
	ds_read_b128 v[196:199], v255 offset:32768
	ds_read_b128 v[200:203], v255 offset:34816
	ds_read_b128 v[208:211], v255 offset:36864
	ds_read_b128 v[212:215], v255 offset:38912
	s_nop 4
	s_lshl_b32 m0, s2, 9
	s_and_b32 m0, m0, 0x10000
	s_xor_b32 m0, m0, 0x10000
	s_add_i32 m0, m0, s6
	s_nop 0
	global_load_lds_dwordx4 v250, s[98:99]
	s_add_i32 m0, m0, 0x8000
	s_nop 0
	global_load_lds_dwordx4 v250, s[100:101]
	s_add_i32 m0, m0, 0xffff8400
	s_nop 0
	global_load_lds_dwordx4 v251, s[98:99]
	s_add_i32 m0, m0, 0x8000
	s_nop 0
	global_load_lds_dwordx4 v251, s[100:101]

.Lgx_2071:
	s_setprio 0
	v_mfma_f32_16x16x32_bf16 v[20:23], v[242:245], v[196:199], v[20:23]
	v_mfma_f32_16x16x32_bf16 v[4:7], v[246:249], v[196:199], v[4:7]
	v_mfma_f32_16x16x32_bf16 v[16:19], v[242:245], v[200:203], v[16:19]
	v_mfma_f32_16x16x32_bf16 v[0:3], v[246:249], v[200:203], v[0:3]
	v_mfma_f32_16x16x32_bf16 v[12:15], v[242:245], v[208:211], v[12:15]
	v_mfma_f32_16x16x32_bf16 v[88:91], v[246:249], v[208:211], v[88:91]
	v_mfma_f32_16x16x32_bf16 v[8:11], v[242:245], v[212:215], v[8:11]
	v_mfma_f32_16x16x32_bf16 v[72:75], v[246:249], v[212:215], v[72:75]
	s_add_i32 s2, 0, 0x10000
	v_add_u32_e32 v139, s2, v139
	v_add_u32_e32 v141, v139, v155
	ds_read_b128 v[142:145], v141
	v_add_u32_e32 v128, s2, v128
	v_add_u32_e32 v195, v128, v155
	ds_read_b128 v[146:149], v195 offset:32768
	ds_read_b128 v[150:153], v195 offset:34816
	ds_read_b128 v[196:199], v141 offset:2048
	ds_read_b128 v[200:203], v195 offset:36864
	ds_read_b128 v[204:207], v195 offset:38912
	s_waitcnt lgkmcnt(2)
	v_mfma_f32_16x16x32_bf16 v[108:111], v[196:199], v[146:149], v[108:111]
	v_add_u32_e32 v139, v139, v156
	v_add_u32_e32 v128, v128, v156
	s_and_b64 vcc, exec, s[60:61]
	v_mfma_f32_16x16x32_bf16 v[124:127], v[142:145], v[146:149], v[124:127]
	v_mfma_f32_16x16x32_bf16 v[120:123], v[142:145], v[150:153], v[120:123]
	s_waitcnt lgkmcnt(1)
	v_mfma_f32_16x16x32_bf16 v[116:119], v[142:145], v[200:203], v[116:119]
	s_waitcnt lgkmcnt(0)
	v_mfma_f32_16x16x32_bf16 v[112:115], v[142:145], v[204:207], v[112:115]
	v_mfma_f32_16x16x32_bf16 v[104:107], v[196:199], v[150:153], v[104:107]
	v_mfma_f32_16x16x32_bf16 v[100:103], v[196:199], v[200:203], v[100:103]
	v_mfma_f32_16x16x32_bf16 v[96:99], v[196:199], v[204:207], v[96:99]
	ds_read_b128 v[142:145], v141 offset:4096
	ds_read_b128 v[196:199], v141 offset:6144
	s_waitcnt lgkmcnt(1)
	v_mfma_f32_16x16x32_bf16 v[92:95], v[142:145], v[146:149], v[92:95]
	v_mfma_f32_16x16x32_bf16 v[84:87], v[142:145], v[150:153], v[84:87]
	v_mfma_f32_16x16x32_bf16 v[80:83], v[142:145], v[200:203], v[80:83]
	v_mfma_f32_16x16x32_bf16 v[76:79], v[142:145], v[204:207], v[76:79]
	s_waitcnt lgkmcnt(0)
	v_mfma_f32_16x16x32_bf16 v[68:71], v[196:199], v[146:149], v[68:71]
	v_mfma_f32_16x16x32_bf16 v[64:67], v[196:199], v[150:153], v[64:67]
	v_mfma_f32_16x16x32_bf16 v[60:63], v[196:199], v[200:203], v[60:63]
	v_mfma_f32_16x16x32_bf16 v[56:59], v[196:199], v[204:207], v[56:59]
	ds_read_b128 v[142:145], v141 offset:8192
	ds_read_b128 v[196:199], v141 offset:10240
	s_waitcnt lgkmcnt(1)
	v_mfma_f32_16x16x32_bf16 v[52:55], v[142:145], v[146:149], v[52:55]
	v_mfma_f32_16x16x32_bf16 v[48:51], v[142:145], v[150:153], v[48:51]
	v_mfma_f32_16x16x32_bf16 v[44:47], v[142:145], v[200:203], v[44:47]
	v_mfma_f32_16x16x32_bf16 v[40:43], v[142:145], v[204:207], v[40:43]
	s_waitcnt lgkmcnt(0)
	v_mfma_f32_16x16x32_bf16 v[36:39], v[196:199], v[146:149], v[36:39]
	v_mfma_f32_16x16x32_bf16 v[32:35], v[196:199], v[150:153], v[32:35]
	v_mfma_f32_16x16x32_bf16 v[28:31], v[196:199], v[200:203], v[28:31]
	v_mfma_f32_16x16x32_bf16 v[24:27], v[196:199], v[204:207], v[24:27]
	ds_read_b128 v[142:145], v141 offset:12288
	ds_read_b128 v[196:199], v141 offset:14336
	s_waitcnt lgkmcnt(1)
	v_mfma_f32_16x16x32_bf16 v[20:23], v[142:145], v[146:149], v[20:23]
	v_mfma_f32_16x16x32_bf16 v[16:19], v[142:145], v[150:153], v[16:19]
	v_mfma_f32_16x16x32_bf16 v[12:15], v[142:145], v[200:203], v[12:15]
	v_mfma_f32_16x16x32_bf16 v[8:11], v[142:145], v[204:207], v[8:11]
	s_waitcnt lgkmcnt(0)
	v_mfma_f32_16x16x32_bf16 v[4:7], v[196:199], v[146:149], v[4:7]
	v_mfma_f32_16x16x32_bf16 v[0:3], v[196:199], v[150:153], v[0:3]
	v_mfma_f32_16x16x32_bf16 v[142:145], v[196:199], v[200:203], v[88:91]
	s_nop 2
	ds_read_b128 v[88:91], v139
	v_mfma_f32_16x16x32_bf16 v[146:149], v[196:199], v[204:207], v[72:75]
	ds_read_b128 v[150:153], v128 offset:32768
	ds_read_b128 v[196:199], v128 offset:34816
	s_nop 0
	ds_read_b128 v[72:75], v139 offset:2048
	ds_read_b128 v[200:203], v128 offset:36864
	ds_read_b128 v[204:207], v128 offset:38912
	s_waitcnt lgkmcnt(2)
	v_mfma_f32_16x16x32_bf16 v[108:111], v[72:75], v[150:153], v[108:111]
	v_mfma_f32_16x16x32_bf16 v[104:107], v[72:75], v[196:199], v[104:107]
	s_waitcnt lgkmcnt(1)
	v_mfma_f32_16x16x32_bf16 v[100:103], v[72:75], v[200:203], v[100:103]
	s_waitcnt lgkmcnt(0)
	v_mfma_f32_16x16x32_bf16 v[96:99], v[72:75], v[204:207], v[96:99]
	ds_read_b128 v[72:75], v139 offset:4096
	ds_read_b128 v[208:211], v139 offset:6144
	v_mfma_f32_16x16x32_bf16 v[124:127], v[88:91], v[150:153], v[124:127]
	v_mfma_f32_16x16x32_bf16 v[120:123], v[88:91], v[196:199], v[120:123]
	v_mfma_f32_16x16x32_bf16 v[116:119], v[88:91], v[200:203], v[116:119]
	v_mfma_f32_16x16x32_bf16 v[112:115], v[88:91], v[204:207], v[112:115]
	s_waitcnt lgkmcnt(1)
	v_mfma_f32_16x16x32_bf16 v[92:95], v[72:75], v[150:153], v[92:95]
	v_mfma_f32_16x16x32_bf16 v[88:91], v[72:75], v[196:199], v[84:87]
	v_mfma_f32_16x16x32_bf16 v[84:87], v[72:75], v[200:203], v[80:83]
	v_mfma_f32_16x16x32_bf16 v[80:83], v[72:75], v[204:207], v[76:79]
	s_waitcnt lgkmcnt(0)
	v_mfma_f32_16x16x32_bf16 v[76:79], v[208:211], v[150:153], v[68:71]
	v_mfma_f32_16x16x32_bf16 v[72:75], v[208:211], v[196:199], v[64:67]
	v_mfma_f32_16x16x32_bf16 v[68:71], v[208:211], v[200:203], v[60:63]
	v_mfma_f32_16x16x32_bf16 v[64:67], v[208:211], v[204:207], v[56:59]
	ds_read_b128 v[208:211], v139 offset:8192
	ds_read_b128 v[212:215], v139 offset:10240
	s_waitcnt lgkmcnt(1)
	v_mfma_f32_16x16x32_bf16 v[60:63], v[208:211], v[150:153], v[52:55]
	v_mfma_f32_16x16x32_bf16 v[56:59], v[208:211], v[196:199], v[48:51]
	v_mfma_f32_16x16x32_bf16 v[52:55], v[208:211], v[200:203], v[44:47]
	v_mfma_f32_16x16x32_bf16 v[48:51], v[208:211], v[204:207], v[40:43]
	s_waitcnt lgkmcnt(0)
	v_mfma_f32_16x16x32_bf16 v[44:47], v[212:215], v[150:153], v[36:39]
	v_mfma_f32_16x16x32_bf16 v[40:43], v[212:215], v[196:199], v[32:35]
	v_mfma_f32_16x16x32_bf16 v[36:39], v[212:215], v[200:203], v[28:31]
	v_mfma_f32_16x16x32_bf16 v[32:35], v[212:215], v[204:207], v[24:27]
	ds_read_b128 v[208:211], v139 offset:12288
	ds_read_b128 v[212:215], v139 offset:14336
	s_waitcnt vmcnt(0)
	s_waitcnt lgkmcnt(0)
	v_mfma_f32_16x16x32_bf16 v[28:31], v[208:211], v[150:153], v[20:23]
	s_barrier
	v_mfma_f32_16x16x32_bf16 v[24:27], v[208:211], v[196:199], v[16:19]
	v_mfma_f32_16x16x32_bf16 v[20:23], v[208:211], v[200:203], v[12:15]
	v_mfma_f32_16x16x32_bf16 v[16:19], v[208:211], v[204:207], v[8:11]
	v_mfma_f32_16x16x32_bf16 v[12:15], v[212:215], v[150:153], v[4:7]
	v_mfma_f32_16x16x32_bf16 v[8:11], v[212:215], v[196:199], v[0:3]
	v_mfma_f32_16x16x32_bf16 v[4:7], v[212:215], v[200:203], v[142:145]
	v_mfma_f32_16x16x32_bf16 v[0:3], v[212:215], v[204:207], v[146:149]
	s_cbranch_vccz .LBB0_2074
	s_lshl_b64 s[0:1], s[0:1], 1
	s_add_u32 s2, s62, s0
	s_addc_u32 s3, s63, s1
	s_add_u32 s0, s64, s0
	s_addc_u32 s1, s65, s1
	s_add_i32 s4, s6, 0
	v_mov_b32_e32 v139, v129
	s_mov_b32 m0, s4
	v_mov_b32_e32 v141, v129
	v_lshl_add_u64 v[142:143], s[2:3], 0, v[138:139]
	global_load_lds_dwordx4 v138, s[2:3]
	s_add_i32 m0, s4, 0x8000
	v_lshl_add_u64 v[146:147], s[2:3], 0, v[140:141]
	s_mov_b64 s[4:5], 0x4000
	s_add_i32 s2, s9, 0
	global_load_lds_dwordx4 v138, s[0:1]
	v_lshl_add_u64 v[148:149], v[146:147], 0, s[4:5]
	s_mov_b32 m0, s2
	v_lshl_add_u64 v[144:145], s[0:1], 0, v[138:139]
	global_load_lds_dwordx4 v[148:149], off
	v_lshl_add_u64 v[148:149], s[0:1], 0, v[140:141]
	v_lshl_add_u64 v[150:151], v[148:149], 0, s[4:5]
	s_add_i32 m0, s2, 0x8000
	s_mov_b64 s[2:3], 0x8000
	s_add_i32 s0, s8, 0
	global_load_lds_dwordx4 v[150:151], off
	v_lshl_add_u64 v[142:143], v[142:143], 0, s[2:3]
	s_mov_b32 m0, s0
	s_nop 0
	global_load_lds_dwordx4 v[142:143], off
	v_lshl_add_u64 v[142:143], v[144:145], 0, s[2:3]
	s_add_i32 m0, s0, 0x8000
	s_mov_b64 s[2:3], 0xc000
	s_add_i32 s0, s7, 0
	global_load_lds_dwordx4 v[142:143], off
	v_lshl_add_u64 v[142:143], v[146:147], 0, s[2:3]
	s_mov_b32 m0, s0
	s_nop 0
	global_load_lds_dwordx4 v[142:143], off
	v_lshl_add_u64 v[142:143], v[148:149], 0, s[2:3]
	s_add_i32 m0, s0, 0x8000
	s_nop 0
	global_load_lds_dwordx4 v[142:143], off
